# delete redundant vmcnt waits in out-proj norm epilogue output stage (they serialised on write-through stores); adaLN conditioning loads batched
# speedup vs baseline: 1.0211x; 1.0135x over previous
.LBB0_424:
	s_cmp_eq_u32 s39, 4
	s_cbranch_scc1 .LBB0_979
	s_cmp_eq_u32 s39, 0
	s_cselect_b64 s[22:23], -1, 0
	s_cmp_gt_i32 s74, 2
	s_cselect_b64 s[4:5], -1, 0
	s_and_b64 s[4:5], s[22:23], s[4:5]
	v_mbcnt_lo_u32_b32 v187, -1, 0
	v_mbcnt_hi_u32_b32 v187, -1, v187
	s_and_b64 vcc, exec, s[4:5]
	v_and_b32_e32 v189, 15, v187
	v_ashrrev_i32_e32 v191, 4, v187
	s_cbranch_vccnz .LBB0_972
	s_cmp_eq_u32 s39, 3
	s_cselect_b64 s[4:5], -1, 0
	s_cmp_gt_i32 s74, 5
	s_cselect_b64 s[6:7], -1, 0
	s_and_b64 s[4:5], s[4:5], s[6:7]
	s_andn2_b64 vcc, exec, s[4:5]
	s_mov_b64 s[4:5], -1
	s_cbranch_vccz .LBB0_972
	s_cmp_lt_i32 s39, 2
	s_cbranch_scc1 .LBB0_687
	s_cmp_gt_i32 s39, 2
	s_cbranch_scc0 .LBB0_639
	s_load_dwordx2 s[4:5], s[0:1], 0xd0
	v_readlane_b32 s48, v254, 36
	v_readlane_b32 s49, v254, 45
	v_readlane_b32 s50, v255, 17
	v_readlane_b32 s96, v255, 32
	v_readlane_b32 s97, v255, 33
	v_lshlrev_b32_e32 v131, 7, v189
	v_lshl_add_u32 v131, v191, 4, v131
	v_add_u32_e32 v132, 0x20000, v131
	v_lshlrev_b32_e32 v133, 5, v191
	v_and_b32_e32 v180, 3, v187
	v_lshlrev_b32_e32 v180, 4, v180
	v_lshrrev_b32_e32 v136, 2, v187
	v_add_lshl_u32 v180, v180, v136, 2
	s_lshl_b32 s51, s48, 8
	s_add_u32 s51, s51, s49
	s_sub_u32 s58, s48, 32
	s_and_b32 s59, s58, 3
	s_lshl_b32 s59, s59, 8
	s_add_u32 s59, s59, s49
	s_cmp_gt_u32 s74, 3
	s_cbranch_scc1 .Lq3_kv
	s_lshl_b32 s35, s51, 11
	s_lshl_b32 s70, s74, 9
	s_add_u32 s35, s35, s70
	s_lshl_b32 s70, s19, 1
	s_add_u32 s35, s35, s70
	s_add_u32 s35, s35, 0x3c00000
	s_mov_b32 s33, 0x8000
	s_mov_b32 s34, 0x28000
	s_mov_b32 s36, 0x3e38aa3b
	s_mov_b32 s71, 0xa0
	v_lshrrev_b32_e32 v130, 2, v187
	v_lshlrev_b32_e32 v130, 11, v130
	s_mov_b64 s[24:25], 0
	s_branch .Lq3_common

.Lq3_kv_ctx:
	s_lshl_b32 s35, s35, 9
	s_lshl_b32 s70, s19, 1
	s_add_u32 s35, s35, s70
	s_mov_b32 s70, 0xc900000
	s_cmp_eq_u32 s74, 4
	s_cselect_b32 s70, s70, 0xd700000
	s_add_u32 s35, s35, s70
	s_mov_b32 s33, 0x2000
	s_mov_b32 s34, 0xa000
	s_mov_b32 s36, 1.0
	s_mov_b32 s71, 0xa8
	v_lshrrev_b32_e32 v130, 2, v187
	v_lshlrev_b32_e32 v130, 9, v130
	s_mov_b64 s[24:25], s[96:97]
.Lq3_common:
	v_and_b32_e32 v136, 3, v187
	v_lshl_add_u32 v130, v136, 4, v130
	s_waitcnt lgkmcnt(0)
	s_add_u32 s6, s4, s35
	s_addc_u32 s7, s5, 0
	s_add_u32 s6, s6, s24
	s_addc_u32 s7, s7, s25
	s_lshl_b32 s59, s59, 7
	s_add_u32 s8, s4, s59
	s_addc_u32 s9, s5, 0
	s_add_u32 s8, s8, 0x180000
	s_addc_u32 s9, s9, 0
	s_cmp_eq_u32 s74, 5
	s_cbranch_scc1 .Lq3_D
	s_cmp_lg_u32 s50, 0
	s_cbranch_scc0 .Lq3_nonorm
	s_add_u32 s24, s0, s71
	s_addc_u32 s25, s1, 0
	s_load_dwordx2 s[24:25], s[24:25], 0x0
	s_cmp_lt_u32 s48, 32
	s_waitcnt lgkmcnt(0)
	s_cbranch_scc1 .Lq3_B
	s_branch .Lq3_A

.Lq3_A:
	global_load_dwordx4 v[148:151], v133, s[24:25]
	global_load_dwordx4 v[152:155], v133, s[24:25] offset:16
	global_load_dwordx4 v[156:159], v133, s[24:25] offset:128
	global_load_dwordx4 v[160:163], v133, s[24:25] offset:144
	global_load_dwordx4 v[164:167], v131, s[8:9]
	global_load_dwordx4 v[168:171], v132, s[8:9]
	global_load_dwordx4 v[172:175], v131, s[8:9] offset:64
	global_load_dwordx4 v[176:179], v132, s[8:9] offset:64
	s_add_u32 s8, s8, 0x800
	s_addc_u32 s9, s9, 0
	global_load_dwordx4 v[202:205], v131, s[8:9]
	global_load_dwordx4 v[206:209], v132, s[8:9]
	global_load_dwordx4 v[210:213], v131, s[8:9] offset:64
	global_load_dwordx4 v[214:217], v132, s[8:9] offset:64
	v_mul_f32_e32 v134, v127, v127
	v_fmac_f32_e32 v134, v126, v126
	v_fmac_f32_e32 v134, v128, v128
	v_fmac_f32_e32 v134, v129, v129
	v_fmac_f32_e32 v134, v122, v122
	v_fmac_f32_e32 v134, v123, v123
	v_fmac_f32_e32 v134, v124, v124
	v_fmac_f32_e32 v134, v125, v125
	v_fmac_f32_e32 v134, v118, v118
	v_fmac_f32_e32 v134, v119, v119
	v_pk_mul_f32 v[136:137], v[120:121], v[120:121]
	v_pk_mul_f32 v[138:139], v[114:115], v[114:115]
	v_add_f32_e32 v134, v136, v134
	v_add_f32_e32 v134, v137, v134
	v_add_f32_e32 v134, v138, v134
	v_pk_mul_f32 v[136:137], v[116:117], v[116:117]
	v_add_f32_e32 v134, v139, v134
	v_add_f32_e32 v134, v136, v134
	v_add_f32_e32 v134, v137, v134
	ds_swizzle_b32 v135, v134 offset:swizzle(SWAP,16)
	s_waitcnt lgkmcnt(0)
	v_add_f32_e32 v134, v134, v135
	v_mov_b32_e32 v135, v134
	s_nop 1
	v_permlane32_swap_b32 v134, v135
	s_nop 1
	v_add_f32_e32 v134, v134, v135
	v_fmamk_f32 v134, v134, 0x3c800000, v242
	v_rsq_f32_e32 v134, v134
	s_waitcnt vmcnt(8)
	v_pk_mul_f32 v[136:137], v[134:135], v[148:149] op_sel_hi:[0,1]
	v_pk_mul_f32 v[126:127], v[126:127], v[136:137]
	v_pk_mul_f32 v[136:137], v[134:135], v[150:151] op_sel_hi:[0,1]
	v_pk_mul_f32 v[128:129], v[128:129], v[136:137]
	v_pk_mul_f32 v[136:137], v[134:135], v[152:153] op_sel_hi:[0,1]
	v_pk_mul_f32 v[122:123], v[122:123], v[136:137]
	v_pk_mul_f32 v[136:137], v[134:135], v[154:155] op_sel_hi:[0,1]
	v_pk_mul_f32 v[124:125], v[124:125], v[136:137]
	v_pk_mul_f32 v[136:137], v[134:135], v[156:157] op_sel_hi:[0,1]
	v_pk_mul_f32 v[118:119], v[118:119], v[136:137]
	v_pk_mul_f32 v[136:137], v[134:135], v[158:159] op_sel_hi:[0,1]
	v_pk_mul_f32 v[120:121], v[120:121], v[136:137]
	v_pk_mul_f32 v[136:137], v[134:135], v[160:161] op_sel_hi:[0,1]
	v_pk_mul_f32 v[114:115], v[114:115], v[136:137]
	v_pk_mul_f32 v[136:137], v[134:135], v[162:163] op_sel_hi:[0,1]
	v_pk_mul_f32 v[116:117], v[116:117], v[136:137]
	s_waitcnt vmcnt(4)
	v_pk_mul_f32 v[136:137], v[126:127], v[168:169] op_sel:[1,0] op_sel_hi:[0,0]
	v_pk_fma_f32 v[126:127], v[126:127], v[164:165], v[136:137] op_sel:[0,0,0] op_sel_hi:[1,0,1] neg_lo:[0,0,1]
	v_pk_mul_f32 v[136:137], v[128:129], v[168:169] op_sel:[1,1] op_sel_hi:[0,1]
	v_pk_fma_f32 v[128:129], v[128:129], v[164:165], v[136:137] op_sel:[0,1,0] op_sel_hi:[1,1,1] neg_lo:[0,0,1]
	v_pk_mul_f32 v[136:137], v[122:123], v[170:171] op_sel:[1,0] op_sel_hi:[0,0]
	v_pk_fma_f32 v[122:123], v[122:123], v[166:167], v[136:137] op_sel:[0,0,0] op_sel_hi:[1,0,1] neg_lo:[0,0,1]
	v_pk_mul_f32 v[136:137], v[124:125], v[170:171] op_sel:[1,1] op_sel_hi:[0,1]
	v_pk_fma_f32 v[124:125], v[124:125], v[166:167], v[136:137] op_sel:[0,1,0] op_sel_hi:[1,1,1] neg_lo:[0,0,1]
	v_pk_mul_f32 v[126:127], v[126:127], s[36:37] op_sel_hi:[1,0]
	v_pk_mul_f32 v[128:129], v[128:129], s[36:37] op_sel_hi:[1,0]
	v_pk_mul_f32 v[122:123], v[122:123], s[36:37] op_sel_hi:[1,0]
	v_pk_mul_f32 v[124:125], v[124:125], s[36:37] op_sel_hi:[1,0]
	v_cvt_pk_bf16_f32 v140, v126, v127
	v_cvt_pk_bf16_f32 v141, v128, v129
	v_cvt_pk_bf16_f32 v142, v122, v123
	v_cvt_pk_bf16_f32 v143, v124, v125
	v_pk_mul_f32 v[136:137], v[118:119], v[176:177] op_sel:[1,0] op_sel_hi:[0,0]
	v_pk_fma_f32 v[118:119], v[118:119], v[172:173], v[136:137] op_sel:[0,0,0] op_sel_hi:[1,0,1] neg_lo:[0,0,1]
	v_pk_mul_f32 v[136:137], v[120:121], v[176:177] op_sel:[1,1] op_sel_hi:[0,1]
	v_pk_fma_f32 v[120:121], v[120:121], v[172:173], v[136:137] op_sel:[0,1,0] op_sel_hi:[1,1,1] neg_lo:[0,0,1]
	v_pk_mul_f32 v[136:137], v[114:115], v[178:179] op_sel:[1,0] op_sel_hi:[0,0]
	v_pk_fma_f32 v[114:115], v[114:115], v[174:175], v[136:137] op_sel:[0,0,0] op_sel_hi:[1,0,1] neg_lo:[0,0,1]
	v_pk_mul_f32 v[136:137], v[116:117], v[178:179] op_sel:[1,1] op_sel_hi:[0,1]
	v_pk_fma_f32 v[116:117], v[116:117], v[174:175], v[136:137] op_sel:[0,1,0] op_sel_hi:[1,1,1] neg_lo:[0,0,1]
	v_pk_mul_f32 v[118:119], v[118:119], s[36:37] op_sel_hi:[1,0]
	v_pk_mul_f32 v[120:121], v[120:121], s[36:37] op_sel_hi:[1,0]
	v_pk_mul_f32 v[114:115], v[114:115], s[36:37] op_sel_hi:[1,0]
	v_pk_mul_f32 v[116:117], v[116:117], s[36:37] op_sel_hi:[1,0]
	v_cvt_pk_bf16_f32 v144, v118, v119
	v_cvt_pk_bf16_f32 v145, v120, v121
	v_cvt_pk_bf16_f32 v146, v114, v115
	v_cvt_pk_bf16_f32 v147, v116, v117
	ds_bpermute_b32 v218, v180, v140
	ds_bpermute_b32 v219, v180, v141
	ds_bpermute_b32 v220, v180, v142
	ds_bpermute_b32 v221, v180, v143
	ds_bpermute_b32 v222, v180, v144
	ds_bpermute_b32 v223, v180, v145
	ds_bpermute_b32 v224, v180, v146
	ds_bpermute_b32 v225, v180, v147
	s_add_u32 s8, s8, 0x800
	s_addc_u32 s9, s9, 0
	global_load_dwordx4 v[164:167], v131, s[8:9]
	global_load_dwordx4 v[168:171], v132, s[8:9]
	global_load_dwordx4 v[172:175], v131, s[8:9] offset:64
	global_load_dwordx4 v[176:179], v132, s[8:9] offset:64
	v_mul_f32_e32 v134, v109, v109
	v_fmac_f32_e32 v134, v108, v108
	v_fmac_f32_e32 v134, v110, v110
	v_fmac_f32_e32 v134, v111, v111
	v_fmac_f32_e32 v134, v104, v104
	v_fmac_f32_e32 v134, v105, v105
	v_fmac_f32_e32 v134, v106, v106
	v_fmac_f32_e32 v134, v107, v107
	v_fmac_f32_e32 v134, v100, v100
	v_fmac_f32_e32 v134, v101, v101
	v_pk_mul_f32 v[136:137], v[102:103], v[102:103]
	v_pk_mul_f32 v[138:139], v[96:97], v[96:97]
	v_add_f32_e32 v134, v136, v134
	v_add_f32_e32 v134, v137, v134
	v_add_f32_e32 v134, v138, v134
	v_pk_mul_f32 v[136:137], v[98:99], v[98:99]
	v_add_f32_e32 v134, v139, v134
	v_add_f32_e32 v134, v136, v134
	v_add_f32_e32 v134, v137, v134
	ds_swizzle_b32 v135, v134 offset:swizzle(SWAP,16)
	s_waitcnt lgkmcnt(0)
	v_add_f32_e32 v134, v134, v135
	v_mov_b32_e32 v135, v134
	s_nop 1
	v_permlane32_swap_b32 v134, v135
	s_nop 1
	v_add_f32_e32 v134, v134, v135
	v_fmamk_f32 v134, v134, 0x3c800000, v242
	v_rsq_f32_e32 v134, v134
	s_nop 0
	v_pk_mul_f32 v[136:137], v[134:135], v[148:149] op_sel_hi:[0,1]
	v_pk_mul_f32 v[108:109], v[108:109], v[136:137]
	v_pk_mul_f32 v[136:137], v[134:135], v[150:151] op_sel_hi:[0,1]
	v_pk_mul_f32 v[110:111], v[110:111], v[136:137]
	v_pk_mul_f32 v[136:137], v[134:135], v[152:153] op_sel_hi:[0,1]
	v_pk_mul_f32 v[104:105], v[104:105], v[136:137]
	v_pk_mul_f32 v[136:137], v[134:135], v[154:155] op_sel_hi:[0,1]
	v_pk_mul_f32 v[106:107], v[106:107], v[136:137]
	v_pk_mul_f32 v[136:137], v[134:135], v[156:157] op_sel_hi:[0,1]
	v_pk_mul_f32 v[100:101], v[100:101], v[136:137]
	v_pk_mul_f32 v[136:137], v[134:135], v[158:159] op_sel_hi:[0,1]
	v_pk_mul_f32 v[102:103], v[102:103], v[136:137]
	v_pk_mul_f32 v[136:137], v[134:135], v[160:161] op_sel_hi:[0,1]
	v_pk_mul_f32 v[96:97], v[96:97], v[136:137]
	v_pk_mul_f32 v[136:137], v[134:135], v[162:163] op_sel_hi:[0,1]
	v_pk_mul_f32 v[98:99], v[98:99], v[136:137]
	s_waitcnt vmcnt(4)
	v_pk_mul_f32 v[136:137], v[108:109], v[206:207] op_sel:[1,0] op_sel_hi:[0,0]
	v_pk_fma_f32 v[108:109], v[108:109], v[202:203], v[136:137] op_sel:[0,0,0] op_sel_hi:[1,0,1] neg_lo:[0,0,1]
	v_pk_mul_f32 v[136:137], v[110:111], v[206:207] op_sel:[1,1] op_sel_hi:[0,1]
	v_pk_fma_f32 v[110:111], v[110:111], v[202:203], v[136:137] op_sel:[0,1,0] op_sel_hi:[1,1,1] neg_lo:[0,0,1]
	v_pk_mul_f32 v[136:137], v[104:105], v[208:209] op_sel:[1,0] op_sel_hi:[0,0]
	v_pk_fma_f32 v[104:105], v[104:105], v[204:205], v[136:137] op_sel:[0,0,0] op_sel_hi:[1,0,1] neg_lo:[0,0,1]
	v_pk_mul_f32 v[136:137], v[106:107], v[208:209] op_sel:[1,1] op_sel_hi:[0,1]
	v_pk_fma_f32 v[106:107], v[106:107], v[204:205], v[136:137] op_sel:[0,1,0] op_sel_hi:[1,1,1] neg_lo:[0,0,1]
	v_pk_mul_f32 v[108:109], v[108:109], s[36:37] op_sel_hi:[1,0]
	v_pk_mul_f32 v[110:111], v[110:111], s[36:37] op_sel_hi:[1,0]
	v_pk_mul_f32 v[104:105], v[104:105], s[36:37] op_sel_hi:[1,0]
	v_pk_mul_f32 v[106:107], v[106:107], s[36:37] op_sel_hi:[1,0]
	v_cvt_pk_bf16_f32 v140, v108, v109
	v_cvt_pk_bf16_f32 v141, v110, v111
	v_cvt_pk_bf16_f32 v142, v104, v105
	v_cvt_pk_bf16_f32 v143, v106, v107
	v_pk_mul_f32 v[136:137], v[100:101], v[214:215] op_sel:[1,0] op_sel_hi:[0,0]
	v_pk_fma_f32 v[100:101], v[100:101], v[210:211], v[136:137] op_sel:[0,0,0] op_sel_hi:[1,0,1] neg_lo:[0,0,1]
	v_pk_mul_f32 v[136:137], v[102:103], v[214:215] op_sel:[1,1] op_sel_hi:[0,1]
	v_pk_fma_f32 v[102:103], v[102:103], v[210:211], v[136:137] op_sel:[0,1,0] op_sel_hi:[1,1,1] neg_lo:[0,0,1]
	v_pk_mul_f32 v[136:137], v[96:97], v[216:217] op_sel:[1,0] op_sel_hi:[0,0]
	v_pk_fma_f32 v[96:97], v[96:97], v[212:213], v[136:137] op_sel:[0,0,0] op_sel_hi:[1,0,1] neg_lo:[0,0,1]
	v_pk_mul_f32 v[136:137], v[98:99], v[216:217] op_sel:[1,1] op_sel_hi:[0,1]
	v_pk_fma_f32 v[98:99], v[98:99], v[212:213], v[136:137] op_sel:[0,1,0] op_sel_hi:[1,1,1] neg_lo:[0,0,1]
	v_pk_mul_f32 v[100:101], v[100:101], s[36:37] op_sel_hi:[1,0]
	v_pk_mul_f32 v[102:103], v[102:103], s[36:37] op_sel_hi:[1,0]
	v_pk_mul_f32 v[96:97], v[96:97], s[36:37] op_sel_hi:[1,0]
	v_pk_mul_f32 v[98:99], v[98:99], s[36:37] op_sel_hi:[1,0]
	v_cvt_pk_bf16_f32 v144, v100, v101
	v_cvt_pk_bf16_f32 v145, v102, v103
	v_cvt_pk_bf16_f32 v146, v96, v97
	v_cvt_pk_bf16_f32 v147, v98, v99
	s_waitcnt lgkmcnt(0)
	global_store_dwordx4 v130, v[218:221], s[6:7]
	global_store_dwordx4 v130, v[222:225], s[6:7] offset:64
	s_add_u32 s6, s6, s33
	s_addc_u32 s7, s7, 0
	ds_bpermute_b32 v226, v180, v140
	ds_bpermute_b32 v227, v180, v141
	ds_bpermute_b32 v228, v180, v142
	ds_bpermute_b32 v229, v180, v143
	ds_bpermute_b32 v230, v180, v144
	ds_bpermute_b32 v231, v180, v145
	ds_bpermute_b32 v232, v180, v146
	ds_bpermute_b32 v233, v180, v147
	s_add_u32 s8, s8, 0x800
	s_addc_u32 s9, s9, 0
	global_load_dwordx4 v[202:205], v131, s[8:9]
	global_load_dwordx4 v[206:209], v132, s[8:9]
	global_load_dwordx4 v[210:213], v131, s[8:9] offset:64
	global_load_dwordx4 v[214:217], v132, s[8:9] offset:64
	v_mul_f32_e32 v134, v93, v93
	v_fmac_f32_e32 v134, v92, v92
	v_fmac_f32_e32 v134, v94, v94
	v_fmac_f32_e32 v134, v95, v95
	v_fmac_f32_e32 v134, v88, v88
	v_fmac_f32_e32 v134, v89, v89
	v_fmac_f32_e32 v134, v90, v90
	v_fmac_f32_e32 v134, v91, v91
	v_fmac_f32_e32 v134, v84, v84
	v_fmac_f32_e32 v134, v85, v85
	v_pk_mul_f32 v[136:137], v[86:87], v[86:87]
	v_pk_mul_f32 v[138:139], v[80:81], v[80:81]
	v_add_f32_e32 v134, v136, v134
	v_add_f32_e32 v134, v137, v134
	v_add_f32_e32 v134, v138, v134
	v_pk_mul_f32 v[136:137], v[82:83], v[82:83]
	v_add_f32_e32 v134, v139, v134
	v_add_f32_e32 v134, v136, v134
	v_add_f32_e32 v134, v137, v134
	ds_swizzle_b32 v135, v134 offset:swizzle(SWAP,16)
	s_waitcnt lgkmcnt(0)
	v_add_f32_e32 v134, v134, v135
	v_mov_b32_e32 v135, v134
	s_nop 1
	v_permlane32_swap_b32 v134, v135
	s_nop 1
	v_add_f32_e32 v134, v134, v135
	v_fmamk_f32 v134, v134, 0x3c800000, v242
	v_rsq_f32_e32 v134, v134
	s_nop 0
	v_pk_mul_f32 v[136:137], v[134:135], v[148:149] op_sel_hi:[0,1]
	v_pk_mul_f32 v[92:93], v[92:93], v[136:137]
	v_pk_mul_f32 v[136:137], v[134:135], v[150:151] op_sel_hi:[0,1]
	v_pk_mul_f32 v[94:95], v[94:95], v[136:137]
	v_pk_mul_f32 v[136:137], v[134:135], v[152:153] op_sel_hi:[0,1]
	v_pk_mul_f32 v[88:89], v[88:89], v[136:137]
	v_pk_mul_f32 v[136:137], v[134:135], v[154:155] op_sel_hi:[0,1]
	v_pk_mul_f32 v[90:91], v[90:91], v[136:137]
	v_pk_mul_f32 v[136:137], v[134:135], v[156:157] op_sel_hi:[0,1]
	v_pk_mul_f32 v[84:85], v[84:85], v[136:137]
	v_pk_mul_f32 v[136:137], v[134:135], v[158:159] op_sel_hi:[0,1]
	v_pk_mul_f32 v[86:87], v[86:87], v[136:137]
	v_pk_mul_f32 v[136:137], v[134:135], v[160:161] op_sel_hi:[0,1]
	v_pk_mul_f32 v[80:81], v[80:81], v[136:137]
	v_pk_mul_f32 v[136:137], v[134:135], v[162:163] op_sel_hi:[0,1]
	v_pk_mul_f32 v[82:83], v[82:83], v[136:137]
	s_waitcnt vmcnt(6)
	v_pk_mul_f32 v[136:137], v[92:93], v[168:169] op_sel:[1,0] op_sel_hi:[0,0]
	v_pk_fma_f32 v[92:93], v[92:93], v[164:165], v[136:137] op_sel:[0,0,0] op_sel_hi:[1,0,1] neg_lo:[0,0,1]
	v_pk_mul_f32 v[136:137], v[94:95], v[168:169] op_sel:[1,1] op_sel_hi:[0,1]
	v_pk_fma_f32 v[94:95], v[94:95], v[164:165], v[136:137] op_sel:[0,1,0] op_sel_hi:[1,1,1] neg_lo:[0,0,1]
	v_pk_mul_f32 v[136:137], v[88:89], v[170:171] op_sel:[1,0] op_sel_hi:[0,0]
	v_pk_fma_f32 v[88:89], v[88:89], v[166:167], v[136:137] op_sel:[0,0,0] op_sel_hi:[1,0,1] neg_lo:[0,0,1]
	v_pk_mul_f32 v[136:137], v[90:91], v[170:171] op_sel:[1,1] op_sel_hi:[0,1]
	v_pk_fma_f32 v[90:91], v[90:91], v[166:167], v[136:137] op_sel:[0,1,0] op_sel_hi:[1,1,1] neg_lo:[0,0,1]
	v_pk_mul_f32 v[92:93], v[92:93], s[36:37] op_sel_hi:[1,0]
	v_pk_mul_f32 v[94:95], v[94:95], s[36:37] op_sel_hi:[1,0]
	v_pk_mul_f32 v[88:89], v[88:89], s[36:37] op_sel_hi:[1,0]
	v_pk_mul_f32 v[90:91], v[90:91], s[36:37] op_sel_hi:[1,0]
	v_cvt_pk_bf16_f32 v140, v92, v93
	v_cvt_pk_bf16_f32 v141, v94, v95
	v_cvt_pk_bf16_f32 v142, v88, v89
	v_cvt_pk_bf16_f32 v143, v90, v91
	v_pk_mul_f32 v[136:137], v[84:85], v[176:177] op_sel:[1,0] op_sel_hi:[0,0]
	v_pk_fma_f32 v[84:85], v[84:85], v[172:173], v[136:137] op_sel:[0,0,0] op_sel_hi:[1,0,1] neg_lo:[0,0,1]
	v_pk_mul_f32 v[136:137], v[86:87], v[176:177] op_sel:[1,1] op_sel_hi:[0,1]
	v_pk_fma_f32 v[86:87], v[86:87], v[172:173], v[136:137] op_sel:[0,1,0] op_sel_hi:[1,1,1] neg_lo:[0,0,1]
	v_pk_mul_f32 v[136:137], v[80:81], v[178:179] op_sel:[1,0] op_sel_hi:[0,0]
	v_pk_fma_f32 v[80:81], v[80:81], v[174:175], v[136:137] op_sel:[0,0,0] op_sel_hi:[1,0,1] neg_lo:[0,0,1]
	v_pk_mul_f32 v[136:137], v[82:83], v[178:179] op_sel:[1,1] op_sel_hi:[0,1]
	v_pk_fma_f32 v[82:83], v[82:83], v[174:175], v[136:137] op_sel:[0,1,0] op_sel_hi:[1,1,1] neg_lo:[0,0,1]
	v_pk_mul_f32 v[84:85], v[84:85], s[36:37] op_sel_hi:[1,0]
	v_pk_mul_f32 v[86:87], v[86:87], s[36:37] op_sel_hi:[1,0]
	v_pk_mul_f32 v[80:81], v[80:81], s[36:37] op_sel_hi:[1,0]
	v_pk_mul_f32 v[82:83], v[82:83], s[36:37] op_sel_hi:[1,0]
	v_cvt_pk_bf16_f32 v144, v84, v85
	v_cvt_pk_bf16_f32 v145, v86, v87
	v_cvt_pk_bf16_f32 v146, v80, v81
	v_cvt_pk_bf16_f32 v147, v82, v83
	s_waitcnt lgkmcnt(0)
	global_store_dwordx4 v130, v[226:229], s[6:7]
	global_store_dwordx4 v130, v[230:233], s[6:7] offset:64
	s_add_u32 s6, s6, s33
	s_addc_u32 s7, s7, 0
	ds_bpermute_b32 v218, v180, v140
	ds_bpermute_b32 v219, v180, v141
	ds_bpermute_b32 v220, v180, v142
	ds_bpermute_b32 v221, v180, v143
	ds_bpermute_b32 v222, v180, v144
	ds_bpermute_b32 v223, v180, v145
	ds_bpermute_b32 v224, v180, v146
	ds_bpermute_b32 v225, v180, v147
	s_add_u32 s8, s8, 0x2800
	s_addc_u32 s9, s9, 0
	global_load_dwordx4 v[164:167], v131, s[8:9]
	global_load_dwordx4 v[168:171], v132, s[8:9]
	global_load_dwordx4 v[172:175], v131, s[8:9] offset:64
	global_load_dwordx4 v[176:179], v132, s[8:9] offset:64
	v_mul_f32_e32 v134, v77, v77
	v_fmac_f32_e32 v134, v76, v76
	v_fmac_f32_e32 v134, v78, v78
	v_fmac_f32_e32 v134, v79, v79
	v_fmac_f32_e32 v134, v72, v72
	v_fmac_f32_e32 v134, v73, v73
	v_fmac_f32_e32 v134, v74, v74
	v_fmac_f32_e32 v134, v75, v75
	v_fmac_f32_e32 v134, v68, v68
	v_fmac_f32_e32 v134, v69, v69
	v_pk_mul_f32 v[136:137], v[70:71], v[70:71]
	v_pk_mul_f32 v[138:139], v[64:65], v[64:65]
	v_add_f32_e32 v134, v136, v134
	v_add_f32_e32 v134, v137, v134
	v_add_f32_e32 v134, v138, v134
	v_pk_mul_f32 v[136:137], v[66:67], v[66:67]
	v_add_f32_e32 v134, v139, v134
	v_add_f32_e32 v134, v136, v134
	v_add_f32_e32 v134, v137, v134
	ds_swizzle_b32 v135, v134 offset:swizzle(SWAP,16)
	s_waitcnt lgkmcnt(0)
	v_add_f32_e32 v134, v134, v135
	v_mov_b32_e32 v135, v134
	s_nop 1
	v_permlane32_swap_b32 v134, v135
	s_nop 1
	v_add_f32_e32 v134, v134, v135
	v_fmamk_f32 v134, v134, 0x3c800000, v242
	v_rsq_f32_e32 v134, v134
	s_nop 0
	v_pk_mul_f32 v[136:137], v[134:135], v[148:149] op_sel_hi:[0,1]
	v_pk_mul_f32 v[76:77], v[76:77], v[136:137]
	v_pk_mul_f32 v[136:137], v[134:135], v[150:151] op_sel_hi:[0,1]
	v_pk_mul_f32 v[78:79], v[78:79], v[136:137]
	v_pk_mul_f32 v[136:137], v[134:135], v[152:153] op_sel_hi:[0,1]
	v_pk_mul_f32 v[72:73], v[72:73], v[136:137]
	v_pk_mul_f32 v[136:137], v[134:135], v[154:155] op_sel_hi:[0,1]
	v_pk_mul_f32 v[74:75], v[74:75], v[136:137]
	v_pk_mul_f32 v[136:137], v[134:135], v[156:157] op_sel_hi:[0,1]
	v_pk_mul_f32 v[68:69], v[68:69], v[136:137]
	v_pk_mul_f32 v[136:137], v[134:135], v[158:159] op_sel_hi:[0,1]
	v_pk_mul_f32 v[70:71], v[70:71], v[136:137]
	v_pk_mul_f32 v[136:137], v[134:135], v[160:161] op_sel_hi:[0,1]
	v_pk_mul_f32 v[64:65], v[64:65], v[136:137]
	v_pk_mul_f32 v[136:137], v[134:135], v[162:163] op_sel_hi:[0,1]
	v_pk_mul_f32 v[66:67], v[66:67], v[136:137]
	s_waitcnt vmcnt(6)
	v_pk_mul_f32 v[136:137], v[76:77], v[206:207] op_sel:[1,0] op_sel_hi:[0,0]
	v_pk_fma_f32 v[76:77], v[76:77], v[202:203], v[136:137] op_sel:[0,0,0] op_sel_hi:[1,0,1] neg_lo:[0,0,1]
	v_pk_mul_f32 v[136:137], v[78:79], v[206:207] op_sel:[1,1] op_sel_hi:[0,1]
	v_pk_fma_f32 v[78:79], v[78:79], v[202:203], v[136:137] op_sel:[0,1,0] op_sel_hi:[1,1,1] neg_lo:[0,0,1]
	v_pk_mul_f32 v[136:137], v[72:73], v[208:209] op_sel:[1,0] op_sel_hi:[0,0]
	v_pk_fma_f32 v[72:73], v[72:73], v[204:205], v[136:137] op_sel:[0,0,0] op_sel_hi:[1,0,1] neg_lo:[0,0,1]
	v_pk_mul_f32 v[136:137], v[74:75], v[208:209] op_sel:[1,1] op_sel_hi:[0,1]
	v_pk_fma_f32 v[74:75], v[74:75], v[204:205], v[136:137] op_sel:[0,1,0] op_sel_hi:[1,1,1] neg_lo:[0,0,1]
	v_pk_mul_f32 v[76:77], v[76:77], s[36:37] op_sel_hi:[1,0]
	v_pk_mul_f32 v[78:79], v[78:79], s[36:37] op_sel_hi:[1,0]
	v_pk_mul_f32 v[72:73], v[72:73], s[36:37] op_sel_hi:[1,0]
	v_pk_mul_f32 v[74:75], v[74:75], s[36:37] op_sel_hi:[1,0]
	v_cvt_pk_bf16_f32 v140, v76, v77
	v_cvt_pk_bf16_f32 v141, v78, v79
	v_cvt_pk_bf16_f32 v142, v72, v73
	v_cvt_pk_bf16_f32 v143, v74, v75
	v_pk_mul_f32 v[136:137], v[68:69], v[214:215] op_sel:[1,0] op_sel_hi:[0,0]
	v_pk_fma_f32 v[68:69], v[68:69], v[210:211], v[136:137] op_sel:[0,0,0] op_sel_hi:[1,0,1] neg_lo:[0,0,1]
	v_pk_mul_f32 v[136:137], v[70:71], v[214:215] op_sel:[1,1] op_sel_hi:[0,1]
	v_pk_fma_f32 v[70:71], v[70:71], v[210:211], v[136:137] op_sel:[0,1,0] op_sel_hi:[1,1,1] neg_lo:[0,0,1]
	v_pk_mul_f32 v[136:137], v[64:65], v[216:217] op_sel:[1,0] op_sel_hi:[0,0]
	v_pk_fma_f32 v[64:65], v[64:65], v[212:213], v[136:137] op_sel:[0,0,0] op_sel_hi:[1,0,1] neg_lo:[0,0,1]
	v_pk_mul_f32 v[136:137], v[66:67], v[216:217] op_sel:[1,1] op_sel_hi:[0,1]
	v_pk_fma_f32 v[66:67], v[66:67], v[212:213], v[136:137] op_sel:[0,1,0] op_sel_hi:[1,1,1] neg_lo:[0,0,1]
	v_pk_mul_f32 v[68:69], v[68:69], s[36:37] op_sel_hi:[1,0]
	v_pk_mul_f32 v[70:71], v[70:71], s[36:37] op_sel_hi:[1,0]
	v_pk_mul_f32 v[64:65], v[64:65], s[36:37] op_sel_hi:[1,0]
	v_pk_mul_f32 v[66:67], v[66:67], s[36:37] op_sel_hi:[1,0]
	v_cvt_pk_bf16_f32 v144, v68, v69
	v_cvt_pk_bf16_f32 v145, v70, v71
	v_cvt_pk_bf16_f32 v146, v64, v65
	v_cvt_pk_bf16_f32 v147, v66, v67
	s_waitcnt lgkmcnt(0)
	global_store_dwordx4 v130, v[218:221], s[6:7]
	global_store_dwordx4 v130, v[222:225], s[6:7] offset:64
	s_add_u32 s6, s6, s33
	s_addc_u32 s7, s7, 0
	ds_bpermute_b32 v226, v180, v140
	ds_bpermute_b32 v227, v180, v141
	ds_bpermute_b32 v228, v180, v142
	ds_bpermute_b32 v229, v180, v143
	ds_bpermute_b32 v230, v180, v144
	ds_bpermute_b32 v231, v180, v145
	ds_bpermute_b32 v232, v180, v146
	ds_bpermute_b32 v233, v180, v147
	s_add_u32 s8, s8, 0x800
	s_addc_u32 s9, s9, 0
	global_load_dwordx4 v[202:205], v131, s[8:9]
	global_load_dwordx4 v[206:209], v132, s[8:9]
	global_load_dwordx4 v[210:213], v131, s[8:9] offset:64
	global_load_dwordx4 v[214:217], v132, s[8:9] offset:64
	v_mul_f32_e32 v134, v61, v61
	v_fmac_f32_e32 v134, v60, v60
	v_fmac_f32_e32 v134, v62, v62
	v_fmac_f32_e32 v134, v63, v63
	v_fmac_f32_e32 v134, v56, v56
	v_fmac_f32_e32 v134, v57, v57
	v_fmac_f32_e32 v134, v58, v58
	v_fmac_f32_e32 v134, v59, v59
	v_fmac_f32_e32 v134, v52, v52
	v_fmac_f32_e32 v134, v53, v53
	v_pk_mul_f32 v[136:137], v[54:55], v[54:55]
	v_pk_mul_f32 v[138:139], v[48:49], v[48:49]
	v_add_f32_e32 v134, v136, v134
	v_add_f32_e32 v134, v137, v134
	v_add_f32_e32 v134, v138, v134
	v_pk_mul_f32 v[136:137], v[50:51], v[50:51]
	v_add_f32_e32 v134, v139, v134
	v_add_f32_e32 v134, v136, v134
	v_add_f32_e32 v134, v137, v134
	ds_swizzle_b32 v135, v134 offset:swizzle(SWAP,16)
	s_waitcnt lgkmcnt(0)
	v_add_f32_e32 v134, v134, v135
	v_mov_b32_e32 v135, v134
	s_nop 1
	v_permlane32_swap_b32 v134, v135
	s_nop 1
	v_add_f32_e32 v134, v134, v135
	v_fmamk_f32 v134, v134, 0x3c800000, v242
	v_rsq_f32_e32 v134, v134
	s_nop 0
	v_pk_mul_f32 v[136:137], v[134:135], v[148:149] op_sel_hi:[0,1]
	v_pk_mul_f32 v[60:61], v[60:61], v[136:137]
	v_pk_mul_f32 v[136:137], v[134:135], v[150:151] op_sel_hi:[0,1]
	v_pk_mul_f32 v[62:63], v[62:63], v[136:137]
	v_pk_mul_f32 v[136:137], v[134:135], v[152:153] op_sel_hi:[0,1]
	v_pk_mul_f32 v[56:57], v[56:57], v[136:137]
	v_pk_mul_f32 v[136:137], v[134:135], v[154:155] op_sel_hi:[0,1]
	v_pk_mul_f32 v[58:59], v[58:59], v[136:137]
	v_pk_mul_f32 v[136:137], v[134:135], v[156:157] op_sel_hi:[0,1]
	v_pk_mul_f32 v[52:53], v[52:53], v[136:137]
	v_pk_mul_f32 v[136:137], v[134:135], v[158:159] op_sel_hi:[0,1]
	v_pk_mul_f32 v[54:55], v[54:55], v[136:137]
	v_pk_mul_f32 v[136:137], v[134:135], v[160:161] op_sel_hi:[0,1]
	v_pk_mul_f32 v[48:49], v[48:49], v[136:137]
	v_pk_mul_f32 v[136:137], v[134:135], v[162:163] op_sel_hi:[0,1]
	v_pk_mul_f32 v[50:51], v[50:51], v[136:137]
	s_waitcnt vmcnt(6)
	v_pk_mul_f32 v[136:137], v[60:61], v[168:169] op_sel:[1,0] op_sel_hi:[0,0]
	v_pk_fma_f32 v[60:61], v[60:61], v[164:165], v[136:137] op_sel:[0,0,0] op_sel_hi:[1,0,1] neg_lo:[0,0,1]
	v_pk_mul_f32 v[136:137], v[62:63], v[168:169] op_sel:[1,1] op_sel_hi:[0,1]
	v_pk_fma_f32 v[62:63], v[62:63], v[164:165], v[136:137] op_sel:[0,1,0] op_sel_hi:[1,1,1] neg_lo:[0,0,1]
	v_pk_mul_f32 v[136:137], v[56:57], v[170:171] op_sel:[1,0] op_sel_hi:[0,0]
	v_pk_fma_f32 v[56:57], v[56:57], v[166:167], v[136:137] op_sel:[0,0,0] op_sel_hi:[1,0,1] neg_lo:[0,0,1]
	v_pk_mul_f32 v[136:137], v[58:59], v[170:171] op_sel:[1,1] op_sel_hi:[0,1]
	v_pk_fma_f32 v[58:59], v[58:59], v[166:167], v[136:137] op_sel:[0,1,0] op_sel_hi:[1,1,1] neg_lo:[0,0,1]
	v_pk_mul_f32 v[60:61], v[60:61], s[36:37] op_sel_hi:[1,0]
	v_pk_mul_f32 v[62:63], v[62:63], s[36:37] op_sel_hi:[1,0]
	v_pk_mul_f32 v[56:57], v[56:57], s[36:37] op_sel_hi:[1,0]
	v_pk_mul_f32 v[58:59], v[58:59], s[36:37] op_sel_hi:[1,0]
	v_cvt_pk_bf16_f32 v140, v60, v61
	v_cvt_pk_bf16_f32 v141, v62, v63
	v_cvt_pk_bf16_f32 v142, v56, v57
	v_cvt_pk_bf16_f32 v143, v58, v59
	v_pk_mul_f32 v[136:137], v[52:53], v[176:177] op_sel:[1,0] op_sel_hi:[0,0]
	v_pk_fma_f32 v[52:53], v[52:53], v[172:173], v[136:137] op_sel:[0,0,0] op_sel_hi:[1,0,1] neg_lo:[0,0,1]
	v_pk_mul_f32 v[136:137], v[54:55], v[176:177] op_sel:[1,1] op_sel_hi:[0,1]
	v_pk_fma_f32 v[54:55], v[54:55], v[172:173], v[136:137] op_sel:[0,1,0] op_sel_hi:[1,1,1] neg_lo:[0,0,1]
	v_pk_mul_f32 v[136:137], v[48:49], v[178:179] op_sel:[1,0] op_sel_hi:[0,0]
	v_pk_fma_f32 v[48:49], v[48:49], v[174:175], v[136:137] op_sel:[0,0,0] op_sel_hi:[1,0,1] neg_lo:[0,0,1]
	v_pk_mul_f32 v[136:137], v[50:51], v[178:179] op_sel:[1,1] op_sel_hi:[0,1]
	v_pk_fma_f32 v[50:51], v[50:51], v[174:175], v[136:137] op_sel:[0,1,0] op_sel_hi:[1,1,1] neg_lo:[0,0,1]
	v_pk_mul_f32 v[52:53], v[52:53], s[36:37] op_sel_hi:[1,0]
	v_pk_mul_f32 v[54:55], v[54:55], s[36:37] op_sel_hi:[1,0]
	v_pk_mul_f32 v[48:49], v[48:49], s[36:37] op_sel_hi:[1,0]
	v_pk_mul_f32 v[50:51], v[50:51], s[36:37] op_sel_hi:[1,0]
	v_cvt_pk_bf16_f32 v144, v52, v53
	v_cvt_pk_bf16_f32 v145, v54, v55
	v_cvt_pk_bf16_f32 v146, v48, v49
	v_cvt_pk_bf16_f32 v147, v50, v51
	s_waitcnt lgkmcnt(0)
	global_store_dwordx4 v130, v[226:229], s[6:7]
	global_store_dwordx4 v130, v[230:233], s[6:7] offset:64
	s_add_u32 s6, s6, s34
	s_addc_u32 s7, s7, 0
	ds_bpermute_b32 v218, v180, v140
	ds_bpermute_b32 v219, v180, v141
	ds_bpermute_b32 v220, v180, v142
	ds_bpermute_b32 v221, v180, v143
	ds_bpermute_b32 v222, v180, v144
	ds_bpermute_b32 v223, v180, v145
	ds_bpermute_b32 v224, v180, v146
	ds_bpermute_b32 v225, v180, v147
	s_add_u32 s8, s8, 0x800
	s_addc_u32 s9, s9, 0
	global_load_dwordx4 v[164:167], v131, s[8:9]
	global_load_dwordx4 v[168:171], v132, s[8:9]
	global_load_dwordx4 v[172:175], v131, s[8:9] offset:64
	global_load_dwordx4 v[176:179], v132, s[8:9] offset:64
	v_mul_f32_e32 v134, v45, v45
	v_fmac_f32_e32 v134, v44, v44
	v_fmac_f32_e32 v134, v46, v46
	v_fmac_f32_e32 v134, v47, v47
	v_fmac_f32_e32 v134, v40, v40
	v_fmac_f32_e32 v134, v41, v41
	v_fmac_f32_e32 v134, v42, v42
	v_fmac_f32_e32 v134, v43, v43
	v_fmac_f32_e32 v134, v36, v36
	v_fmac_f32_e32 v134, v37, v37
	v_pk_mul_f32 v[136:137], v[38:39], v[38:39]
	v_pk_mul_f32 v[138:139], v[32:33], v[32:33]
	v_add_f32_e32 v134, v136, v134
	v_add_f32_e32 v134, v137, v134
	v_add_f32_e32 v134, v138, v134
	v_pk_mul_f32 v[136:137], v[34:35], v[34:35]
	v_add_f32_e32 v134, v139, v134
	v_add_f32_e32 v134, v136, v134
	v_add_f32_e32 v134, v137, v134
	ds_swizzle_b32 v135, v134 offset:swizzle(SWAP,16)
	s_waitcnt lgkmcnt(0)
	v_add_f32_e32 v134, v134, v135
	v_mov_b32_e32 v135, v134
	s_nop 1
	v_permlane32_swap_b32 v134, v135
	s_nop 1
	v_add_f32_e32 v134, v134, v135
	v_fmamk_f32 v134, v134, 0x3c800000, v242
	v_rsq_f32_e32 v134, v134
	s_nop 0
	v_pk_mul_f32 v[136:137], v[134:135], v[148:149] op_sel_hi:[0,1]
	v_pk_mul_f32 v[44:45], v[44:45], v[136:137]
	v_pk_mul_f32 v[136:137], v[134:135], v[150:151] op_sel_hi:[0,1]
	v_pk_mul_f32 v[46:47], v[46:47], v[136:137]
	v_pk_mul_f32 v[136:137], v[134:135], v[152:153] op_sel_hi:[0,1]
	v_pk_mul_f32 v[40:41], v[40:41], v[136:137]
	v_pk_mul_f32 v[136:137], v[134:135], v[154:155] op_sel_hi:[0,1]
	v_pk_mul_f32 v[42:43], v[42:43], v[136:137]
	v_pk_mul_f32 v[136:137], v[134:135], v[156:157] op_sel_hi:[0,1]
	v_pk_mul_f32 v[36:37], v[36:37], v[136:137]
	v_pk_mul_f32 v[136:137], v[134:135], v[158:159] op_sel_hi:[0,1]
	v_pk_mul_f32 v[38:39], v[38:39], v[136:137]
	v_pk_mul_f32 v[136:137], v[134:135], v[160:161] op_sel_hi:[0,1]
	v_pk_mul_f32 v[32:33], v[32:33], v[136:137]
	v_pk_mul_f32 v[136:137], v[134:135], v[162:163] op_sel_hi:[0,1]
	v_pk_mul_f32 v[34:35], v[34:35], v[136:137]
	s_waitcnt vmcnt(6)
	v_pk_mul_f32 v[136:137], v[44:45], v[206:207] op_sel:[1,0] op_sel_hi:[0,0]
	v_pk_fma_f32 v[44:45], v[44:45], v[202:203], v[136:137] op_sel:[0,0,0] op_sel_hi:[1,0,1] neg_lo:[0,0,1]
	v_pk_mul_f32 v[136:137], v[46:47], v[206:207] op_sel:[1,1] op_sel_hi:[0,1]
	v_pk_fma_f32 v[46:47], v[46:47], v[202:203], v[136:137] op_sel:[0,1,0] op_sel_hi:[1,1,1] neg_lo:[0,0,1]
	v_pk_mul_f32 v[136:137], v[40:41], v[208:209] op_sel:[1,0] op_sel_hi:[0,0]
	v_pk_fma_f32 v[40:41], v[40:41], v[204:205], v[136:137] op_sel:[0,0,0] op_sel_hi:[1,0,1] neg_lo:[0,0,1]
	v_pk_mul_f32 v[136:137], v[42:43], v[208:209] op_sel:[1,1] op_sel_hi:[0,1]
	v_pk_fma_f32 v[42:43], v[42:43], v[204:205], v[136:137] op_sel:[0,1,0] op_sel_hi:[1,1,1] neg_lo:[0,0,1]
	v_pk_mul_f32 v[44:45], v[44:45], s[36:37] op_sel_hi:[1,0]
	v_pk_mul_f32 v[46:47], v[46:47], s[36:37] op_sel_hi:[1,0]
	v_pk_mul_f32 v[40:41], v[40:41], s[36:37] op_sel_hi:[1,0]
	v_pk_mul_f32 v[42:43], v[42:43], s[36:37] op_sel_hi:[1,0]
	v_cvt_pk_bf16_f32 v140, v44, v45
	v_cvt_pk_bf16_f32 v141, v46, v47
	v_cvt_pk_bf16_f32 v142, v40, v41
	v_cvt_pk_bf16_f32 v143, v42, v43
	v_pk_mul_f32 v[136:137], v[36:37], v[214:215] op_sel:[1,0] op_sel_hi:[0,0]
	v_pk_fma_f32 v[36:37], v[36:37], v[210:211], v[136:137] op_sel:[0,0,0] op_sel_hi:[1,0,1] neg_lo:[0,0,1]
	v_pk_mul_f32 v[136:137], v[38:39], v[214:215] op_sel:[1,1] op_sel_hi:[0,1]
	v_pk_fma_f32 v[38:39], v[38:39], v[210:211], v[136:137] op_sel:[0,1,0] op_sel_hi:[1,1,1] neg_lo:[0,0,1]
	v_pk_mul_f32 v[136:137], v[32:33], v[216:217] op_sel:[1,0] op_sel_hi:[0,0]
	v_pk_fma_f32 v[32:33], v[32:33], v[212:213], v[136:137] op_sel:[0,0,0] op_sel_hi:[1,0,1] neg_lo:[0,0,1]
	v_pk_mul_f32 v[136:137], v[34:35], v[216:217] op_sel:[1,1] op_sel_hi:[0,1]
	v_pk_fma_f32 v[34:35], v[34:35], v[212:213], v[136:137] op_sel:[0,1,0] op_sel_hi:[1,1,1] neg_lo:[0,0,1]
	v_pk_mul_f32 v[36:37], v[36:37], s[36:37] op_sel_hi:[1,0]
	v_pk_mul_f32 v[38:39], v[38:39], s[36:37] op_sel_hi:[1,0]
	v_pk_mul_f32 v[32:33], v[32:33], s[36:37] op_sel_hi:[1,0]
	v_pk_mul_f32 v[34:35], v[34:35], s[36:37] op_sel_hi:[1,0]
	v_cvt_pk_bf16_f32 v144, v36, v37
	v_cvt_pk_bf16_f32 v145, v38, v39
	v_cvt_pk_bf16_f32 v146, v32, v33
	v_cvt_pk_bf16_f32 v147, v34, v35
	s_waitcnt lgkmcnt(0)
	global_store_dwordx4 v130, v[218:221], s[6:7]
	global_store_dwordx4 v130, v[222:225], s[6:7] offset:64
	s_add_u32 s6, s6, s33
	s_addc_u32 s7, s7, 0
	ds_bpermute_b32 v226, v180, v140
	ds_bpermute_b32 v227, v180, v141
	ds_bpermute_b32 v228, v180, v142
	ds_bpermute_b32 v229, v180, v143
	ds_bpermute_b32 v230, v180, v144
	ds_bpermute_b32 v231, v180, v145
	ds_bpermute_b32 v232, v180, v146
	ds_bpermute_b32 v233, v180, v147
	s_add_u32 s8, s8, 0x800
	s_addc_u32 s9, s9, 0
	global_load_dwordx4 v[202:205], v131, s[8:9]
	global_load_dwordx4 v[206:209], v132, s[8:9]
	global_load_dwordx4 v[210:213], v131, s[8:9] offset:64
	global_load_dwordx4 v[214:217], v132, s[8:9] offset:64
	v_mul_f32_e32 v134, v29, v29
	v_fmac_f32_e32 v134, v28, v28
	v_fmac_f32_e32 v134, v30, v30
	v_fmac_f32_e32 v134, v31, v31
	v_fmac_f32_e32 v134, v24, v24
	v_fmac_f32_e32 v134, v25, v25
	v_fmac_f32_e32 v134, v26, v26
	v_fmac_f32_e32 v134, v27, v27
	v_fmac_f32_e32 v134, v20, v20
	v_fmac_f32_e32 v134, v21, v21
	v_pk_mul_f32 v[136:137], v[22:23], v[22:23]
	v_pk_mul_f32 v[138:139], v[16:17], v[16:17]
	v_add_f32_e32 v134, v136, v134
	v_add_f32_e32 v134, v137, v134
	v_add_f32_e32 v134, v138, v134
	v_pk_mul_f32 v[136:137], v[18:19], v[18:19]
	v_add_f32_e32 v134, v139, v134
	v_add_f32_e32 v134, v136, v134
	v_add_f32_e32 v134, v137, v134
	ds_swizzle_b32 v135, v134 offset:swizzle(SWAP,16)
	s_waitcnt lgkmcnt(0)
	v_add_f32_e32 v134, v134, v135
	v_mov_b32_e32 v135, v134
	s_nop 1
	v_permlane32_swap_b32 v134, v135
	s_nop 1
	v_add_f32_e32 v134, v134, v135
	v_fmamk_f32 v134, v134, 0x3c800000, v242
	v_rsq_f32_e32 v134, v134
	s_nop 0
	v_pk_mul_f32 v[136:137], v[134:135], v[148:149] op_sel_hi:[0,1]
	v_pk_mul_f32 v[28:29], v[28:29], v[136:137]
	v_pk_mul_f32 v[136:137], v[134:135], v[150:151] op_sel_hi:[0,1]
	v_pk_mul_f32 v[30:31], v[30:31], v[136:137]
	v_pk_mul_f32 v[136:137], v[134:135], v[152:153] op_sel_hi:[0,1]
	v_pk_mul_f32 v[24:25], v[24:25], v[136:137]
	v_pk_mul_f32 v[136:137], v[134:135], v[154:155] op_sel_hi:[0,1]
	v_pk_mul_f32 v[26:27], v[26:27], v[136:137]
	v_pk_mul_f32 v[136:137], v[134:135], v[156:157] op_sel_hi:[0,1]
	v_pk_mul_f32 v[20:21], v[20:21], v[136:137]
	v_pk_mul_f32 v[136:137], v[134:135], v[158:159] op_sel_hi:[0,1]
	v_pk_mul_f32 v[22:23], v[22:23], v[136:137]
	v_pk_mul_f32 v[136:137], v[134:135], v[160:161] op_sel_hi:[0,1]
	v_pk_mul_f32 v[16:17], v[16:17], v[136:137]
	v_pk_mul_f32 v[136:137], v[134:135], v[162:163] op_sel_hi:[0,1]
	v_pk_mul_f32 v[18:19], v[18:19], v[136:137]
	s_waitcnt vmcnt(6)
	v_pk_mul_f32 v[136:137], v[28:29], v[168:169] op_sel:[1,0] op_sel_hi:[0,0]
	v_pk_fma_f32 v[28:29], v[28:29], v[164:165], v[136:137] op_sel:[0,0,0] op_sel_hi:[1,0,1] neg_lo:[0,0,1]
	v_pk_mul_f32 v[136:137], v[30:31], v[168:169] op_sel:[1,1] op_sel_hi:[0,1]
	v_pk_fma_f32 v[30:31], v[30:31], v[164:165], v[136:137] op_sel:[0,1,0] op_sel_hi:[1,1,1] neg_lo:[0,0,1]
	v_pk_mul_f32 v[136:137], v[24:25], v[170:171] op_sel:[1,0] op_sel_hi:[0,0]
	v_pk_fma_f32 v[24:25], v[24:25], v[166:167], v[136:137] op_sel:[0,0,0] op_sel_hi:[1,0,1] neg_lo:[0,0,1]
	v_pk_mul_f32 v[136:137], v[26:27], v[170:171] op_sel:[1,1] op_sel_hi:[0,1]
	v_pk_fma_f32 v[26:27], v[26:27], v[166:167], v[136:137] op_sel:[0,1,0] op_sel_hi:[1,1,1] neg_lo:[0,0,1]
	v_pk_mul_f32 v[28:29], v[28:29], s[36:37] op_sel_hi:[1,0]
	v_pk_mul_f32 v[30:31], v[30:31], s[36:37] op_sel_hi:[1,0]
	v_pk_mul_f32 v[24:25], v[24:25], s[36:37] op_sel_hi:[1,0]
	v_pk_mul_f32 v[26:27], v[26:27], s[36:37] op_sel_hi:[1,0]
	v_cvt_pk_bf16_f32 v140, v28, v29
	v_cvt_pk_bf16_f32 v141, v30, v31
	v_cvt_pk_bf16_f32 v142, v24, v25
	v_cvt_pk_bf16_f32 v143, v26, v27
	v_pk_mul_f32 v[136:137], v[20:21], v[176:177] op_sel:[1,0] op_sel_hi:[0,0]
	v_pk_fma_f32 v[20:21], v[20:21], v[172:173], v[136:137] op_sel:[0,0,0] op_sel_hi:[1,0,1] neg_lo:[0,0,1]
	v_pk_mul_f32 v[136:137], v[22:23], v[176:177] op_sel:[1,1] op_sel_hi:[0,1]
	v_pk_fma_f32 v[22:23], v[22:23], v[172:173], v[136:137] op_sel:[0,1,0] op_sel_hi:[1,1,1] neg_lo:[0,0,1]
	v_pk_mul_f32 v[136:137], v[16:17], v[178:179] op_sel:[1,0] op_sel_hi:[0,0]
	v_pk_fma_f32 v[16:17], v[16:17], v[174:175], v[136:137] op_sel:[0,0,0] op_sel_hi:[1,0,1] neg_lo:[0,0,1]
	v_pk_mul_f32 v[136:137], v[18:19], v[178:179] op_sel:[1,1] op_sel_hi:[0,1]
	v_pk_fma_f32 v[18:19], v[18:19], v[174:175], v[136:137] op_sel:[0,1,0] op_sel_hi:[1,1,1] neg_lo:[0,0,1]
	v_pk_mul_f32 v[20:21], v[20:21], s[36:37] op_sel_hi:[1,0]
	v_pk_mul_f32 v[22:23], v[22:23], s[36:37] op_sel_hi:[1,0]
	v_pk_mul_f32 v[16:17], v[16:17], s[36:37] op_sel_hi:[1,0]
	v_pk_mul_f32 v[18:19], v[18:19], s[36:37] op_sel_hi:[1,0]
	v_cvt_pk_bf16_f32 v144, v20, v21
	v_cvt_pk_bf16_f32 v145, v22, v23
	v_cvt_pk_bf16_f32 v146, v16, v17
	v_cvt_pk_bf16_f32 v147, v18, v19
	s_waitcnt lgkmcnt(0)
	global_store_dwordx4 v130, v[226:229], s[6:7]
	global_store_dwordx4 v130, v[230:233], s[6:7] offset:64
	s_add_u32 s6, s6, s33
	s_addc_u32 s7, s7, 0
	ds_bpermute_b32 v218, v180, v140
	ds_bpermute_b32 v219, v180, v141
	ds_bpermute_b32 v220, v180, v142
	ds_bpermute_b32 v221, v180, v143
	ds_bpermute_b32 v222, v180, v144
	ds_bpermute_b32 v223, v180, v145
	ds_bpermute_b32 v224, v180, v146
	ds_bpermute_b32 v225, v180, v147
	v_mul_f32_e32 v134, v13, v13
	v_fmac_f32_e32 v134, v12, v12
	v_fmac_f32_e32 v134, v14, v14
	v_fmac_f32_e32 v134, v15, v15
	v_fmac_f32_e32 v134, v4, v4
	v_fmac_f32_e32 v134, v5, v5
	v_fmac_f32_e32 v134, v6, v6
	v_fmac_f32_e32 v134, v7, v7
	v_fmac_f32_e32 v134, v8, v8
	v_fmac_f32_e32 v134, v9, v9
	v_pk_mul_f32 v[136:137], v[10:11], v[10:11]
	v_pk_mul_f32 v[138:139], v[0:1], v[0:1]
	v_add_f32_e32 v134, v136, v134
	v_add_f32_e32 v134, v137, v134
	v_add_f32_e32 v134, v138, v134
	v_pk_mul_f32 v[136:137], v[2:3], v[2:3]
	v_add_f32_e32 v134, v139, v134
	v_add_f32_e32 v134, v136, v134
	v_add_f32_e32 v134, v137, v134
	ds_swizzle_b32 v135, v134 offset:swizzle(SWAP,16)
	s_waitcnt lgkmcnt(0)
	v_add_f32_e32 v134, v134, v135
	v_mov_b32_e32 v135, v134
	s_nop 1
	v_permlane32_swap_b32 v134, v135
	s_nop 1
	v_add_f32_e32 v134, v134, v135
	v_fmamk_f32 v134, v134, 0x3c800000, v242
	v_rsq_f32_e32 v134, v134
	s_nop 0
	v_pk_mul_f32 v[136:137], v[134:135], v[148:149] op_sel_hi:[0,1]
	v_pk_mul_f32 v[12:13], v[12:13], v[136:137]
	v_pk_mul_f32 v[136:137], v[134:135], v[150:151] op_sel_hi:[0,1]
	v_pk_mul_f32 v[14:15], v[14:15], v[136:137]
	v_pk_mul_f32 v[136:137], v[134:135], v[152:153] op_sel_hi:[0,1]
	v_pk_mul_f32 v[4:5], v[4:5], v[136:137]
	v_pk_mul_f32 v[136:137], v[134:135], v[154:155] op_sel_hi:[0,1]
	v_pk_mul_f32 v[6:7], v[6:7], v[136:137]
	v_pk_mul_f32 v[136:137], v[134:135], v[156:157] op_sel_hi:[0,1]
	v_pk_mul_f32 v[8:9], v[8:9], v[136:137]
	v_pk_mul_f32 v[136:137], v[134:135], v[158:159] op_sel_hi:[0,1]
	v_pk_mul_f32 v[10:11], v[10:11], v[136:137]
	v_pk_mul_f32 v[136:137], v[134:135], v[160:161] op_sel_hi:[0,1]
	v_pk_mul_f32 v[0:1], v[0:1], v[136:137]
	v_pk_mul_f32 v[136:137], v[134:135], v[162:163] op_sel_hi:[0,1]
	v_pk_mul_f32 v[2:3], v[2:3], v[136:137]
	s_waitcnt vmcnt(2)
	v_pk_mul_f32 v[136:137], v[12:13], v[206:207] op_sel:[1,0] op_sel_hi:[0,0]
	v_pk_fma_f32 v[12:13], v[12:13], v[202:203], v[136:137] op_sel:[0,0,0] op_sel_hi:[1,0,1] neg_lo:[0,0,1]
	v_pk_mul_f32 v[136:137], v[14:15], v[206:207] op_sel:[1,1] op_sel_hi:[0,1]
	v_pk_fma_f32 v[14:15], v[14:15], v[202:203], v[136:137] op_sel:[0,1,0] op_sel_hi:[1,1,1] neg_lo:[0,0,1]
	v_pk_mul_f32 v[136:137], v[4:5], v[208:209] op_sel:[1,0] op_sel_hi:[0,0]
	v_pk_fma_f32 v[4:5], v[4:5], v[204:205], v[136:137] op_sel:[0,0,0] op_sel_hi:[1,0,1] neg_lo:[0,0,1]
	v_pk_mul_f32 v[136:137], v[6:7], v[208:209] op_sel:[1,1] op_sel_hi:[0,1]
	v_pk_fma_f32 v[6:7], v[6:7], v[204:205], v[136:137] op_sel:[0,1,0] op_sel_hi:[1,1,1] neg_lo:[0,0,1]
	v_pk_mul_f32 v[12:13], v[12:13], s[36:37] op_sel_hi:[1,0]
	v_pk_mul_f32 v[14:15], v[14:15], s[36:37] op_sel_hi:[1,0]
	v_pk_mul_f32 v[4:5], v[4:5], s[36:37] op_sel_hi:[1,0]
	v_pk_mul_f32 v[6:7], v[6:7], s[36:37] op_sel_hi:[1,0]
	v_cvt_pk_bf16_f32 v140, v12, v13
	v_cvt_pk_bf16_f32 v141, v14, v15
	v_cvt_pk_bf16_f32 v142, v4, v5
	v_cvt_pk_bf16_f32 v143, v6, v7
	v_pk_mul_f32 v[136:137], v[8:9], v[214:215] op_sel:[1,0] op_sel_hi:[0,0]
	v_pk_fma_f32 v[8:9], v[8:9], v[210:211], v[136:137] op_sel:[0,0,0] op_sel_hi:[1,0,1] neg_lo:[0,0,1]
	v_pk_mul_f32 v[136:137], v[10:11], v[214:215] op_sel:[1,1] op_sel_hi:[0,1]
	v_pk_fma_f32 v[10:11], v[10:11], v[210:211], v[136:137] op_sel:[0,1,0] op_sel_hi:[1,1,1] neg_lo:[0,0,1]
	v_pk_mul_f32 v[136:137], v[0:1], v[216:217] op_sel:[1,0] op_sel_hi:[0,0]
	v_pk_fma_f32 v[0:1], v[0:1], v[212:213], v[136:137] op_sel:[0,0,0] op_sel_hi:[1,0,1] neg_lo:[0,0,1]
	v_pk_mul_f32 v[136:137], v[2:3], v[216:217] op_sel:[1,1] op_sel_hi:[0,1]
	v_pk_fma_f32 v[2:3], v[2:3], v[212:213], v[136:137] op_sel:[0,1,0] op_sel_hi:[1,1,1] neg_lo:[0,0,1]
	v_pk_mul_f32 v[8:9], v[8:9], s[36:37] op_sel_hi:[1,0]
	v_pk_mul_f32 v[10:11], v[10:11], s[36:37] op_sel_hi:[1,0]
	v_pk_mul_f32 v[0:1], v[0:1], s[36:37] op_sel_hi:[1,0]
	v_pk_mul_f32 v[2:3], v[2:3], s[36:37] op_sel_hi:[1,0]
	v_cvt_pk_bf16_f32 v144, v8, v9
	v_cvt_pk_bf16_f32 v145, v10, v11
	v_cvt_pk_bf16_f32 v146, v0, v1
	v_cvt_pk_bf16_f32 v147, v2, v3
	s_waitcnt lgkmcnt(0)
	global_store_dwordx4 v130, v[218:221], s[6:7]
	global_store_dwordx4 v130, v[222:225], s[6:7] offset:64
	s_add_u32 s6, s6, s33
	s_addc_u32 s7, s7, 0
	ds_bpermute_b32 v226, v180, v140
	ds_bpermute_b32 v227, v180, v141
	ds_bpermute_b32 v228, v180, v142
	ds_bpermute_b32 v229, v180, v143
	ds_bpermute_b32 v230, v180, v144
	ds_bpermute_b32 v231, v180, v145
	ds_bpermute_b32 v232, v180, v146
	ds_bpermute_b32 v233, v180, v147
	s_waitcnt lgkmcnt(0)
	global_store_dwordx4 v130, v[226:229], s[6:7]
	global_store_dwordx4 v130, v[230:233], s[6:7] offset:64
	s_branch .LBB0_638
.Lq3_B:
	global_load_dwordx4 v[148:151], v133, s[24:25]
	global_load_dwordx4 v[152:155], v133, s[24:25] offset:16
	global_load_dwordx4 v[156:159], v133, s[24:25] offset:128
	global_load_dwordx4 v[160:163], v133, s[24:25] offset:144
	v_mul_f32_e32 v134, v127, v127
	v_fmac_f32_e32 v134, v126, v126
	v_fmac_f32_e32 v134, v128, v128
	v_fmac_f32_e32 v134, v129, v129
	v_fmac_f32_e32 v134, v122, v122
	v_fmac_f32_e32 v134, v123, v123
	v_fmac_f32_e32 v134, v124, v124
	v_fmac_f32_e32 v134, v125, v125
	v_fmac_f32_e32 v134, v118, v118
	v_fmac_f32_e32 v134, v119, v119
	v_pk_mul_f32 v[136:137], v[120:121], v[120:121]
	v_pk_mul_f32 v[138:139], v[114:115], v[114:115]
	v_add_f32_e32 v134, v136, v134
	v_add_f32_e32 v134, v137, v134
	v_add_f32_e32 v134, v138, v134
	v_pk_mul_f32 v[136:137], v[116:117], v[116:117]
	v_add_f32_e32 v134, v139, v134
	v_add_f32_e32 v134, v136, v134
	v_add_f32_e32 v134, v137, v134
	ds_swizzle_b32 v135, v134 offset:swizzle(SWAP,16)
	s_waitcnt lgkmcnt(0)
	v_add_f32_e32 v134, v134, v135
	v_mov_b32_e32 v135, v134
	s_nop 1
	v_permlane32_swap_b32 v134, v135
	s_nop 1
	v_add_f32_e32 v134, v134, v135
	v_fmamk_f32 v134, v134, 0x3c800000, v242
	v_rsq_f32_e32 v134, v134
	s_waitcnt vmcnt(0)
	v_pk_mul_f32 v[136:137], v[134:135], v[148:149] op_sel_hi:[0,1]
	v_pk_mul_f32 v[126:127], v[126:127], v[136:137]
	v_pk_mul_f32 v[136:137], v[134:135], v[150:151] op_sel_hi:[0,1]
	v_pk_mul_f32 v[128:129], v[128:129], v[136:137]
	v_pk_mul_f32 v[136:137], v[134:135], v[152:153] op_sel_hi:[0,1]
	v_pk_mul_f32 v[122:123], v[122:123], v[136:137]
	v_pk_mul_f32 v[136:137], v[134:135], v[154:155] op_sel_hi:[0,1]
	v_pk_mul_f32 v[124:125], v[124:125], v[136:137]
	v_pk_mul_f32 v[136:137], v[134:135], v[156:157] op_sel_hi:[0,1]
	v_pk_mul_f32 v[118:119], v[118:119], v[136:137]
	v_pk_mul_f32 v[136:137], v[134:135], v[158:159] op_sel_hi:[0,1]
	v_pk_mul_f32 v[120:121], v[120:121], v[136:137]
	v_pk_mul_f32 v[136:137], v[134:135], v[160:161] op_sel_hi:[0,1]
	v_pk_mul_f32 v[114:115], v[114:115], v[136:137]
	v_pk_mul_f32 v[136:137], v[134:135], v[162:163] op_sel_hi:[0,1]
	v_pk_mul_f32 v[116:117], v[116:117], v[136:137]
	v_pk_mul_f32 v[126:127], v[126:127], s[36:37] op_sel_hi:[1,0]
	v_pk_mul_f32 v[128:129], v[128:129], s[36:37] op_sel_hi:[1,0]
	v_pk_mul_f32 v[122:123], v[122:123], s[36:37] op_sel_hi:[1,0]
	v_pk_mul_f32 v[124:125], v[124:125], s[36:37] op_sel_hi:[1,0]
	v_cvt_pk_bf16_f32 v140, v126, v127
	v_cvt_pk_bf16_f32 v141, v128, v129
	v_cvt_pk_bf16_f32 v142, v122, v123
	v_cvt_pk_bf16_f32 v143, v124, v125
	v_pk_mul_f32 v[118:119], v[118:119], s[36:37] op_sel_hi:[1,0]
	v_pk_mul_f32 v[120:121], v[120:121], s[36:37] op_sel_hi:[1,0]
	v_pk_mul_f32 v[114:115], v[114:115], s[36:37] op_sel_hi:[1,0]
	v_pk_mul_f32 v[116:117], v[116:117], s[36:37] op_sel_hi:[1,0]
	v_cvt_pk_bf16_f32 v144, v118, v119
	v_cvt_pk_bf16_f32 v145, v120, v121
	v_cvt_pk_bf16_f32 v146, v114, v115
	v_cvt_pk_bf16_f32 v147, v116, v117
	ds_bpermute_b32 v218, v180, v140
	ds_bpermute_b32 v219, v180, v141
	ds_bpermute_b32 v220, v180, v142
	ds_bpermute_b32 v221, v180, v143
	ds_bpermute_b32 v222, v180, v144
	ds_bpermute_b32 v223, v180, v145
	ds_bpermute_b32 v224, v180, v146
	ds_bpermute_b32 v225, v180, v147
	v_mul_f32_e32 v134, v109, v109
	v_fmac_f32_e32 v134, v108, v108
	v_fmac_f32_e32 v134, v110, v110
	v_fmac_f32_e32 v134, v111, v111
	v_fmac_f32_e32 v134, v104, v104
	v_fmac_f32_e32 v134, v105, v105
	v_fmac_f32_e32 v134, v106, v106
	v_fmac_f32_e32 v134, v107, v107
	v_fmac_f32_e32 v134, v100, v100
	v_fmac_f32_e32 v134, v101, v101
	v_pk_mul_f32 v[136:137], v[102:103], v[102:103]
	v_pk_mul_f32 v[138:139], v[96:97], v[96:97]
	v_add_f32_e32 v134, v136, v134
	v_add_f32_e32 v134, v137, v134
	v_add_f32_e32 v134, v138, v134
	v_pk_mul_f32 v[136:137], v[98:99], v[98:99]
	v_add_f32_e32 v134, v139, v134
	v_add_f32_e32 v134, v136, v134
	v_add_f32_e32 v134, v137, v134
	ds_swizzle_b32 v135, v134 offset:swizzle(SWAP,16)
	s_waitcnt lgkmcnt(0)
	v_add_f32_e32 v134, v134, v135
	v_mov_b32_e32 v135, v134
	s_nop 1
	v_permlane32_swap_b32 v134, v135
	s_nop 1
	v_add_f32_e32 v134, v134, v135
	v_fmamk_f32 v134, v134, 0x3c800000, v242
	v_rsq_f32_e32 v134, v134
	s_nop 0
	v_pk_mul_f32 v[136:137], v[134:135], v[148:149] op_sel_hi:[0,1]
	v_pk_mul_f32 v[108:109], v[108:109], v[136:137]
	v_pk_mul_f32 v[136:137], v[134:135], v[150:151] op_sel_hi:[0,1]
	v_pk_mul_f32 v[110:111], v[110:111], v[136:137]
	v_pk_mul_f32 v[136:137], v[134:135], v[152:153] op_sel_hi:[0,1]
	v_pk_mul_f32 v[104:105], v[104:105], v[136:137]
	v_pk_mul_f32 v[136:137], v[134:135], v[154:155] op_sel_hi:[0,1]
	v_pk_mul_f32 v[106:107], v[106:107], v[136:137]
	v_pk_mul_f32 v[136:137], v[134:135], v[156:157] op_sel_hi:[0,1]
	v_pk_mul_f32 v[100:101], v[100:101], v[136:137]
	v_pk_mul_f32 v[136:137], v[134:135], v[158:159] op_sel_hi:[0,1]
	v_pk_mul_f32 v[102:103], v[102:103], v[136:137]
	v_pk_mul_f32 v[136:137], v[134:135], v[160:161] op_sel_hi:[0,1]
	v_pk_mul_f32 v[96:97], v[96:97], v[136:137]
	v_pk_mul_f32 v[136:137], v[134:135], v[162:163] op_sel_hi:[0,1]
	v_pk_mul_f32 v[98:99], v[98:99], v[136:137]
	v_pk_mul_f32 v[108:109], v[108:109], s[36:37] op_sel_hi:[1,0]
	v_pk_mul_f32 v[110:111], v[110:111], s[36:37] op_sel_hi:[1,0]
	v_pk_mul_f32 v[104:105], v[104:105], s[36:37] op_sel_hi:[1,0]
	v_pk_mul_f32 v[106:107], v[106:107], s[36:37] op_sel_hi:[1,0]
	v_cvt_pk_bf16_f32 v140, v108, v109
	v_cvt_pk_bf16_f32 v141, v110, v111
	v_cvt_pk_bf16_f32 v142, v104, v105
	v_cvt_pk_bf16_f32 v143, v106, v107
	v_pk_mul_f32 v[100:101], v[100:101], s[36:37] op_sel_hi:[1,0]
	v_pk_mul_f32 v[102:103], v[102:103], s[36:37] op_sel_hi:[1,0]
	v_pk_mul_f32 v[96:97], v[96:97], s[36:37] op_sel_hi:[1,0]
	v_pk_mul_f32 v[98:99], v[98:99], s[36:37] op_sel_hi:[1,0]
	v_cvt_pk_bf16_f32 v144, v100, v101
	v_cvt_pk_bf16_f32 v145, v102, v103
	v_cvt_pk_bf16_f32 v146, v96, v97
	v_cvt_pk_bf16_f32 v147, v98, v99
	s_waitcnt lgkmcnt(0)
	global_store_dwordx4 v130, v[218:221], s[6:7]
	global_store_dwordx4 v130, v[222:225], s[6:7] offset:64
	s_add_u32 s6, s6, s33
	s_addc_u32 s7, s7, 0
	ds_bpermute_b32 v226, v180, v140
	ds_bpermute_b32 v227, v180, v141
	ds_bpermute_b32 v228, v180, v142
	ds_bpermute_b32 v229, v180, v143
	ds_bpermute_b32 v230, v180, v144
	ds_bpermute_b32 v231, v180, v145
	ds_bpermute_b32 v232, v180, v146
	ds_bpermute_b32 v233, v180, v147
	v_mul_f32_e32 v134, v93, v93
	v_fmac_f32_e32 v134, v92, v92
	v_fmac_f32_e32 v134, v94, v94
	v_fmac_f32_e32 v134, v95, v95
	v_fmac_f32_e32 v134, v88, v88
	v_fmac_f32_e32 v134, v89, v89
	v_fmac_f32_e32 v134, v90, v90
	v_fmac_f32_e32 v134, v91, v91
	v_fmac_f32_e32 v134, v84, v84
	v_fmac_f32_e32 v134, v85, v85
	v_pk_mul_f32 v[136:137], v[86:87], v[86:87]
	v_pk_mul_f32 v[138:139], v[80:81], v[80:81]
	v_add_f32_e32 v134, v136, v134
	v_add_f32_e32 v134, v137, v134
	v_add_f32_e32 v134, v138, v134
	v_pk_mul_f32 v[136:137], v[82:83], v[82:83]
	v_add_f32_e32 v134, v139, v134
	v_add_f32_e32 v134, v136, v134
	v_add_f32_e32 v134, v137, v134
	ds_swizzle_b32 v135, v134 offset:swizzle(SWAP,16)
	s_waitcnt lgkmcnt(0)
	v_add_f32_e32 v134, v134, v135
	v_mov_b32_e32 v135, v134
	s_nop 1
	v_permlane32_swap_b32 v134, v135
	s_nop 1
	v_add_f32_e32 v134, v134, v135
	v_fmamk_f32 v134, v134, 0x3c800000, v242
	v_rsq_f32_e32 v134, v134
	s_nop 0
	v_pk_mul_f32 v[136:137], v[134:135], v[148:149] op_sel_hi:[0,1]
	v_pk_mul_f32 v[92:93], v[92:93], v[136:137]
	v_pk_mul_f32 v[136:137], v[134:135], v[150:151] op_sel_hi:[0,1]
	v_pk_mul_f32 v[94:95], v[94:95], v[136:137]
	v_pk_mul_f32 v[136:137], v[134:135], v[152:153] op_sel_hi:[0,1]
	v_pk_mul_f32 v[88:89], v[88:89], v[136:137]
	v_pk_mul_f32 v[136:137], v[134:135], v[154:155] op_sel_hi:[0,1]
	v_pk_mul_f32 v[90:91], v[90:91], v[136:137]
	v_pk_mul_f32 v[136:137], v[134:135], v[156:157] op_sel_hi:[0,1]
	v_pk_mul_f32 v[84:85], v[84:85], v[136:137]
	v_pk_mul_f32 v[136:137], v[134:135], v[158:159] op_sel_hi:[0,1]
	v_pk_mul_f32 v[86:87], v[86:87], v[136:137]
	v_pk_mul_f32 v[136:137], v[134:135], v[160:161] op_sel_hi:[0,1]
	v_pk_mul_f32 v[80:81], v[80:81], v[136:137]
	v_pk_mul_f32 v[136:137], v[134:135], v[162:163] op_sel_hi:[0,1]
	v_pk_mul_f32 v[82:83], v[82:83], v[136:137]
	v_pk_mul_f32 v[92:93], v[92:93], s[36:37] op_sel_hi:[1,0]
	v_pk_mul_f32 v[94:95], v[94:95], s[36:37] op_sel_hi:[1,0]
	v_pk_mul_f32 v[88:89], v[88:89], s[36:37] op_sel_hi:[1,0]
	v_pk_mul_f32 v[90:91], v[90:91], s[36:37] op_sel_hi:[1,0]
	v_cvt_pk_bf16_f32 v140, v92, v93
	v_cvt_pk_bf16_f32 v141, v94, v95
	v_cvt_pk_bf16_f32 v142, v88, v89
	v_cvt_pk_bf16_f32 v143, v90, v91
	v_pk_mul_f32 v[84:85], v[84:85], s[36:37] op_sel_hi:[1,0]
	v_pk_mul_f32 v[86:87], v[86:87], s[36:37] op_sel_hi:[1,0]
	v_pk_mul_f32 v[80:81], v[80:81], s[36:37] op_sel_hi:[1,0]
	v_pk_mul_f32 v[82:83], v[82:83], s[36:37] op_sel_hi:[1,0]
	v_cvt_pk_bf16_f32 v144, v84, v85
	v_cvt_pk_bf16_f32 v145, v86, v87
	v_cvt_pk_bf16_f32 v146, v80, v81
	v_cvt_pk_bf16_f32 v147, v82, v83
	s_waitcnt lgkmcnt(0)
	global_store_dwordx4 v130, v[226:229], s[6:7]
	global_store_dwordx4 v130, v[230:233], s[6:7] offset:64
	s_add_u32 s6, s6, s33
	s_addc_u32 s7, s7, 0
	ds_bpermute_b32 v218, v180, v140
	ds_bpermute_b32 v219, v180, v141
	ds_bpermute_b32 v220, v180, v142
	ds_bpermute_b32 v221, v180, v143
	ds_bpermute_b32 v222, v180, v144
	ds_bpermute_b32 v223, v180, v145
	ds_bpermute_b32 v224, v180, v146
	ds_bpermute_b32 v225, v180, v147
	v_mul_f32_e32 v134, v77, v77
	v_fmac_f32_e32 v134, v76, v76
	v_fmac_f32_e32 v134, v78, v78
	v_fmac_f32_e32 v134, v79, v79
	v_fmac_f32_e32 v134, v72, v72
	v_fmac_f32_e32 v134, v73, v73
	v_fmac_f32_e32 v134, v74, v74
	v_fmac_f32_e32 v134, v75, v75
	v_fmac_f32_e32 v134, v68, v68
	v_fmac_f32_e32 v134, v69, v69
	v_pk_mul_f32 v[136:137], v[70:71], v[70:71]
	v_pk_mul_f32 v[138:139], v[64:65], v[64:65]
	v_add_f32_e32 v134, v136, v134
	v_add_f32_e32 v134, v137, v134
	v_add_f32_e32 v134, v138, v134
	v_pk_mul_f32 v[136:137], v[66:67], v[66:67]
	v_add_f32_e32 v134, v139, v134
	v_add_f32_e32 v134, v136, v134
	v_add_f32_e32 v134, v137, v134
	ds_swizzle_b32 v135, v134 offset:swizzle(SWAP,16)
	s_waitcnt lgkmcnt(0)
	v_add_f32_e32 v134, v134, v135
	v_mov_b32_e32 v135, v134
	s_nop 1
	v_permlane32_swap_b32 v134, v135
	s_nop 1
	v_add_f32_e32 v134, v134, v135
	v_fmamk_f32 v134, v134, 0x3c800000, v242
	v_rsq_f32_e32 v134, v134
	s_nop 0
	v_pk_mul_f32 v[136:137], v[134:135], v[148:149] op_sel_hi:[0,1]
	v_pk_mul_f32 v[76:77], v[76:77], v[136:137]
	v_pk_mul_f32 v[136:137], v[134:135], v[150:151] op_sel_hi:[0,1]
	v_pk_mul_f32 v[78:79], v[78:79], v[136:137]
	v_pk_mul_f32 v[136:137], v[134:135], v[152:153] op_sel_hi:[0,1]
	v_pk_mul_f32 v[72:73], v[72:73], v[136:137]
	v_pk_mul_f32 v[136:137], v[134:135], v[154:155] op_sel_hi:[0,1]
	v_pk_mul_f32 v[74:75], v[74:75], v[136:137]
	v_pk_mul_f32 v[136:137], v[134:135], v[156:157] op_sel_hi:[0,1]
	v_pk_mul_f32 v[68:69], v[68:69], v[136:137]
	v_pk_mul_f32 v[136:137], v[134:135], v[158:159] op_sel_hi:[0,1]
	v_pk_mul_f32 v[70:71], v[70:71], v[136:137]
	v_pk_mul_f32 v[136:137], v[134:135], v[160:161] op_sel_hi:[0,1]
	v_pk_mul_f32 v[64:65], v[64:65], v[136:137]
	v_pk_mul_f32 v[136:137], v[134:135], v[162:163] op_sel_hi:[0,1]
	v_pk_mul_f32 v[66:67], v[66:67], v[136:137]
	v_pk_mul_f32 v[76:77], v[76:77], s[36:37] op_sel_hi:[1,0]
	v_pk_mul_f32 v[78:79], v[78:79], s[36:37] op_sel_hi:[1,0]
	v_pk_mul_f32 v[72:73], v[72:73], s[36:37] op_sel_hi:[1,0]
	v_pk_mul_f32 v[74:75], v[74:75], s[36:37] op_sel_hi:[1,0]
	v_cvt_pk_bf16_f32 v140, v76, v77
	v_cvt_pk_bf16_f32 v141, v78, v79
	v_cvt_pk_bf16_f32 v142, v72, v73
	v_cvt_pk_bf16_f32 v143, v74, v75
	v_pk_mul_f32 v[68:69], v[68:69], s[36:37] op_sel_hi:[1,0]
	v_pk_mul_f32 v[70:71], v[70:71], s[36:37] op_sel_hi:[1,0]
	v_pk_mul_f32 v[64:65], v[64:65], s[36:37] op_sel_hi:[1,0]
	v_pk_mul_f32 v[66:67], v[66:67], s[36:37] op_sel_hi:[1,0]
	v_cvt_pk_bf16_f32 v144, v68, v69
	v_cvt_pk_bf16_f32 v145, v70, v71
	v_cvt_pk_bf16_f32 v146, v64, v65
	v_cvt_pk_bf16_f32 v147, v66, v67
	s_waitcnt lgkmcnt(0)
	global_store_dwordx4 v130, v[218:221], s[6:7]
	global_store_dwordx4 v130, v[222:225], s[6:7] offset:64
	s_add_u32 s6, s6, s33
	s_addc_u32 s7, s7, 0
	ds_bpermute_b32 v226, v180, v140
	ds_bpermute_b32 v227, v180, v141
	ds_bpermute_b32 v228, v180, v142
	ds_bpermute_b32 v229, v180, v143
	ds_bpermute_b32 v230, v180, v144
	ds_bpermute_b32 v231, v180, v145
	ds_bpermute_b32 v232, v180, v146
	ds_bpermute_b32 v233, v180, v147
	v_mul_f32_e32 v134, v61, v61
	v_fmac_f32_e32 v134, v60, v60
	v_fmac_f32_e32 v134, v62, v62
	v_fmac_f32_e32 v134, v63, v63
	v_fmac_f32_e32 v134, v56, v56
	v_fmac_f32_e32 v134, v57, v57
	v_fmac_f32_e32 v134, v58, v58
	v_fmac_f32_e32 v134, v59, v59
	v_fmac_f32_e32 v134, v52, v52
	v_fmac_f32_e32 v134, v53, v53
	v_pk_mul_f32 v[136:137], v[54:55], v[54:55]
	v_pk_mul_f32 v[138:139], v[48:49], v[48:49]
	v_add_f32_e32 v134, v136, v134
	v_add_f32_e32 v134, v137, v134
	v_add_f32_e32 v134, v138, v134
	v_pk_mul_f32 v[136:137], v[50:51], v[50:51]
	v_add_f32_e32 v134, v139, v134
	v_add_f32_e32 v134, v136, v134
	v_add_f32_e32 v134, v137, v134
	ds_swizzle_b32 v135, v134 offset:swizzle(SWAP,16)
	s_waitcnt lgkmcnt(0)
	v_add_f32_e32 v134, v134, v135
	v_mov_b32_e32 v135, v134
	s_nop 1
	v_permlane32_swap_b32 v134, v135
	s_nop 1
	v_add_f32_e32 v134, v134, v135
	v_fmamk_f32 v134, v134, 0x3c800000, v242
	v_rsq_f32_e32 v134, v134
	s_nop 0
	v_pk_mul_f32 v[136:137], v[134:135], v[148:149] op_sel_hi:[0,1]
	v_pk_mul_f32 v[60:61], v[60:61], v[136:137]
	v_pk_mul_f32 v[136:137], v[134:135], v[150:151] op_sel_hi:[0,1]
	v_pk_mul_f32 v[62:63], v[62:63], v[136:137]
	v_pk_mul_f32 v[136:137], v[134:135], v[152:153] op_sel_hi:[0,1]
	v_pk_mul_f32 v[56:57], v[56:57], v[136:137]
	v_pk_mul_f32 v[136:137], v[134:135], v[154:155] op_sel_hi:[0,1]
	v_pk_mul_f32 v[58:59], v[58:59], v[136:137]
	v_pk_mul_f32 v[136:137], v[134:135], v[156:157] op_sel_hi:[0,1]
	v_pk_mul_f32 v[52:53], v[52:53], v[136:137]
	v_pk_mul_f32 v[136:137], v[134:135], v[158:159] op_sel_hi:[0,1]
	v_pk_mul_f32 v[54:55], v[54:55], v[136:137]
	v_pk_mul_f32 v[136:137], v[134:135], v[160:161] op_sel_hi:[0,1]
	v_pk_mul_f32 v[48:49], v[48:49], v[136:137]
	v_pk_mul_f32 v[136:137], v[134:135], v[162:163] op_sel_hi:[0,1]
	v_pk_mul_f32 v[50:51], v[50:51], v[136:137]
	v_pk_mul_f32 v[60:61], v[60:61], s[36:37] op_sel_hi:[1,0]
	v_pk_mul_f32 v[62:63], v[62:63], s[36:37] op_sel_hi:[1,0]
	v_pk_mul_f32 v[56:57], v[56:57], s[36:37] op_sel_hi:[1,0]
	v_pk_mul_f32 v[58:59], v[58:59], s[36:37] op_sel_hi:[1,0]
	v_cvt_pk_bf16_f32 v140, v60, v61
	v_cvt_pk_bf16_f32 v141, v62, v63
	v_cvt_pk_bf16_f32 v142, v56, v57
	v_cvt_pk_bf16_f32 v143, v58, v59
	v_pk_mul_f32 v[52:53], v[52:53], s[36:37] op_sel_hi:[1,0]
	v_pk_mul_f32 v[54:55], v[54:55], s[36:37] op_sel_hi:[1,0]
	v_pk_mul_f32 v[48:49], v[48:49], s[36:37] op_sel_hi:[1,0]
	v_pk_mul_f32 v[50:51], v[50:51], s[36:37] op_sel_hi:[1,0]
	v_cvt_pk_bf16_f32 v144, v52, v53
	v_cvt_pk_bf16_f32 v145, v54, v55
	v_cvt_pk_bf16_f32 v146, v48, v49
	v_cvt_pk_bf16_f32 v147, v50, v51
	s_waitcnt lgkmcnt(0)
	global_store_dwordx4 v130, v[226:229], s[6:7]
	global_store_dwordx4 v130, v[230:233], s[6:7] offset:64
	s_add_u32 s6, s6, s34
	s_addc_u32 s7, s7, 0
	ds_bpermute_b32 v218, v180, v140
	ds_bpermute_b32 v219, v180, v141
	ds_bpermute_b32 v220, v180, v142
	ds_bpermute_b32 v221, v180, v143
	ds_bpermute_b32 v222, v180, v144
	ds_bpermute_b32 v223, v180, v145
	ds_bpermute_b32 v224, v180, v146
	ds_bpermute_b32 v225, v180, v147
	v_mul_f32_e32 v134, v45, v45
	v_fmac_f32_e32 v134, v44, v44
	v_fmac_f32_e32 v134, v46, v46
	v_fmac_f32_e32 v134, v47, v47
	v_fmac_f32_e32 v134, v40, v40
	v_fmac_f32_e32 v134, v41, v41
	v_fmac_f32_e32 v134, v42, v42
	v_fmac_f32_e32 v134, v43, v43
	v_fmac_f32_e32 v134, v36, v36
	v_fmac_f32_e32 v134, v37, v37
	v_pk_mul_f32 v[136:137], v[38:39], v[38:39]
	v_pk_mul_f32 v[138:139], v[32:33], v[32:33]
	v_add_f32_e32 v134, v136, v134
	v_add_f32_e32 v134, v137, v134
	v_add_f32_e32 v134, v138, v134
	v_pk_mul_f32 v[136:137], v[34:35], v[34:35]
	v_add_f32_e32 v134, v139, v134
	v_add_f32_e32 v134, v136, v134
	v_add_f32_e32 v134, v137, v134
	ds_swizzle_b32 v135, v134 offset:swizzle(SWAP,16)
	s_waitcnt lgkmcnt(0)
	v_add_f32_e32 v134, v134, v135
	v_mov_b32_e32 v135, v134
	s_nop 1
	v_permlane32_swap_b32 v134, v135
	s_nop 1
	v_add_f32_e32 v134, v134, v135
	v_fmamk_f32 v134, v134, 0x3c800000, v242
	v_rsq_f32_e32 v134, v134
	s_nop 0
	v_pk_mul_f32 v[136:137], v[134:135], v[148:149] op_sel_hi:[0,1]
	v_pk_mul_f32 v[44:45], v[44:45], v[136:137]
	v_pk_mul_f32 v[136:137], v[134:135], v[150:151] op_sel_hi:[0,1]
	v_pk_mul_f32 v[46:47], v[46:47], v[136:137]
	v_pk_mul_f32 v[136:137], v[134:135], v[152:153] op_sel_hi:[0,1]
	v_pk_mul_f32 v[40:41], v[40:41], v[136:137]
	v_pk_mul_f32 v[136:137], v[134:135], v[154:155] op_sel_hi:[0,1]
	v_pk_mul_f32 v[42:43], v[42:43], v[136:137]
	v_pk_mul_f32 v[136:137], v[134:135], v[156:157] op_sel_hi:[0,1]
	v_pk_mul_f32 v[36:37], v[36:37], v[136:137]
	v_pk_mul_f32 v[136:137], v[134:135], v[158:159] op_sel_hi:[0,1]
	v_pk_mul_f32 v[38:39], v[38:39], v[136:137]
	v_pk_mul_f32 v[136:137], v[134:135], v[160:161] op_sel_hi:[0,1]
	v_pk_mul_f32 v[32:33], v[32:33], v[136:137]
	v_pk_mul_f32 v[136:137], v[134:135], v[162:163] op_sel_hi:[0,1]
	v_pk_mul_f32 v[34:35], v[34:35], v[136:137]
	v_pk_mul_f32 v[44:45], v[44:45], s[36:37] op_sel_hi:[1,0]
	v_pk_mul_f32 v[46:47], v[46:47], s[36:37] op_sel_hi:[1,0]
	v_pk_mul_f32 v[40:41], v[40:41], s[36:37] op_sel_hi:[1,0]
	v_pk_mul_f32 v[42:43], v[42:43], s[36:37] op_sel_hi:[1,0]
	v_cvt_pk_bf16_f32 v140, v44, v45
	v_cvt_pk_bf16_f32 v141, v46, v47
	v_cvt_pk_bf16_f32 v142, v40, v41
	v_cvt_pk_bf16_f32 v143, v42, v43
	v_pk_mul_f32 v[36:37], v[36:37], s[36:37] op_sel_hi:[1,0]
	v_pk_mul_f32 v[38:39], v[38:39], s[36:37] op_sel_hi:[1,0]
	v_pk_mul_f32 v[32:33], v[32:33], s[36:37] op_sel_hi:[1,0]
	v_pk_mul_f32 v[34:35], v[34:35], s[36:37] op_sel_hi:[1,0]
	v_cvt_pk_bf16_f32 v144, v36, v37
	v_cvt_pk_bf16_f32 v145, v38, v39
	v_cvt_pk_bf16_f32 v146, v32, v33
	v_cvt_pk_bf16_f32 v147, v34, v35
	s_waitcnt lgkmcnt(0)
	global_store_dwordx4 v130, v[218:221], s[6:7]
	global_store_dwordx4 v130, v[222:225], s[6:7] offset:64
	s_add_u32 s6, s6, s33
	s_addc_u32 s7, s7, 0
	ds_bpermute_b32 v226, v180, v140
	ds_bpermute_b32 v227, v180, v141
	ds_bpermute_b32 v228, v180, v142
	ds_bpermute_b32 v229, v180, v143
	ds_bpermute_b32 v230, v180, v144
	ds_bpermute_b32 v231, v180, v145
	ds_bpermute_b32 v232, v180, v146
	ds_bpermute_b32 v233, v180, v147
	v_mul_f32_e32 v134, v29, v29
	v_fmac_f32_e32 v134, v28, v28
	v_fmac_f32_e32 v134, v30, v30
	v_fmac_f32_e32 v134, v31, v31
	v_fmac_f32_e32 v134, v24, v24
	v_fmac_f32_e32 v134, v25, v25
	v_fmac_f32_e32 v134, v26, v26
	v_fmac_f32_e32 v134, v27, v27
	v_fmac_f32_e32 v134, v20, v20
	v_fmac_f32_e32 v134, v21, v21
	v_pk_mul_f32 v[136:137], v[22:23], v[22:23]
	v_pk_mul_f32 v[138:139], v[16:17], v[16:17]
	v_add_f32_e32 v134, v136, v134
	v_add_f32_e32 v134, v137, v134
	v_add_f32_e32 v134, v138, v134
	v_pk_mul_f32 v[136:137], v[18:19], v[18:19]
	v_add_f32_e32 v134, v139, v134
	v_add_f32_e32 v134, v136, v134
	v_add_f32_e32 v134, v137, v134
	ds_swizzle_b32 v135, v134 offset:swizzle(SWAP,16)
	s_waitcnt lgkmcnt(0)
	v_add_f32_e32 v134, v134, v135
	v_mov_b32_e32 v135, v134
	s_nop 1
	v_permlane32_swap_b32 v134, v135
	s_nop 1
	v_add_f32_e32 v134, v134, v135
	v_fmamk_f32 v134, v134, 0x3c800000, v242
	v_rsq_f32_e32 v134, v134
	s_nop 0
	v_pk_mul_f32 v[136:137], v[134:135], v[148:149] op_sel_hi:[0,1]
	v_pk_mul_f32 v[28:29], v[28:29], v[136:137]
	v_pk_mul_f32 v[136:137], v[134:135], v[150:151] op_sel_hi:[0,1]
	v_pk_mul_f32 v[30:31], v[30:31], v[136:137]
	v_pk_mul_f32 v[136:137], v[134:135], v[152:153] op_sel_hi:[0,1]
	v_pk_mul_f32 v[24:25], v[24:25], v[136:137]
	v_pk_mul_f32 v[136:137], v[134:135], v[154:155] op_sel_hi:[0,1]
	v_pk_mul_f32 v[26:27], v[26:27], v[136:137]
	v_pk_mul_f32 v[136:137], v[134:135], v[156:157] op_sel_hi:[0,1]
	v_pk_mul_f32 v[20:21], v[20:21], v[136:137]
	v_pk_mul_f32 v[136:137], v[134:135], v[158:159] op_sel_hi:[0,1]
	v_pk_mul_f32 v[22:23], v[22:23], v[136:137]
	v_pk_mul_f32 v[136:137], v[134:135], v[160:161] op_sel_hi:[0,1]
	v_pk_mul_f32 v[16:17], v[16:17], v[136:137]
	v_pk_mul_f32 v[136:137], v[134:135], v[162:163] op_sel_hi:[0,1]
	v_pk_mul_f32 v[18:19], v[18:19], v[136:137]
	v_pk_mul_f32 v[28:29], v[28:29], s[36:37] op_sel_hi:[1,0]
	v_pk_mul_f32 v[30:31], v[30:31], s[36:37] op_sel_hi:[1,0]
	v_pk_mul_f32 v[24:25], v[24:25], s[36:37] op_sel_hi:[1,0]
	v_pk_mul_f32 v[26:27], v[26:27], s[36:37] op_sel_hi:[1,0]
	v_cvt_pk_bf16_f32 v140, v28, v29
	v_cvt_pk_bf16_f32 v141, v30, v31
	v_cvt_pk_bf16_f32 v142, v24, v25
	v_cvt_pk_bf16_f32 v143, v26, v27
	v_pk_mul_f32 v[20:21], v[20:21], s[36:37] op_sel_hi:[1,0]
	v_pk_mul_f32 v[22:23], v[22:23], s[36:37] op_sel_hi:[1,0]
	v_pk_mul_f32 v[16:17], v[16:17], s[36:37] op_sel_hi:[1,0]
	v_pk_mul_f32 v[18:19], v[18:19], s[36:37] op_sel_hi:[1,0]
	v_cvt_pk_bf16_f32 v144, v20, v21
	v_cvt_pk_bf16_f32 v145, v22, v23
	v_cvt_pk_bf16_f32 v146, v16, v17
	v_cvt_pk_bf16_f32 v147, v18, v19
	s_waitcnt lgkmcnt(0)
	global_store_dwordx4 v130, v[226:229], s[6:7]
	global_store_dwordx4 v130, v[230:233], s[6:7] offset:64
	s_add_u32 s6, s6, s33
	s_addc_u32 s7, s7, 0
	ds_bpermute_b32 v218, v180, v140
	ds_bpermute_b32 v219, v180, v141
	ds_bpermute_b32 v220, v180, v142
	ds_bpermute_b32 v221, v180, v143
	ds_bpermute_b32 v222, v180, v144
	ds_bpermute_b32 v223, v180, v145
	ds_bpermute_b32 v224, v180, v146
	ds_bpermute_b32 v225, v180, v147
	v_mul_f32_e32 v134, v13, v13
	v_fmac_f32_e32 v134, v12, v12
	v_fmac_f32_e32 v134, v14, v14
	v_fmac_f32_e32 v134, v15, v15
	v_fmac_f32_e32 v134, v4, v4
	v_fmac_f32_e32 v134, v5, v5
	v_fmac_f32_e32 v134, v6, v6
	v_fmac_f32_e32 v134, v7, v7
	v_fmac_f32_e32 v134, v8, v8
	v_fmac_f32_e32 v134, v9, v9
	v_pk_mul_f32 v[136:137], v[10:11], v[10:11]
	v_pk_mul_f32 v[138:139], v[0:1], v[0:1]
	v_add_f32_e32 v134, v136, v134
	v_add_f32_e32 v134, v137, v134
	v_add_f32_e32 v134, v138, v134
	v_pk_mul_f32 v[136:137], v[2:3], v[2:3]
	v_add_f32_e32 v134, v139, v134
	v_add_f32_e32 v134, v136, v134
	v_add_f32_e32 v134, v137, v134
	ds_swizzle_b32 v135, v134 offset:swizzle(SWAP,16)
	s_waitcnt lgkmcnt(0)
	v_add_f32_e32 v134, v134, v135
	v_mov_b32_e32 v135, v134
	s_nop 1
	v_permlane32_swap_b32 v134, v135
	s_nop 1
	v_add_f32_e32 v134, v134, v135
	v_fmamk_f32 v134, v134, 0x3c800000, v242
	v_rsq_f32_e32 v134, v134
	s_nop 0
	v_pk_mul_f32 v[136:137], v[134:135], v[148:149] op_sel_hi:[0,1]
	v_pk_mul_f32 v[12:13], v[12:13], v[136:137]
	v_pk_mul_f32 v[136:137], v[134:135], v[150:151] op_sel_hi:[0,1]
	v_pk_mul_f32 v[14:15], v[14:15], v[136:137]
	v_pk_mul_f32 v[136:137], v[134:135], v[152:153] op_sel_hi:[0,1]
	v_pk_mul_f32 v[4:5], v[4:5], v[136:137]
	v_pk_mul_f32 v[136:137], v[134:135], v[154:155] op_sel_hi:[0,1]
	v_pk_mul_f32 v[6:7], v[6:7], v[136:137]
	v_pk_mul_f32 v[136:137], v[134:135], v[156:157] op_sel_hi:[0,1]
	v_pk_mul_f32 v[8:9], v[8:9], v[136:137]
	v_pk_mul_f32 v[136:137], v[134:135], v[158:159] op_sel_hi:[0,1]
	v_pk_mul_f32 v[10:11], v[10:11], v[136:137]
	v_pk_mul_f32 v[136:137], v[134:135], v[160:161] op_sel_hi:[0,1]
	v_pk_mul_f32 v[0:1], v[0:1], v[136:137]
	v_pk_mul_f32 v[136:137], v[134:135], v[162:163] op_sel_hi:[0,1]
	v_pk_mul_f32 v[2:3], v[2:3], v[136:137]
	v_pk_mul_f32 v[12:13], v[12:13], s[36:37] op_sel_hi:[1,0]
	v_pk_mul_f32 v[14:15], v[14:15], s[36:37] op_sel_hi:[1,0]
	v_pk_mul_f32 v[4:5], v[4:5], s[36:37] op_sel_hi:[1,0]
	v_pk_mul_f32 v[6:7], v[6:7], s[36:37] op_sel_hi:[1,0]
	v_cvt_pk_bf16_f32 v140, v12, v13
	v_cvt_pk_bf16_f32 v141, v14, v15
	v_cvt_pk_bf16_f32 v142, v4, v5
	v_cvt_pk_bf16_f32 v143, v6, v7
	v_pk_mul_f32 v[8:9], v[8:9], s[36:37] op_sel_hi:[1,0]
	v_pk_mul_f32 v[10:11], v[10:11], s[36:37] op_sel_hi:[1,0]
	v_pk_mul_f32 v[0:1], v[0:1], s[36:37] op_sel_hi:[1,0]
	v_pk_mul_f32 v[2:3], v[2:3], s[36:37] op_sel_hi:[1,0]
	v_cvt_pk_bf16_f32 v144, v8, v9
	v_cvt_pk_bf16_f32 v145, v10, v11
	v_cvt_pk_bf16_f32 v146, v0, v1
	v_cvt_pk_bf16_f32 v147, v2, v3
	s_waitcnt lgkmcnt(0)
	global_store_dwordx4 v130, v[218:221], s[6:7]
	global_store_dwordx4 v130, v[222:225], s[6:7] offset:64
	s_add_u32 s6, s6, s33
	s_addc_u32 s7, s7, 0
	ds_bpermute_b32 v226, v180, v140
	ds_bpermute_b32 v227, v180, v141
	ds_bpermute_b32 v228, v180, v142
	ds_bpermute_b32 v229, v180, v143
	ds_bpermute_b32 v230, v180, v144
	ds_bpermute_b32 v231, v180, v145
	ds_bpermute_b32 v232, v180, v146
	ds_bpermute_b32 v233, v180, v147
	s_waitcnt lgkmcnt(0)
	global_store_dwordx4 v130, v[226:229], s[6:7]
	global_store_dwordx4 v130, v[230:233], s[6:7] offset:64
	s_branch .LBB0_638
.Lq3_C:
	global_load_dwordx4 v[164:167], v131, s[8:9]
	global_load_dwordx4 v[168:171], v132, s[8:9]
	global_load_dwordx4 v[172:175], v131, s[8:9] offset:64
	global_load_dwordx4 v[176:179], v132, s[8:9] offset:64
	s_add_u32 s8, s8, 0x800
	s_addc_u32 s9, s9, 0
	global_load_dwordx4 v[202:205], v131, s[8:9]
	global_load_dwordx4 v[206:209], v132, s[8:9]
	global_load_dwordx4 v[210:213], v131, s[8:9] offset:64
	global_load_dwordx4 v[214:217], v132, s[8:9] offset:64
	s_waitcnt vmcnt(4)
	v_pk_mul_f32 v[136:137], v[126:127], v[168:169] op_sel:[1,0] op_sel_hi:[0,0]
	v_pk_fma_f32 v[126:127], v[126:127], v[164:165], v[136:137] op_sel:[0,0,0] op_sel_hi:[1,0,1] neg_lo:[0,0,1]
	v_pk_mul_f32 v[136:137], v[128:129], v[168:169] op_sel:[1,1] op_sel_hi:[0,1]
	v_pk_fma_f32 v[128:129], v[128:129], v[164:165], v[136:137] op_sel:[0,1,0] op_sel_hi:[1,1,1] neg_lo:[0,0,1]
	v_pk_mul_f32 v[136:137], v[122:123], v[170:171] op_sel:[1,0] op_sel_hi:[0,0]
	v_pk_fma_f32 v[122:123], v[122:123], v[166:167], v[136:137] op_sel:[0,0,0] op_sel_hi:[1,0,1] neg_lo:[0,0,1]
	v_pk_mul_f32 v[136:137], v[124:125], v[170:171] op_sel:[1,1] op_sel_hi:[0,1]
	v_pk_fma_f32 v[124:125], v[124:125], v[166:167], v[136:137] op_sel:[0,1,0] op_sel_hi:[1,1,1] neg_lo:[0,0,1]
	v_pk_mul_f32 v[126:127], v[126:127], s[36:37] op_sel_hi:[1,0]
	v_pk_mul_f32 v[128:129], v[128:129], s[36:37] op_sel_hi:[1,0]
	v_pk_mul_f32 v[122:123], v[122:123], s[36:37] op_sel_hi:[1,0]
	v_pk_mul_f32 v[124:125], v[124:125], s[36:37] op_sel_hi:[1,0]
	v_cvt_pk_bf16_f32 v140, v126, v127
	v_cvt_pk_bf16_f32 v141, v128, v129
	v_cvt_pk_bf16_f32 v142, v122, v123
	v_cvt_pk_bf16_f32 v143, v124, v125
	v_pk_mul_f32 v[136:137], v[118:119], v[176:177] op_sel:[1,0] op_sel_hi:[0,0]
	v_pk_fma_f32 v[118:119], v[118:119], v[172:173], v[136:137] op_sel:[0,0,0] op_sel_hi:[1,0,1] neg_lo:[0,0,1]
	v_pk_mul_f32 v[136:137], v[120:121], v[176:177] op_sel:[1,1] op_sel_hi:[0,1]
	v_pk_fma_f32 v[120:121], v[120:121], v[172:173], v[136:137] op_sel:[0,1,0] op_sel_hi:[1,1,1] neg_lo:[0,0,1]
	v_pk_mul_f32 v[136:137], v[114:115], v[178:179] op_sel:[1,0] op_sel_hi:[0,0]
	v_pk_fma_f32 v[114:115], v[114:115], v[174:175], v[136:137] op_sel:[0,0,0] op_sel_hi:[1,0,1] neg_lo:[0,0,1]
	v_pk_mul_f32 v[136:137], v[116:117], v[178:179] op_sel:[1,1] op_sel_hi:[0,1]
	v_pk_fma_f32 v[116:117], v[116:117], v[174:175], v[136:137] op_sel:[0,1,0] op_sel_hi:[1,1,1] neg_lo:[0,0,1]
	v_pk_mul_f32 v[118:119], v[118:119], s[36:37] op_sel_hi:[1,0]
	v_pk_mul_f32 v[120:121], v[120:121], s[36:37] op_sel_hi:[1,0]
	v_pk_mul_f32 v[114:115], v[114:115], s[36:37] op_sel_hi:[1,0]
	v_pk_mul_f32 v[116:117], v[116:117], s[36:37] op_sel_hi:[1,0]
	v_cvt_pk_bf16_f32 v144, v118, v119
	v_cvt_pk_bf16_f32 v145, v120, v121
	v_cvt_pk_bf16_f32 v146, v114, v115
	v_cvt_pk_bf16_f32 v147, v116, v117
	ds_bpermute_b32 v218, v180, v140
	ds_bpermute_b32 v219, v180, v141
	ds_bpermute_b32 v220, v180, v142
	ds_bpermute_b32 v221, v180, v143
	ds_bpermute_b32 v222, v180, v144
	ds_bpermute_b32 v223, v180, v145
	ds_bpermute_b32 v224, v180, v146
	ds_bpermute_b32 v225, v180, v147
	s_add_u32 s8, s8, 0x800
	s_addc_u32 s9, s9, 0
	global_load_dwordx4 v[164:167], v131, s[8:9]
	global_load_dwordx4 v[168:171], v132, s[8:9]
	global_load_dwordx4 v[172:175], v131, s[8:9] offset:64
	global_load_dwordx4 v[176:179], v132, s[8:9] offset:64
	s_waitcnt vmcnt(4)
	v_pk_mul_f32 v[136:137], v[108:109], v[206:207] op_sel:[1,0] op_sel_hi:[0,0]
	v_pk_fma_f32 v[108:109], v[108:109], v[202:203], v[136:137] op_sel:[0,0,0] op_sel_hi:[1,0,1] neg_lo:[0,0,1]
	v_pk_mul_f32 v[136:137], v[110:111], v[206:207] op_sel:[1,1] op_sel_hi:[0,1]
	v_pk_fma_f32 v[110:111], v[110:111], v[202:203], v[136:137] op_sel:[0,1,0] op_sel_hi:[1,1,1] neg_lo:[0,0,1]
	v_pk_mul_f32 v[136:137], v[104:105], v[208:209] op_sel:[1,0] op_sel_hi:[0,0]
	v_pk_fma_f32 v[104:105], v[104:105], v[204:205], v[136:137] op_sel:[0,0,0] op_sel_hi:[1,0,1] neg_lo:[0,0,1]
	v_pk_mul_f32 v[136:137], v[106:107], v[208:209] op_sel:[1,1] op_sel_hi:[0,1]
	v_pk_fma_f32 v[106:107], v[106:107], v[204:205], v[136:137] op_sel:[0,1,0] op_sel_hi:[1,1,1] neg_lo:[0,0,1]
	v_pk_mul_f32 v[108:109], v[108:109], s[36:37] op_sel_hi:[1,0]
	v_pk_mul_f32 v[110:111], v[110:111], s[36:37] op_sel_hi:[1,0]
	v_pk_mul_f32 v[104:105], v[104:105], s[36:37] op_sel_hi:[1,0]
	v_pk_mul_f32 v[106:107], v[106:107], s[36:37] op_sel_hi:[1,0]
	v_cvt_pk_bf16_f32 v140, v108, v109
	v_cvt_pk_bf16_f32 v141, v110, v111
	v_cvt_pk_bf16_f32 v142, v104, v105
	v_cvt_pk_bf16_f32 v143, v106, v107
	v_pk_mul_f32 v[136:137], v[100:101], v[214:215] op_sel:[1,0] op_sel_hi:[0,0]
	v_pk_fma_f32 v[100:101], v[100:101], v[210:211], v[136:137] op_sel:[0,0,0] op_sel_hi:[1,0,1] neg_lo:[0,0,1]
	v_pk_mul_f32 v[136:137], v[102:103], v[214:215] op_sel:[1,1] op_sel_hi:[0,1]
	v_pk_fma_f32 v[102:103], v[102:103], v[210:211], v[136:137] op_sel:[0,1,0] op_sel_hi:[1,1,1] neg_lo:[0,0,1]
	v_pk_mul_f32 v[136:137], v[96:97], v[216:217] op_sel:[1,0] op_sel_hi:[0,0]
	v_pk_fma_f32 v[96:97], v[96:97], v[212:213], v[136:137] op_sel:[0,0,0] op_sel_hi:[1,0,1] neg_lo:[0,0,1]
	v_pk_mul_f32 v[136:137], v[98:99], v[216:217] op_sel:[1,1] op_sel_hi:[0,1]
	v_pk_fma_f32 v[98:99], v[98:99], v[212:213], v[136:137] op_sel:[0,1,0] op_sel_hi:[1,1,1] neg_lo:[0,0,1]
	v_pk_mul_f32 v[100:101], v[100:101], s[36:37] op_sel_hi:[1,0]
	v_pk_mul_f32 v[102:103], v[102:103], s[36:37] op_sel_hi:[1,0]
	v_pk_mul_f32 v[96:97], v[96:97], s[36:37] op_sel_hi:[1,0]
	v_pk_mul_f32 v[98:99], v[98:99], s[36:37] op_sel_hi:[1,0]
	v_cvt_pk_bf16_f32 v144, v100, v101
	v_cvt_pk_bf16_f32 v145, v102, v103
	v_cvt_pk_bf16_f32 v146, v96, v97
	v_cvt_pk_bf16_f32 v147, v98, v99
	s_waitcnt lgkmcnt(0)
	global_store_dwordx4 v130, v[218:221], s[6:7]
	global_store_dwordx4 v130, v[222:225], s[6:7] offset:64
	s_add_u32 s6, s6, s33
	s_addc_u32 s7, s7, 0
	ds_bpermute_b32 v226, v180, v140
	ds_bpermute_b32 v227, v180, v141
	ds_bpermute_b32 v228, v180, v142
	ds_bpermute_b32 v229, v180, v143
	ds_bpermute_b32 v230, v180, v144
	ds_bpermute_b32 v231, v180, v145
	ds_bpermute_b32 v232, v180, v146
	ds_bpermute_b32 v233, v180, v147
	s_add_u32 s8, s8, 0x800
	s_addc_u32 s9, s9, 0
	global_load_dwordx4 v[202:205], v131, s[8:9]
	global_load_dwordx4 v[206:209], v132, s[8:9]
	global_load_dwordx4 v[210:213], v131, s[8:9] offset:64
	global_load_dwordx4 v[214:217], v132, s[8:9] offset:64
	s_waitcnt vmcnt(6)
	v_pk_mul_f32 v[136:137], v[92:93], v[168:169] op_sel:[1,0] op_sel_hi:[0,0]
	v_pk_fma_f32 v[92:93], v[92:93], v[164:165], v[136:137] op_sel:[0,0,0] op_sel_hi:[1,0,1] neg_lo:[0,0,1]
	v_pk_mul_f32 v[136:137], v[94:95], v[168:169] op_sel:[1,1] op_sel_hi:[0,1]
	v_pk_fma_f32 v[94:95], v[94:95], v[164:165], v[136:137] op_sel:[0,1,0] op_sel_hi:[1,1,1] neg_lo:[0,0,1]
	v_pk_mul_f32 v[136:137], v[88:89], v[170:171] op_sel:[1,0] op_sel_hi:[0,0]
	v_pk_fma_f32 v[88:89], v[88:89], v[166:167], v[136:137] op_sel:[0,0,0] op_sel_hi:[1,0,1] neg_lo:[0,0,1]
	v_pk_mul_f32 v[136:137], v[90:91], v[170:171] op_sel:[1,1] op_sel_hi:[0,1]
	v_pk_fma_f32 v[90:91], v[90:91], v[166:167], v[136:137] op_sel:[0,1,0] op_sel_hi:[1,1,1] neg_lo:[0,0,1]
	v_pk_mul_f32 v[92:93], v[92:93], s[36:37] op_sel_hi:[1,0]
	v_pk_mul_f32 v[94:95], v[94:95], s[36:37] op_sel_hi:[1,0]
	v_pk_mul_f32 v[88:89], v[88:89], s[36:37] op_sel_hi:[1,0]
	v_pk_mul_f32 v[90:91], v[90:91], s[36:37] op_sel_hi:[1,0]
	v_cvt_pk_bf16_f32 v140, v92, v93
	v_cvt_pk_bf16_f32 v141, v94, v95
	v_cvt_pk_bf16_f32 v142, v88, v89
	v_cvt_pk_bf16_f32 v143, v90, v91
	v_pk_mul_f32 v[136:137], v[84:85], v[176:177] op_sel:[1,0] op_sel_hi:[0,0]
	v_pk_fma_f32 v[84:85], v[84:85], v[172:173], v[136:137] op_sel:[0,0,0] op_sel_hi:[1,0,1] neg_lo:[0,0,1]
	v_pk_mul_f32 v[136:137], v[86:87], v[176:177] op_sel:[1,1] op_sel_hi:[0,1]
	v_pk_fma_f32 v[86:87], v[86:87], v[172:173], v[136:137] op_sel:[0,1,0] op_sel_hi:[1,1,1] neg_lo:[0,0,1]
	v_pk_mul_f32 v[136:137], v[80:81], v[178:179] op_sel:[1,0] op_sel_hi:[0,0]
	v_pk_fma_f32 v[80:81], v[80:81], v[174:175], v[136:137] op_sel:[0,0,0] op_sel_hi:[1,0,1] neg_lo:[0,0,1]
	v_pk_mul_f32 v[136:137], v[82:83], v[178:179] op_sel:[1,1] op_sel_hi:[0,1]
	v_pk_fma_f32 v[82:83], v[82:83], v[174:175], v[136:137] op_sel:[0,1,0] op_sel_hi:[1,1,1] neg_lo:[0,0,1]
	v_pk_mul_f32 v[84:85], v[84:85], s[36:37] op_sel_hi:[1,0]
	v_pk_mul_f32 v[86:87], v[86:87], s[36:37] op_sel_hi:[1,0]
	v_pk_mul_f32 v[80:81], v[80:81], s[36:37] op_sel_hi:[1,0]
	v_pk_mul_f32 v[82:83], v[82:83], s[36:37] op_sel_hi:[1,0]
	v_cvt_pk_bf16_f32 v144, v84, v85
	v_cvt_pk_bf16_f32 v145, v86, v87
	v_cvt_pk_bf16_f32 v146, v80, v81
	v_cvt_pk_bf16_f32 v147, v82, v83
	s_waitcnt lgkmcnt(0)
	global_store_dwordx4 v130, v[226:229], s[6:7]
	global_store_dwordx4 v130, v[230:233], s[6:7] offset:64
	s_add_u32 s6, s6, s33
	s_addc_u32 s7, s7, 0
	ds_bpermute_b32 v218, v180, v140
	ds_bpermute_b32 v219, v180, v141
	ds_bpermute_b32 v220, v180, v142
	ds_bpermute_b32 v221, v180, v143
	ds_bpermute_b32 v222, v180, v144
	ds_bpermute_b32 v223, v180, v145
	ds_bpermute_b32 v224, v180, v146
	ds_bpermute_b32 v225, v180, v147
	s_add_u32 s8, s8, 0x2800
	s_addc_u32 s9, s9, 0
	global_load_dwordx4 v[164:167], v131, s[8:9]
	global_load_dwordx4 v[168:171], v132, s[8:9]
	global_load_dwordx4 v[172:175], v131, s[8:9] offset:64
	global_load_dwordx4 v[176:179], v132, s[8:9] offset:64
	s_waitcnt vmcnt(6)
	v_pk_mul_f32 v[136:137], v[76:77], v[206:207] op_sel:[1,0] op_sel_hi:[0,0]
	v_pk_fma_f32 v[76:77], v[76:77], v[202:203], v[136:137] op_sel:[0,0,0] op_sel_hi:[1,0,1] neg_lo:[0,0,1]
	v_pk_mul_f32 v[136:137], v[78:79], v[206:207] op_sel:[1,1] op_sel_hi:[0,1]
	v_pk_fma_f32 v[78:79], v[78:79], v[202:203], v[136:137] op_sel:[0,1,0] op_sel_hi:[1,1,1] neg_lo:[0,0,1]
	v_pk_mul_f32 v[136:137], v[72:73], v[208:209] op_sel:[1,0] op_sel_hi:[0,0]
	v_pk_fma_f32 v[72:73], v[72:73], v[204:205], v[136:137] op_sel:[0,0,0] op_sel_hi:[1,0,1] neg_lo:[0,0,1]
	v_pk_mul_f32 v[136:137], v[74:75], v[208:209] op_sel:[1,1] op_sel_hi:[0,1]
	v_pk_fma_f32 v[74:75], v[74:75], v[204:205], v[136:137] op_sel:[0,1,0] op_sel_hi:[1,1,1] neg_lo:[0,0,1]
	v_pk_mul_f32 v[76:77], v[76:77], s[36:37] op_sel_hi:[1,0]
	v_pk_mul_f32 v[78:79], v[78:79], s[36:37] op_sel_hi:[1,0]
	v_pk_mul_f32 v[72:73], v[72:73], s[36:37] op_sel_hi:[1,0]
	v_pk_mul_f32 v[74:75], v[74:75], s[36:37] op_sel_hi:[1,0]
	v_cvt_pk_bf16_f32 v140, v76, v77
	v_cvt_pk_bf16_f32 v141, v78, v79
	v_cvt_pk_bf16_f32 v142, v72, v73
	v_cvt_pk_bf16_f32 v143, v74, v75
	v_pk_mul_f32 v[136:137], v[68:69], v[214:215] op_sel:[1,0] op_sel_hi:[0,0]
	v_pk_fma_f32 v[68:69], v[68:69], v[210:211], v[136:137] op_sel:[0,0,0] op_sel_hi:[1,0,1] neg_lo:[0,0,1]
	v_pk_mul_f32 v[136:137], v[70:71], v[214:215] op_sel:[1,1] op_sel_hi:[0,1]
	v_pk_fma_f32 v[70:71], v[70:71], v[210:211], v[136:137] op_sel:[0,1,0] op_sel_hi:[1,1,1] neg_lo:[0,0,1]
	v_pk_mul_f32 v[136:137], v[64:65], v[216:217] op_sel:[1,0] op_sel_hi:[0,0]
	v_pk_fma_f32 v[64:65], v[64:65], v[212:213], v[136:137] op_sel:[0,0,0] op_sel_hi:[1,0,1] neg_lo:[0,0,1]
	v_pk_mul_f32 v[136:137], v[66:67], v[216:217] op_sel:[1,1] op_sel_hi:[0,1]
	v_pk_fma_f32 v[66:67], v[66:67], v[212:213], v[136:137] op_sel:[0,1,0] op_sel_hi:[1,1,1] neg_lo:[0,0,1]
	v_pk_mul_f32 v[68:69], v[68:69], s[36:37] op_sel_hi:[1,0]
	v_pk_mul_f32 v[70:71], v[70:71], s[36:37] op_sel_hi:[1,0]
	v_pk_mul_f32 v[64:65], v[64:65], s[36:37] op_sel_hi:[1,0]
	v_pk_mul_f32 v[66:67], v[66:67], s[36:37] op_sel_hi:[1,0]
	v_cvt_pk_bf16_f32 v144, v68, v69
	v_cvt_pk_bf16_f32 v145, v70, v71
	v_cvt_pk_bf16_f32 v146, v64, v65
	v_cvt_pk_bf16_f32 v147, v66, v67
	s_waitcnt lgkmcnt(0)
	global_store_dwordx4 v130, v[218:221], s[6:7]
	global_store_dwordx4 v130, v[222:225], s[6:7] offset:64
	s_add_u32 s6, s6, s33
	s_addc_u32 s7, s7, 0
	ds_bpermute_b32 v226, v180, v140
	ds_bpermute_b32 v227, v180, v141
	ds_bpermute_b32 v228, v180, v142
	ds_bpermute_b32 v229, v180, v143
	ds_bpermute_b32 v230, v180, v144
	ds_bpermute_b32 v231, v180, v145
	ds_bpermute_b32 v232, v180, v146
	ds_bpermute_b32 v233, v180, v147
	s_add_u32 s8, s8, 0x800
	s_addc_u32 s9, s9, 0
	global_load_dwordx4 v[202:205], v131, s[8:9]
	global_load_dwordx4 v[206:209], v132, s[8:9]
	global_load_dwordx4 v[210:213], v131, s[8:9] offset:64
	global_load_dwordx4 v[214:217], v132, s[8:9] offset:64
	s_waitcnt vmcnt(6)
	v_pk_mul_f32 v[136:137], v[60:61], v[168:169] op_sel:[1,0] op_sel_hi:[0,0]
	v_pk_fma_f32 v[60:61], v[60:61], v[164:165], v[136:137] op_sel:[0,0,0] op_sel_hi:[1,0,1] neg_lo:[0,0,1]
	v_pk_mul_f32 v[136:137], v[62:63], v[168:169] op_sel:[1,1] op_sel_hi:[0,1]
	v_pk_fma_f32 v[62:63], v[62:63], v[164:165], v[136:137] op_sel:[0,1,0] op_sel_hi:[1,1,1] neg_lo:[0,0,1]
	v_pk_mul_f32 v[136:137], v[56:57], v[170:171] op_sel:[1,0] op_sel_hi:[0,0]
	v_pk_fma_f32 v[56:57], v[56:57], v[166:167], v[136:137] op_sel:[0,0,0] op_sel_hi:[1,0,1] neg_lo:[0,0,1]
	v_pk_mul_f32 v[136:137], v[58:59], v[170:171] op_sel:[1,1] op_sel_hi:[0,1]
	v_pk_fma_f32 v[58:59], v[58:59], v[166:167], v[136:137] op_sel:[0,1,0] op_sel_hi:[1,1,1] neg_lo:[0,0,1]
	v_pk_mul_f32 v[60:61], v[60:61], s[36:37] op_sel_hi:[1,0]
	v_pk_mul_f32 v[62:63], v[62:63], s[36:37] op_sel_hi:[1,0]
	v_pk_mul_f32 v[56:57], v[56:57], s[36:37] op_sel_hi:[1,0]
	v_pk_mul_f32 v[58:59], v[58:59], s[36:37] op_sel_hi:[1,0]
	v_cvt_pk_bf16_f32 v140, v60, v61
	v_cvt_pk_bf16_f32 v141, v62, v63
	v_cvt_pk_bf16_f32 v142, v56, v57
	v_cvt_pk_bf16_f32 v143, v58, v59
	v_pk_mul_f32 v[136:137], v[52:53], v[176:177] op_sel:[1,0] op_sel_hi:[0,0]
	v_pk_fma_f32 v[52:53], v[52:53], v[172:173], v[136:137] op_sel:[0,0,0] op_sel_hi:[1,0,1] neg_lo:[0,0,1]
	v_pk_mul_f32 v[136:137], v[54:55], v[176:177] op_sel:[1,1] op_sel_hi:[0,1]
	v_pk_fma_f32 v[54:55], v[54:55], v[172:173], v[136:137] op_sel:[0,1,0] op_sel_hi:[1,1,1] neg_lo:[0,0,1]
	v_pk_mul_f32 v[136:137], v[48:49], v[178:179] op_sel:[1,0] op_sel_hi:[0,0]
	v_pk_fma_f32 v[48:49], v[48:49], v[174:175], v[136:137] op_sel:[0,0,0] op_sel_hi:[1,0,1] neg_lo:[0,0,1]
	v_pk_mul_f32 v[136:137], v[50:51], v[178:179] op_sel:[1,1] op_sel_hi:[0,1]
	v_pk_fma_f32 v[50:51], v[50:51], v[174:175], v[136:137] op_sel:[0,1,0] op_sel_hi:[1,1,1] neg_lo:[0,0,1]
	v_pk_mul_f32 v[52:53], v[52:53], s[36:37] op_sel_hi:[1,0]
	v_pk_mul_f32 v[54:55], v[54:55], s[36:37] op_sel_hi:[1,0]
	v_pk_mul_f32 v[48:49], v[48:49], s[36:37] op_sel_hi:[1,0]
	v_pk_mul_f32 v[50:51], v[50:51], s[36:37] op_sel_hi:[1,0]
	v_cvt_pk_bf16_f32 v144, v52, v53
	v_cvt_pk_bf16_f32 v145, v54, v55
	v_cvt_pk_bf16_f32 v146, v48, v49
	v_cvt_pk_bf16_f32 v147, v50, v51
	s_waitcnt lgkmcnt(0)
	global_store_dwordx4 v130, v[226:229], s[6:7]
	global_store_dwordx4 v130, v[230:233], s[6:7] offset:64
	s_add_u32 s6, s6, s34
	s_addc_u32 s7, s7, 0
	ds_bpermute_b32 v218, v180, v140
	ds_bpermute_b32 v219, v180, v141
	ds_bpermute_b32 v220, v180, v142
	ds_bpermute_b32 v221, v180, v143
	ds_bpermute_b32 v222, v180, v144
	ds_bpermute_b32 v223, v180, v145
	ds_bpermute_b32 v224, v180, v146
	ds_bpermute_b32 v225, v180, v147
	s_add_u32 s8, s8, 0x800
	s_addc_u32 s9, s9, 0
	global_load_dwordx4 v[164:167], v131, s[8:9]
	global_load_dwordx4 v[168:171], v132, s[8:9]
	global_load_dwordx4 v[172:175], v131, s[8:9] offset:64
	global_load_dwordx4 v[176:179], v132, s[8:9] offset:64
	s_waitcnt vmcnt(6)
	v_pk_mul_f32 v[136:137], v[44:45], v[206:207] op_sel:[1,0] op_sel_hi:[0,0]
	v_pk_fma_f32 v[44:45], v[44:45], v[202:203], v[136:137] op_sel:[0,0,0] op_sel_hi:[1,0,1] neg_lo:[0,0,1]
	v_pk_mul_f32 v[136:137], v[46:47], v[206:207] op_sel:[1,1] op_sel_hi:[0,1]
	v_pk_fma_f32 v[46:47], v[46:47], v[202:203], v[136:137] op_sel:[0,1,0] op_sel_hi:[1,1,1] neg_lo:[0,0,1]
	v_pk_mul_f32 v[136:137], v[40:41], v[208:209] op_sel:[1,0] op_sel_hi:[0,0]
	v_pk_fma_f32 v[40:41], v[40:41], v[204:205], v[136:137] op_sel:[0,0,0] op_sel_hi:[1,0,1] neg_lo:[0,0,1]
	v_pk_mul_f32 v[136:137], v[42:43], v[208:209] op_sel:[1,1] op_sel_hi:[0,1]
	v_pk_fma_f32 v[42:43], v[42:43], v[204:205], v[136:137] op_sel:[0,1,0] op_sel_hi:[1,1,1] neg_lo:[0,0,1]
	v_pk_mul_f32 v[44:45], v[44:45], s[36:37] op_sel_hi:[1,0]
	v_pk_mul_f32 v[46:47], v[46:47], s[36:37] op_sel_hi:[1,0]
	v_pk_mul_f32 v[40:41], v[40:41], s[36:37] op_sel_hi:[1,0]
	v_pk_mul_f32 v[42:43], v[42:43], s[36:37] op_sel_hi:[1,0]
	v_cvt_pk_bf16_f32 v140, v44, v45
	v_cvt_pk_bf16_f32 v141, v46, v47
	v_cvt_pk_bf16_f32 v142, v40, v41
	v_cvt_pk_bf16_f32 v143, v42, v43
	v_pk_mul_f32 v[136:137], v[36:37], v[214:215] op_sel:[1,0] op_sel_hi:[0,0]
	v_pk_fma_f32 v[36:37], v[36:37], v[210:211], v[136:137] op_sel:[0,0,0] op_sel_hi:[1,0,1] neg_lo:[0,0,1]
	v_pk_mul_f32 v[136:137], v[38:39], v[214:215] op_sel:[1,1] op_sel_hi:[0,1]
	v_pk_fma_f32 v[38:39], v[38:39], v[210:211], v[136:137] op_sel:[0,1,0] op_sel_hi:[1,1,1] neg_lo:[0,0,1]
	v_pk_mul_f32 v[136:137], v[32:33], v[216:217] op_sel:[1,0] op_sel_hi:[0,0]
	v_pk_fma_f32 v[32:33], v[32:33], v[212:213], v[136:137] op_sel:[0,0,0] op_sel_hi:[1,0,1] neg_lo:[0,0,1]
	v_pk_mul_f32 v[136:137], v[34:35], v[216:217] op_sel:[1,1] op_sel_hi:[0,1]
	v_pk_fma_f32 v[34:35], v[34:35], v[212:213], v[136:137] op_sel:[0,1,0] op_sel_hi:[1,1,1] neg_lo:[0,0,1]
	v_pk_mul_f32 v[36:37], v[36:37], s[36:37] op_sel_hi:[1,0]
	v_pk_mul_f32 v[38:39], v[38:39], s[36:37] op_sel_hi:[1,0]
	v_pk_mul_f32 v[32:33], v[32:33], s[36:37] op_sel_hi:[1,0]
	v_pk_mul_f32 v[34:35], v[34:35], s[36:37] op_sel_hi:[1,0]
	v_cvt_pk_bf16_f32 v144, v36, v37
	v_cvt_pk_bf16_f32 v145, v38, v39
	v_cvt_pk_bf16_f32 v146, v32, v33
	v_cvt_pk_bf16_f32 v147, v34, v35
	s_waitcnt lgkmcnt(0)
	global_store_dwordx4 v130, v[218:221], s[6:7]
	global_store_dwordx4 v130, v[222:225], s[6:7] offset:64
	s_add_u32 s6, s6, s33
	s_addc_u32 s7, s7, 0
	ds_bpermute_b32 v226, v180, v140
	ds_bpermute_b32 v227, v180, v141
	ds_bpermute_b32 v228, v180, v142
	ds_bpermute_b32 v229, v180, v143
	ds_bpermute_b32 v230, v180, v144
	ds_bpermute_b32 v231, v180, v145
	ds_bpermute_b32 v232, v180, v146
	ds_bpermute_b32 v233, v180, v147
	s_add_u32 s8, s8, 0x800
	s_addc_u32 s9, s9, 0
	global_load_dwordx4 v[202:205], v131, s[8:9]
	global_load_dwordx4 v[206:209], v132, s[8:9]
	global_load_dwordx4 v[210:213], v131, s[8:9] offset:64
	global_load_dwordx4 v[214:217], v132, s[8:9] offset:64
	s_waitcnt vmcnt(6)
	v_pk_mul_f32 v[136:137], v[28:29], v[168:169] op_sel:[1,0] op_sel_hi:[0,0]
	v_pk_fma_f32 v[28:29], v[28:29], v[164:165], v[136:137] op_sel:[0,0,0] op_sel_hi:[1,0,1] neg_lo:[0,0,1]
	v_pk_mul_f32 v[136:137], v[30:31], v[168:169] op_sel:[1,1] op_sel_hi:[0,1]
	v_pk_fma_f32 v[30:31], v[30:31], v[164:165], v[136:137] op_sel:[0,1,0] op_sel_hi:[1,1,1] neg_lo:[0,0,1]
	v_pk_mul_f32 v[136:137], v[24:25], v[170:171] op_sel:[1,0] op_sel_hi:[0,0]
	v_pk_fma_f32 v[24:25], v[24:25], v[166:167], v[136:137] op_sel:[0,0,0] op_sel_hi:[1,0,1] neg_lo:[0,0,1]
	v_pk_mul_f32 v[136:137], v[26:27], v[170:171] op_sel:[1,1] op_sel_hi:[0,1]
	v_pk_fma_f32 v[26:27], v[26:27], v[166:167], v[136:137] op_sel:[0,1,0] op_sel_hi:[1,1,1] neg_lo:[0,0,1]
	v_pk_mul_f32 v[28:29], v[28:29], s[36:37] op_sel_hi:[1,0]
	v_pk_mul_f32 v[30:31], v[30:31], s[36:37] op_sel_hi:[1,0]
	v_pk_mul_f32 v[24:25], v[24:25], s[36:37] op_sel_hi:[1,0]
	v_pk_mul_f32 v[26:27], v[26:27], s[36:37] op_sel_hi:[1,0]
	v_cvt_pk_bf16_f32 v140, v28, v29
	v_cvt_pk_bf16_f32 v141, v30, v31
	v_cvt_pk_bf16_f32 v142, v24, v25
	v_cvt_pk_bf16_f32 v143, v26, v27
	v_pk_mul_f32 v[136:137], v[20:21], v[176:177] op_sel:[1,0] op_sel_hi:[0,0]
	v_pk_fma_f32 v[20:21], v[20:21], v[172:173], v[136:137] op_sel:[0,0,0] op_sel_hi:[1,0,1] neg_lo:[0,0,1]
	v_pk_mul_f32 v[136:137], v[22:23], v[176:177] op_sel:[1,1] op_sel_hi:[0,1]
	v_pk_fma_f32 v[22:23], v[22:23], v[172:173], v[136:137] op_sel:[0,1,0] op_sel_hi:[1,1,1] neg_lo:[0,0,1]
	v_pk_mul_f32 v[136:137], v[16:17], v[178:179] op_sel:[1,0] op_sel_hi:[0,0]
	v_pk_fma_f32 v[16:17], v[16:17], v[174:175], v[136:137] op_sel:[0,0,0] op_sel_hi:[1,0,1] neg_lo:[0,0,1]
	v_pk_mul_f32 v[136:137], v[18:19], v[178:179] op_sel:[1,1] op_sel_hi:[0,1]
	v_pk_fma_f32 v[18:19], v[18:19], v[174:175], v[136:137] op_sel:[0,1,0] op_sel_hi:[1,1,1] neg_lo:[0,0,1]
	v_pk_mul_f32 v[20:21], v[20:21], s[36:37] op_sel_hi:[1,0]
	v_pk_mul_f32 v[22:23], v[22:23], s[36:37] op_sel_hi:[1,0]
	v_pk_mul_f32 v[16:17], v[16:17], s[36:37] op_sel_hi:[1,0]
	v_pk_mul_f32 v[18:19], v[18:19], s[36:37] op_sel_hi:[1,0]
	v_cvt_pk_bf16_f32 v144, v20, v21
	v_cvt_pk_bf16_f32 v145, v22, v23
	v_cvt_pk_bf16_f32 v146, v16, v17
	v_cvt_pk_bf16_f32 v147, v18, v19
	s_waitcnt lgkmcnt(0)
	global_store_dwordx4 v130, v[226:229], s[6:7]
	global_store_dwordx4 v130, v[230:233], s[6:7] offset:64
	s_add_u32 s6, s6, s33
	s_addc_u32 s7, s7, 0
	ds_bpermute_b32 v218, v180, v140
	ds_bpermute_b32 v219, v180, v141
	ds_bpermute_b32 v220, v180, v142
	ds_bpermute_b32 v221, v180, v143
	ds_bpermute_b32 v222, v180, v144
	ds_bpermute_b32 v223, v180, v145
	ds_bpermute_b32 v224, v180, v146
	ds_bpermute_b32 v225, v180, v147
	s_waitcnt vmcnt(2)
	v_pk_mul_f32 v[136:137], v[12:13], v[206:207] op_sel:[1,0] op_sel_hi:[0,0]
	v_pk_fma_f32 v[12:13], v[12:13], v[202:203], v[136:137] op_sel:[0,0,0] op_sel_hi:[1,0,1] neg_lo:[0,0,1]
	v_pk_mul_f32 v[136:137], v[14:15], v[206:207] op_sel:[1,1] op_sel_hi:[0,1]
	v_pk_fma_f32 v[14:15], v[14:15], v[202:203], v[136:137] op_sel:[0,1,0] op_sel_hi:[1,1,1] neg_lo:[0,0,1]
	v_pk_mul_f32 v[136:137], v[4:5], v[208:209] op_sel:[1,0] op_sel_hi:[0,0]
	v_pk_fma_f32 v[4:5], v[4:5], v[204:205], v[136:137] op_sel:[0,0,0] op_sel_hi:[1,0,1] neg_lo:[0,0,1]
	v_pk_mul_f32 v[136:137], v[6:7], v[208:209] op_sel:[1,1] op_sel_hi:[0,1]
	v_pk_fma_f32 v[6:7], v[6:7], v[204:205], v[136:137] op_sel:[0,1,0] op_sel_hi:[1,1,1] neg_lo:[0,0,1]
	v_pk_mul_f32 v[12:13], v[12:13], s[36:37] op_sel_hi:[1,0]
	v_pk_mul_f32 v[14:15], v[14:15], s[36:37] op_sel_hi:[1,0]
	v_pk_mul_f32 v[4:5], v[4:5], s[36:37] op_sel_hi:[1,0]
	v_pk_mul_f32 v[6:7], v[6:7], s[36:37] op_sel_hi:[1,0]
	v_cvt_pk_bf16_f32 v140, v12, v13
	v_cvt_pk_bf16_f32 v141, v14, v15
	v_cvt_pk_bf16_f32 v142, v4, v5
	v_cvt_pk_bf16_f32 v143, v6, v7
	v_pk_mul_f32 v[136:137], v[8:9], v[214:215] op_sel:[1,0] op_sel_hi:[0,0]
	v_pk_fma_f32 v[8:9], v[8:9], v[210:211], v[136:137] op_sel:[0,0,0] op_sel_hi:[1,0,1] neg_lo:[0,0,1]
	v_pk_mul_f32 v[136:137], v[10:11], v[214:215] op_sel:[1,1] op_sel_hi:[0,1]
	v_pk_fma_f32 v[10:11], v[10:11], v[210:211], v[136:137] op_sel:[0,1,0] op_sel_hi:[1,1,1] neg_lo:[0,0,1]
	v_pk_mul_f32 v[136:137], v[0:1], v[216:217] op_sel:[1,0] op_sel_hi:[0,0]
	v_pk_fma_f32 v[0:1], v[0:1], v[212:213], v[136:137] op_sel:[0,0,0] op_sel_hi:[1,0,1] neg_lo:[0,0,1]
	v_pk_mul_f32 v[136:137], v[2:3], v[216:217] op_sel:[1,1] op_sel_hi:[0,1]
	v_pk_fma_f32 v[2:3], v[2:3], v[212:213], v[136:137] op_sel:[0,1,0] op_sel_hi:[1,1,1] neg_lo:[0,0,1]
	v_pk_mul_f32 v[8:9], v[8:9], s[36:37] op_sel_hi:[1,0]
	v_pk_mul_f32 v[10:11], v[10:11], s[36:37] op_sel_hi:[1,0]
	v_pk_mul_f32 v[0:1], v[0:1], s[36:37] op_sel_hi:[1,0]
	v_pk_mul_f32 v[2:3], v[2:3], s[36:37] op_sel_hi:[1,0]
	v_cvt_pk_bf16_f32 v144, v8, v9
	v_cvt_pk_bf16_f32 v145, v10, v11
	v_cvt_pk_bf16_f32 v146, v0, v1
	v_cvt_pk_bf16_f32 v147, v2, v3
	s_waitcnt lgkmcnt(0)
	global_store_dwordx4 v130, v[218:221], s[6:7]
	global_store_dwordx4 v130, v[222:225], s[6:7] offset:64
	s_add_u32 s6, s6, s33
	s_addc_u32 s7, s7, 0
	ds_bpermute_b32 v226, v180, v140
	ds_bpermute_b32 v227, v180, v141
	ds_bpermute_b32 v228, v180, v142
	ds_bpermute_b32 v229, v180, v143
	ds_bpermute_b32 v230, v180, v144
	ds_bpermute_b32 v231, v180, v145
	ds_bpermute_b32 v232, v180, v146
	ds_bpermute_b32 v233, v180, v147
	s_waitcnt lgkmcnt(0)
	global_store_dwordx4 v130, v[226:229], s[6:7]
	global_store_dwordx4 v130, v[230:233], s[6:7] offset:64
	s_branch .LBB0_638
.Lq3_D:
	v_pk_mul_f32 v[126:127], v[126:127], s[36:37] op_sel_hi:[1,0]
	v_pk_mul_f32 v[128:129], v[128:129], s[36:37] op_sel_hi:[1,0]
	v_pk_mul_f32 v[122:123], v[122:123], s[36:37] op_sel_hi:[1,0]
	v_pk_mul_f32 v[124:125], v[124:125], s[36:37] op_sel_hi:[1,0]
	v_cvt_pk_bf16_f32 v140, v126, v127
	v_cvt_pk_bf16_f32 v141, v128, v129
	v_cvt_pk_bf16_f32 v142, v122, v123
	v_cvt_pk_bf16_f32 v143, v124, v125
	v_pk_mul_f32 v[118:119], v[118:119], s[36:37] op_sel_hi:[1,0]
	v_pk_mul_f32 v[120:121], v[120:121], s[36:37] op_sel_hi:[1,0]
	v_pk_mul_f32 v[114:115], v[114:115], s[36:37] op_sel_hi:[1,0]
	v_pk_mul_f32 v[116:117], v[116:117], s[36:37] op_sel_hi:[1,0]
	v_cvt_pk_bf16_f32 v144, v118, v119
	v_cvt_pk_bf16_f32 v145, v120, v121
	v_cvt_pk_bf16_f32 v146, v114, v115
	v_cvt_pk_bf16_f32 v147, v116, v117
	ds_bpermute_b32 v218, v180, v140
	ds_bpermute_b32 v219, v180, v141
	ds_bpermute_b32 v220, v180, v142
	ds_bpermute_b32 v221, v180, v143
	ds_bpermute_b32 v222, v180, v144
	ds_bpermute_b32 v223, v180, v145
	ds_bpermute_b32 v224, v180, v146
	ds_bpermute_b32 v225, v180, v147
	v_pk_mul_f32 v[108:109], v[108:109], s[36:37] op_sel_hi:[1,0]
	v_pk_mul_f32 v[110:111], v[110:111], s[36:37] op_sel_hi:[1,0]
	v_pk_mul_f32 v[104:105], v[104:105], s[36:37] op_sel_hi:[1,0]
	v_pk_mul_f32 v[106:107], v[106:107], s[36:37] op_sel_hi:[1,0]
	v_cvt_pk_bf16_f32 v140, v108, v109
	v_cvt_pk_bf16_f32 v141, v110, v111
	v_cvt_pk_bf16_f32 v142, v104, v105
	v_cvt_pk_bf16_f32 v143, v106, v107
	v_pk_mul_f32 v[100:101], v[100:101], s[36:37] op_sel_hi:[1,0]
	v_pk_mul_f32 v[102:103], v[102:103], s[36:37] op_sel_hi:[1,0]
	v_pk_mul_f32 v[96:97], v[96:97], s[36:37] op_sel_hi:[1,0]
	v_pk_mul_f32 v[98:99], v[98:99], s[36:37] op_sel_hi:[1,0]
	v_cvt_pk_bf16_f32 v144, v100, v101
	v_cvt_pk_bf16_f32 v145, v102, v103
	v_cvt_pk_bf16_f32 v146, v96, v97
	v_cvt_pk_bf16_f32 v147, v98, v99
	s_waitcnt lgkmcnt(0)
	global_store_dwordx4 v130, v[218:221], s[6:7]
	global_store_dwordx4 v130, v[222:225], s[6:7] offset:64
	s_add_u32 s6, s6, s33
	s_addc_u32 s7, s7, 0
	ds_bpermute_b32 v226, v180, v140
	ds_bpermute_b32 v227, v180, v141
	ds_bpermute_b32 v228, v180, v142
	ds_bpermute_b32 v229, v180, v143
	ds_bpermute_b32 v230, v180, v144
	ds_bpermute_b32 v231, v180, v145
	ds_bpermute_b32 v232, v180, v146
	ds_bpermute_b32 v233, v180, v147
	v_pk_mul_f32 v[92:93], v[92:93], s[36:37] op_sel_hi:[1,0]
	v_pk_mul_f32 v[94:95], v[94:95], s[36:37] op_sel_hi:[1,0]
	v_pk_mul_f32 v[88:89], v[88:89], s[36:37] op_sel_hi:[1,0]
	v_pk_mul_f32 v[90:91], v[90:91], s[36:37] op_sel_hi:[1,0]
	v_cvt_pk_bf16_f32 v140, v92, v93
	v_cvt_pk_bf16_f32 v141, v94, v95
	v_cvt_pk_bf16_f32 v142, v88, v89
	v_cvt_pk_bf16_f32 v143, v90, v91
	v_pk_mul_f32 v[84:85], v[84:85], s[36:37] op_sel_hi:[1,0]
	v_pk_mul_f32 v[86:87], v[86:87], s[36:37] op_sel_hi:[1,0]
	v_pk_mul_f32 v[80:81], v[80:81], s[36:37] op_sel_hi:[1,0]
	v_pk_mul_f32 v[82:83], v[82:83], s[36:37] op_sel_hi:[1,0]
	v_cvt_pk_bf16_f32 v144, v84, v85
	v_cvt_pk_bf16_f32 v145, v86, v87
	v_cvt_pk_bf16_f32 v146, v80, v81
	v_cvt_pk_bf16_f32 v147, v82, v83
	s_waitcnt lgkmcnt(0)
	global_store_dwordx4 v130, v[226:229], s[6:7]
	global_store_dwordx4 v130, v[230:233], s[6:7] offset:64
	s_add_u32 s6, s6, s33
	s_addc_u32 s7, s7, 0
	ds_bpermute_b32 v218, v180, v140
	ds_bpermute_b32 v219, v180, v141
	ds_bpermute_b32 v220, v180, v142
	ds_bpermute_b32 v221, v180, v143
	ds_bpermute_b32 v222, v180, v144
	ds_bpermute_b32 v223, v180, v145
	ds_bpermute_b32 v224, v180, v146
	ds_bpermute_b32 v225, v180, v147
	v_pk_mul_f32 v[76:77], v[76:77], s[36:37] op_sel_hi:[1,0]
	v_pk_mul_f32 v[78:79], v[78:79], s[36:37] op_sel_hi:[1,0]
	v_pk_mul_f32 v[72:73], v[72:73], s[36:37] op_sel_hi:[1,0]
	v_pk_mul_f32 v[74:75], v[74:75], s[36:37] op_sel_hi:[1,0]
	v_cvt_pk_bf16_f32 v140, v76, v77
	v_cvt_pk_bf16_f32 v141, v78, v79
	v_cvt_pk_bf16_f32 v142, v72, v73
	v_cvt_pk_bf16_f32 v143, v74, v75
	v_pk_mul_f32 v[68:69], v[68:69], s[36:37] op_sel_hi:[1,0]
	v_pk_mul_f32 v[70:71], v[70:71], s[36:37] op_sel_hi:[1,0]
	v_pk_mul_f32 v[64:65], v[64:65], s[36:37] op_sel_hi:[1,0]
	v_pk_mul_f32 v[66:67], v[66:67], s[36:37] op_sel_hi:[1,0]
	v_cvt_pk_bf16_f32 v144, v68, v69
	v_cvt_pk_bf16_f32 v145, v70, v71
	v_cvt_pk_bf16_f32 v146, v64, v65
	v_cvt_pk_bf16_f32 v147, v66, v67
	s_waitcnt lgkmcnt(0)
	global_store_dwordx4 v130, v[218:221], s[6:7]
	global_store_dwordx4 v130, v[222:225], s[6:7] offset:64
	s_add_u32 s6, s6, s33
	s_addc_u32 s7, s7, 0
	ds_bpermute_b32 v226, v180, v140
	ds_bpermute_b32 v227, v180, v141
	ds_bpermute_b32 v228, v180, v142
	ds_bpermute_b32 v229, v180, v143
	ds_bpermute_b32 v230, v180, v144
	ds_bpermute_b32 v231, v180, v145
	ds_bpermute_b32 v232, v180, v146
	ds_bpermute_b32 v233, v180, v147
	v_pk_mul_f32 v[60:61], v[60:61], s[36:37] op_sel_hi:[1,0]
	v_pk_mul_f32 v[62:63], v[62:63], s[36:37] op_sel_hi:[1,0]
	v_pk_mul_f32 v[56:57], v[56:57], s[36:37] op_sel_hi:[1,0]
	v_pk_mul_f32 v[58:59], v[58:59], s[36:37] op_sel_hi:[1,0]
	v_cvt_pk_bf16_f32 v140, v60, v61
	v_cvt_pk_bf16_f32 v141, v62, v63
	v_cvt_pk_bf16_f32 v142, v56, v57
	v_cvt_pk_bf16_f32 v143, v58, v59
	v_pk_mul_f32 v[52:53], v[52:53], s[36:37] op_sel_hi:[1,0]
	v_pk_mul_f32 v[54:55], v[54:55], s[36:37] op_sel_hi:[1,0]
	v_pk_mul_f32 v[48:49], v[48:49], s[36:37] op_sel_hi:[1,0]
	v_pk_mul_f32 v[50:51], v[50:51], s[36:37] op_sel_hi:[1,0]
	v_cvt_pk_bf16_f32 v144, v52, v53
	v_cvt_pk_bf16_f32 v145, v54, v55
	v_cvt_pk_bf16_f32 v146, v48, v49
	v_cvt_pk_bf16_f32 v147, v50, v51
	s_waitcnt lgkmcnt(0)
	global_store_dwordx4 v130, v[226:229], s[6:7]
	global_store_dwordx4 v130, v[230:233], s[6:7] offset:64
	s_add_u32 s6, s6, s34
	s_addc_u32 s7, s7, 0
	ds_bpermute_b32 v218, v180, v140
	ds_bpermute_b32 v219, v180, v141
	ds_bpermute_b32 v220, v180, v142
	ds_bpermute_b32 v221, v180, v143
	ds_bpermute_b32 v222, v180, v144
	ds_bpermute_b32 v223, v180, v145
	ds_bpermute_b32 v224, v180, v146
	ds_bpermute_b32 v225, v180, v147
	v_pk_mul_f32 v[44:45], v[44:45], s[36:37] op_sel_hi:[1,0]
	v_pk_mul_f32 v[46:47], v[46:47], s[36:37] op_sel_hi:[1,0]
	v_pk_mul_f32 v[40:41], v[40:41], s[36:37] op_sel_hi:[1,0]
	v_pk_mul_f32 v[42:43], v[42:43], s[36:37] op_sel_hi:[1,0]
	v_cvt_pk_bf16_f32 v140, v44, v45
	v_cvt_pk_bf16_f32 v141, v46, v47
	v_cvt_pk_bf16_f32 v142, v40, v41
	v_cvt_pk_bf16_f32 v143, v42, v43
	v_pk_mul_f32 v[36:37], v[36:37], s[36:37] op_sel_hi:[1,0]
	v_pk_mul_f32 v[38:39], v[38:39], s[36:37] op_sel_hi:[1,0]
	v_pk_mul_f32 v[32:33], v[32:33], s[36:37] op_sel_hi:[1,0]
	v_pk_mul_f32 v[34:35], v[34:35], s[36:37] op_sel_hi:[1,0]
	v_cvt_pk_bf16_f32 v144, v36, v37
	v_cvt_pk_bf16_f32 v145, v38, v39
	v_cvt_pk_bf16_f32 v146, v32, v33
	v_cvt_pk_bf16_f32 v147, v34, v35
	s_waitcnt lgkmcnt(0)
	global_store_dwordx4 v130, v[218:221], s[6:7]
	global_store_dwordx4 v130, v[222:225], s[6:7] offset:64
	s_add_u32 s6, s6, s33
	s_addc_u32 s7, s7, 0
	ds_bpermute_b32 v226, v180, v140
	ds_bpermute_b32 v227, v180, v141
	ds_bpermute_b32 v228, v180, v142
	ds_bpermute_b32 v229, v180, v143
	ds_bpermute_b32 v230, v180, v144
	ds_bpermute_b32 v231, v180, v145
	ds_bpermute_b32 v232, v180, v146
	ds_bpermute_b32 v233, v180, v147
	v_pk_mul_f32 v[28:29], v[28:29], s[36:37] op_sel_hi:[1,0]
	v_pk_mul_f32 v[30:31], v[30:31], s[36:37] op_sel_hi:[1,0]
	v_pk_mul_f32 v[24:25], v[24:25], s[36:37] op_sel_hi:[1,0]
	v_pk_mul_f32 v[26:27], v[26:27], s[36:37] op_sel_hi:[1,0]
	v_cvt_pk_bf16_f32 v140, v28, v29
	v_cvt_pk_bf16_f32 v141, v30, v31
	v_cvt_pk_bf16_f32 v142, v24, v25
	v_cvt_pk_bf16_f32 v143, v26, v27
	v_pk_mul_f32 v[20:21], v[20:21], s[36:37] op_sel_hi:[1,0]
	v_pk_mul_f32 v[22:23], v[22:23], s[36:37] op_sel_hi:[1,0]
	v_pk_mul_f32 v[16:17], v[16:17], s[36:37] op_sel_hi:[1,0]
	v_pk_mul_f32 v[18:19], v[18:19], s[36:37] op_sel_hi:[1,0]
	v_cvt_pk_bf16_f32 v144, v20, v21
	v_cvt_pk_bf16_f32 v145, v22, v23
	v_cvt_pk_bf16_f32 v146, v16, v17
	v_cvt_pk_bf16_f32 v147, v18, v19
	s_waitcnt lgkmcnt(0)
	global_store_dwordx4 v130, v[226:229], s[6:7]
	global_store_dwordx4 v130, v[230:233], s[6:7] offset:64
	s_add_u32 s6, s6, s33
	s_addc_u32 s7, s7, 0
	ds_bpermute_b32 v218, v180, v140
	ds_bpermute_b32 v219, v180, v141
	ds_bpermute_b32 v220, v180, v142
	ds_bpermute_b32 v221, v180, v143
	ds_bpermute_b32 v222, v180, v144
	ds_bpermute_b32 v223, v180, v145
	ds_bpermute_b32 v224, v180, v146
	ds_bpermute_b32 v225, v180, v147
	v_pk_mul_f32 v[12:13], v[12:13], s[36:37] op_sel_hi:[1,0]
	v_pk_mul_f32 v[14:15], v[14:15], s[36:37] op_sel_hi:[1,0]
	v_pk_mul_f32 v[4:5], v[4:5], s[36:37] op_sel_hi:[1,0]
	v_pk_mul_f32 v[6:7], v[6:7], s[36:37] op_sel_hi:[1,0]
	v_cvt_pk_bf16_f32 v140, v12, v13
	v_cvt_pk_bf16_f32 v141, v14, v15
	v_cvt_pk_bf16_f32 v142, v4, v5
	v_cvt_pk_bf16_f32 v143, v6, v7
	v_pk_mul_f32 v[8:9], v[8:9], s[36:37] op_sel_hi:[1,0]
	v_pk_mul_f32 v[10:11], v[10:11], s[36:37] op_sel_hi:[1,0]
	v_pk_mul_f32 v[0:1], v[0:1], s[36:37] op_sel_hi:[1,0]
	v_pk_mul_f32 v[2:3], v[2:3], s[36:37] op_sel_hi:[1,0]
	v_cvt_pk_bf16_f32 v144, v8, v9
	v_cvt_pk_bf16_f32 v145, v10, v11
	v_cvt_pk_bf16_f32 v146, v0, v1
	v_cvt_pk_bf16_f32 v147, v2, v3
	s_waitcnt lgkmcnt(0)
	global_store_dwordx4 v130, v[218:221], s[6:7]
	global_store_dwordx4 v130, v[222:225], s[6:7] offset:64
	s_add_u32 s6, s6, s33
	s_addc_u32 s7, s7, 0
	ds_bpermute_b32 v226, v180, v140
	ds_bpermute_b32 v227, v180, v141
	ds_bpermute_b32 v228, v180, v142
	ds_bpermute_b32 v229, v180, v143
	ds_bpermute_b32 v230, v180, v144
	ds_bpermute_b32 v231, v180, v145
	ds_bpermute_b32 v232, v180, v146
	ds_bpermute_b32 v233, v180, v147
	s_waitcnt lgkmcnt(0)
	global_store_dwordx4 v130, v[226:229], s[6:7]
	global_store_dwordx4 v130, v[230:233], s[6:7] offset:64
	s_branch .LBB0_638

.LBB0_1076:
	s_or_b64 exec, exec, s[16:17]
	s_add_u32 s6, s10, 0xe600000
	s_addc_u32 s7, s11, 0
	s_lshl_b32 s2, s41, 8
	s_add_i32 s2, s2, 0
	v_lshl_add_u32 v32, v232, 2, s2
	s_waitcnt lgkmcnt(0)
	s_barrier
	v_add_u32_e32 v32, 0x1000, v32
	ds_read2_b32 v[62:63], v32 offset1:16
	ds_read2_b32 v[58:59], v32 offset0:32 offset1:48
	ds_read2_b32 v[52:53], v32 offset0:128 offset1:144
	ds_read2_b32 v[44:45], v32 offset0:160 offset1:176
	v_lshlrev_b64 v[126:127], 10, v[224:225]
	s_waitcnt lgkmcnt(3)
	v_mov_b32_e32 v60, v63
	v_mov_b32_e32 v63, v62
	v_pk_mul_f32 v[32:33], v[188:189], v[62:63] op_sel_hi:[1,0]
	v_pk_mul_f32 v[186:187], v[186:187], v[62:63] op_sel_hi:[1,0]
	s_waitcnt lgkmcnt(2)
	v_mov_b32_e32 v56, v59
	s_waitcnt lgkmcnt(1)
	v_mov_b32_e32 v48, v53
	s_waitcnt lgkmcnt(0)
	v_mov_b32_e32 v40, v45
	v_lshl_add_u64 v[128:129], v[126:127], 0, v[54:55]
	v_pk_mul_f32 v[34:35], v[22:23], v[32:33]
	v_pk_mul_f32 v[32:33], v[20:21], v[186:187]
	s_mov_b64 s[2:3], -1
	s_and_b64 vcc, exec, s[24:25]
	v_pk_mul_f32 v[170:171], v[170:171], v[62:63]
	s_cbranch_vccz .LBB0_1078
	v_mov_b32_e32 v190, v62
	v_mov_b32_e32 v191, v62
	v_pk_mul_f32 v[190:191], v[172:173], v[190:191]
	v_pk_add_f32 v[188:189], v[30:31], v[34:35]
	v_pk_add_f32 v[186:187], v[28:29], v[32:33]
	v_pk_fma_f32 v[190:191], v[26:27], v[190:191], v[18:19]
	v_pk_fma_f32 v[192:193], v[24:25], v[170:171], v[16:17]
	v_cvt_pk_bf16_f32 v186, v186, v187
	v_cvt_pk_bf16_f32 v187, v188, v189
	v_cvt_pk_bf16_f32 v188, v192, v193
	v_cvt_pk_bf16_f32 v189, v190, v191
	v_lshl_add_u64 v[190:191], v[128:129], 1, s[6:7]
	global_store_dwordx4 v[190:191], v[186:189], off sc1
	s_nop 1
	s_mov_b64 s[2:3], 0
.LBB0_1078:
	s_andn2_b64 vcc, exec, s[2:3]
	s_cbranch_vccnz .LBB0_1080
	v_lshl_add_u64 v[128:129], v[128:129], 2, s[12:13]
	global_store_dwordx4 v[128:129], v[32:35], off
	s_nop 1
	v_mov_b32_e32 v32, v62
	v_mov_b32_e32 v33, v62
	v_pk_mul_f32 v[32:33], v[172:173], v[32:33]
	v_pk_mul_f32 v[34:35], v[26:27], v[32:33]
	v_pk_mul_f32 v[32:33], v[24:25], v[170:171]
	global_store_dwordx4 v[128:129], v[32:35], off offset:16
.LBB0_1080:
	v_mov_b32_e32 v61, v60
	v_lshlrev_b64 v[128:129], 10, v[222:223]
	v_pk_mul_f32 v[32:33], v[184:185], v[60:61] op_sel_hi:[1,0]
	v_pk_mul_f32 v[172:173], v[182:183], v[60:61] op_sel_hi:[1,0]
	v_lshl_add_u64 v[170:171], v[128:129], 0, v[54:55]
	v_pk_mul_f32 v[34:35], v[22:23], v[32:33]
	v_pk_mul_f32 v[32:33], v[20:21], v[172:173]
	s_mov_b64 s[2:3], -1
	s_and_b64 vcc, exec, s[4:5]
	v_pk_mul_f32 v[166:167], v[166:167], v[60:61]
	s_cbranch_vccnz .LBB0_1082
	v_mov_b32_e32 v184, v60
	v_mov_b32_e32 v185, v60
	v_pk_mul_f32 v[184:185], v[168:169], v[184:185]
	v_pk_add_f32 v[172:173], v[30:31], v[34:35]
	v_pk_add_f32 v[182:183], v[28:29], v[32:33]
	v_pk_fma_f32 v[186:187], v[26:27], v[184:185], v[18:19]
	v_pk_fma_f32 v[184:185], v[24:25], v[166:167], v[16:17]
	v_cvt_pk_bf16_f32 v182, v182, v183
	v_cvt_pk_bf16_f32 v183, v172, v173
	v_cvt_pk_bf16_f32 v184, v184, v185
	v_cvt_pk_bf16_f32 v185, v186, v187
	v_lshl_add_u64 v[172:173], v[170:171], 1, s[6:7]
	global_store_dwordx4 v[172:173], v[182:185], off sc1
	s_nop 1
	s_mov_b64 s[2:3], 0
.LBB0_1082:
	s_andn2_b64 vcc, exec, s[2:3]
	s_cbranch_vccnz .LBB0_1084
	v_lshl_add_u64 v[170:171], v[170:171], 2, s[12:13]
	global_store_dwordx4 v[170:171], v[32:35], off
	s_nop 1
	v_mov_b32_e32 v32, v60
	v_mov_b32_e32 v33, v60
	v_pk_mul_f32 v[32:33], v[168:169], v[32:33]
	v_pk_mul_f32 v[34:35], v[26:27], v[32:33]
	v_pk_mul_f32 v[32:33], v[24:25], v[166:167]
	global_store_dwordx4 v[170:171], v[32:35], off offset:16
.LBB0_1084:
	v_mov_b32_e32 v59, v58
	v_lshlrev_b64 v[166:167], 10, v[220:221]
	v_pk_mul_f32 v[32:33], v[180:181], v[58:59] op_sel_hi:[1,0]
	v_pk_mul_f32 v[170:171], v[178:179], v[58:59] op_sel_hi:[1,0]
	v_lshl_add_u64 v[168:169], v[166:167], 0, v[54:55]
	v_pk_mul_f32 v[34:35], v[22:23], v[32:33]
	v_pk_mul_f32 v[32:33], v[20:21], v[170:171]
	s_mov_b64 s[2:3], -1
	s_and_b64 vcc, exec, s[4:5]
	v_pk_mul_f32 v[158:159], v[158:159], v[58:59]
	s_cbranch_vccnz .LBB0_1086
	v_mov_b32_e32 v178, v58
	v_mov_b32_e32 v179, v58
	v_pk_mul_f32 v[178:179], v[160:161], v[178:179]
	v_pk_add_f32 v[172:173], v[30:31], v[34:35]
	v_pk_add_f32 v[170:171], v[28:29], v[32:33]
	v_pk_fma_f32 v[178:179], v[26:27], v[178:179], v[18:19]
	v_pk_fma_f32 v[180:181], v[24:25], v[158:159], v[16:17]
	v_cvt_pk_bf16_f32 v170, v170, v171
	v_cvt_pk_bf16_f32 v171, v172, v173
	v_cvt_pk_bf16_f32 v172, v180, v181
	v_cvt_pk_bf16_f32 v173, v178, v179
	v_lshl_add_u64 v[178:179], v[168:169], 1, s[6:7]
	global_store_dwordx4 v[178:179], v[170:173], off sc1
	s_nop 1
	s_mov_b64 s[2:3], 0
.LBB0_1086:
	s_andn2_b64 vcc, exec, s[2:3]
	s_cbranch_vccnz .LBB0_1088
	v_lshl_add_u64 v[168:169], v[168:169], 2, s[12:13]
	global_store_dwordx4 v[168:169], v[32:35], off
	s_nop 1
	v_mov_b32_e32 v32, v58
	v_mov_b32_e32 v33, v58
	v_pk_mul_f32 v[32:33], v[160:161], v[32:33]
	v_pk_mul_f32 v[34:35], v[26:27], v[32:33]
	v_pk_mul_f32 v[32:33], v[24:25], v[158:159]
	global_store_dwordx4 v[168:169], v[32:35], off offset:16
.LBB0_1088:
	v_mov_b32_e32 v57, v56
	v_lshlrev_b64 v[158:159], 10, v[218:219]
	v_pk_mul_f32 v[32:33], v[176:177], v[56:57] op_sel_hi:[1,0]
	v_pk_mul_f32 v[168:169], v[174:175], v[56:57] op_sel_hi:[1,0]
	v_lshl_add_u64 v[160:161], v[158:159], 0, v[54:55]
	v_pk_mul_f32 v[34:35], v[22:23], v[32:33]
	v_pk_mul_f32 v[32:33], v[20:21], v[168:169]
	s_mov_b64 s[2:3], -1
	s_and_b64 vcc, exec, s[4:5]
	v_pk_mul_f32 v[162:163], v[162:163], v[56:57]
	s_cbranch_vccnz .LBB0_1090
	v_mov_b32_e32 v172, v56
	v_mov_b32_e32 v173, v56
	v_pk_mul_f32 v[172:173], v[164:165], v[172:173]
	v_pk_add_f32 v[170:171], v[30:31], v[34:35]
	v_pk_add_f32 v[168:169], v[28:29], v[32:33]
	v_pk_fma_f32 v[172:173], v[26:27], v[172:173], v[18:19]
	v_pk_fma_f32 v[174:175], v[24:25], v[162:163], v[16:17]
	v_cvt_pk_bf16_f32 v168, v168, v169
	v_cvt_pk_bf16_f32 v169, v170, v171
	v_cvt_pk_bf16_f32 v170, v174, v175
	v_cvt_pk_bf16_f32 v171, v172, v173
	v_lshl_add_u64 v[172:173], v[160:161], 1, s[6:7]
	global_store_dwordx4 v[172:173], v[168:171], off sc1
	s_nop 1
	s_mov_b64 s[2:3], 0
.LBB0_1090:
	s_andn2_b64 vcc, exec, s[2:3]
	s_cbranch_vccnz .LBB0_1092
	v_lshl_add_u64 v[160:161], v[160:161], 2, s[12:13]
	global_store_dwordx4 v[160:161], v[32:35], off
	s_nop 1
	v_mov_b32_e32 v32, v56
	v_mov_b32_e32 v33, v56
	v_pk_mul_f32 v[32:33], v[164:165], v[32:33]
	v_pk_mul_f32 v[34:35], v[26:27], v[32:33]
	v_pk_mul_f32 v[32:33], v[24:25], v[162:163]
	global_store_dwordx4 v[160:161], v[32:35], off offset:16
.LBB0_1092:
	v_mov_b32_e32 v53, v52
	v_lshlrev_b64 v[160:161], 10, v[228:229]
	v_pk_mul_f32 v[32:33], v[124:125], v[52:53] op_sel_hi:[1,0]
	v_pk_mul_f32 v[122:123], v[122:123], v[52:53] op_sel_hi:[1,0]
	v_lshl_add_u64 v[162:163], v[160:161], 0, v[54:55]
	v_pk_mul_f32 v[34:35], v[22:23], v[32:33]
	v_pk_mul_f32 v[32:33], v[20:21], v[122:123]
	s_mov_b64 s[2:3], -1
	s_and_b64 vcc, exec, s[4:5]
	v_pk_mul_f32 v[104:105], v[104:105], v[52:53]
	s_cbranch_vccnz .LBB0_1094
	v_mov_b32_e32 v164, v52
	v_mov_b32_e32 v165, v52
	v_pk_mul_f32 v[164:165], v[106:107], v[164:165]
	v_pk_add_f32 v[124:125], v[30:31], v[34:35]
	v_pk_add_f32 v[122:123], v[28:29], v[32:33]
	v_pk_fma_f32 v[164:165], v[26:27], v[164:165], v[18:19]
	v_pk_fma_f32 v[168:169], v[24:25], v[104:105], v[16:17]
	v_cvt_pk_bf16_f32 v122, v122, v123
	v_cvt_pk_bf16_f32 v123, v124, v125
	v_cvt_pk_bf16_f32 v124, v168, v169
	v_cvt_pk_bf16_f32 v125, v164, v165
	v_lshl_add_u64 v[164:165], v[162:163], 1, s[6:7]
	global_store_dwordx4 v[164:165], v[122:125], off sc1
	s_nop 1
	s_mov_b64 s[2:3], 0
.LBB0_1094:
	s_andn2_b64 vcc, exec, s[2:3]
	s_cbranch_vccnz .LBB0_1096
	v_lshl_add_u64 v[122:123], v[162:163], 2, s[12:13]
	global_store_dwordx4 v[122:123], v[32:35], off
	s_nop 1
	v_mov_b32_e32 v32, v52
	v_mov_b32_e32 v33, v52
	v_pk_mul_f32 v[32:33], v[106:107], v[32:33]
	v_pk_mul_f32 v[34:35], v[26:27], v[32:33]
	v_pk_mul_f32 v[32:33], v[24:25], v[104:105]
	global_store_dwordx4 v[122:123], v[32:35], off offset:16
.LBB0_1096:
	v_mov_b32_e32 v49, v48
	v_lshlrev_b64 v[50:51], 10, v[50:51]
	v_pk_mul_f32 v[32:33], v[120:121], v[48:49] op_sel_hi:[1,0]
	v_pk_mul_f32 v[106:107], v[118:119], v[48:49] op_sel_hi:[1,0]
	v_lshl_add_u64 v[104:105], v[50:51], 0, v[54:55]
	v_pk_mul_f32 v[34:35], v[22:23], v[32:33]
	v_pk_mul_f32 v[32:33], v[20:21], v[106:107]
	s_mov_b64 s[2:3], -1
	s_and_b64 vcc, exec, s[4:5]
	v_pk_mul_f32 v[96:97], v[96:97], v[48:49]
	s_cbranch_vccnz .LBB0_1098
	v_mov_b32_e32 v120, v48
	v_mov_b32_e32 v121, v48
	v_pk_mul_f32 v[120:121], v[98:99], v[120:121]
	v_pk_add_f32 v[106:107], v[30:31], v[34:35]
	v_pk_add_f32 v[118:119], v[28:29], v[32:33]
	v_pk_fma_f32 v[122:123], v[26:27], v[120:121], v[18:19]
	v_pk_fma_f32 v[120:121], v[24:25], v[96:97], v[16:17]
	v_cvt_pk_bf16_f32 v118, v118, v119
	v_cvt_pk_bf16_f32 v119, v106, v107
	v_cvt_pk_bf16_f32 v120, v120, v121
	v_cvt_pk_bf16_f32 v121, v122, v123
	v_lshl_add_u64 v[106:107], v[104:105], 1, s[6:7]
	global_store_dwordx4 v[106:107], v[118:121], off sc1
	s_nop 1
	s_mov_b64 s[2:3], 0
.LBB0_1098:
	s_andn2_b64 vcc, exec, s[2:3]
	s_cbranch_vccnz .LBB0_1100
	v_lshl_add_u64 v[104:105], v[104:105], 2, s[12:13]
	global_store_dwordx4 v[104:105], v[32:35], off
	s_nop 1
	v_mov_b32_e32 v32, v48
	v_mov_b32_e32 v33, v48
	v_pk_mul_f32 v[32:33], v[98:99], v[32:33]
	v_pk_mul_f32 v[34:35], v[26:27], v[32:33]
	v_pk_mul_f32 v[32:33], v[24:25], v[96:97]
	global_store_dwordx4 v[104:105], v[32:35], off offset:16
.LBB0_1100:
	v_mov_b32_e32 v45, v44
	v_lshlrev_b64 v[46:47], 10, v[46:47]
	v_pk_mul_f32 v[32:33], v[110:111], v[44:45] op_sel_hi:[1,0]
	v_pk_mul_f32 v[98:99], v[108:109], v[44:45] op_sel_hi:[1,0]
	v_lshl_add_u64 v[96:97], v[46:47], 0, v[54:55]
	v_pk_mul_f32 v[34:35], v[22:23], v[32:33]
	v_pk_mul_f32 v[32:33], v[20:21], v[98:99]
	s_mov_b64 s[2:3], -1
	s_and_b64 vcc, exec, s[4:5]
	v_pk_mul_f32 v[92:93], v[92:93], v[44:45]
	s_cbranch_vccnz .LBB0_1102
	v_mov_b32_e32 v106, v44
	v_mov_b32_e32 v107, v44
	v_pk_mul_f32 v[106:107], v[94:95], v[106:107]
	v_pk_add_f32 v[98:99], v[30:31], v[34:35]
	v_pk_add_f32 v[104:105], v[28:29], v[32:33]
	v_pk_fma_f32 v[108:109], v[26:27], v[106:107], v[18:19]
	v_pk_fma_f32 v[106:107], v[24:25], v[92:93], v[16:17]
	v_cvt_pk_bf16_f32 v104, v104, v105
	v_cvt_pk_bf16_f32 v105, v98, v99
	v_cvt_pk_bf16_f32 v106, v106, v107
	v_cvt_pk_bf16_f32 v107, v108, v109
	v_lshl_add_u64 v[98:99], v[96:97], 1, s[6:7]
	global_store_dwordx4 v[98:99], v[104:107], off sc1
	s_nop 1
	s_mov_b64 s[2:3], 0
.LBB0_1102:
	s_andn2_b64 vcc, exec, s[2:3]
	s_cbranch_vccnz .LBB0_1104
	v_lshl_add_u64 v[96:97], v[96:97], 2, s[12:13]
	global_store_dwordx4 v[96:97], v[32:35], off
	s_nop 1
	v_mov_b32_e32 v32, v44
	v_mov_b32_e32 v33, v44
	v_pk_mul_f32 v[32:33], v[94:95], v[32:33]
	v_pk_mul_f32 v[34:35], v[26:27], v[32:33]
	v_pk_mul_f32 v[32:33], v[24:25], v[92:93]
	global_store_dwordx4 v[96:97], v[32:35], off offset:16
.LBB0_1104:
	v_mov_b32_e32 v41, v40
	s_nop 0
	v_lshlrev_b64 v[32:33], 10, v[42:43]
	v_pk_mul_f32 v[42:43], v[116:117], v[40:41] op_sel_hi:[1,0]
	v_pk_mul_f32 v[92:93], v[114:115], v[40:41] op_sel_hi:[1,0]
	v_lshl_add_u64 v[34:35], v[32:33], 0, v[54:55]
	v_pk_mul_f32 v[22:23], v[22:23], v[42:43]
	v_pk_mul_f32 v[20:21], v[20:21], v[92:93]
	s_mov_b64 s[2:3], -1
	s_and_b64 vcc, exec, s[4:5]
	v_pk_mul_f32 v[42:43], v[100:101], v[40:41]
	s_cbranch_vccnz .LBB0_1106
	v_mov_b32_e32 v92, v40
	v_mov_b32_e32 v93, v40
	v_pk_mul_f32 v[92:93], v[102:103], v[92:93]
	v_pk_add_f32 v[30:31], v[30:31], v[22:23]
	v_pk_add_f32 v[28:29], v[28:29], v[20:21]
	v_pk_fma_f32 v[92:93], v[26:27], v[92:93], v[18:19]
	v_pk_fma_f32 v[18:19], v[24:25], v[42:43], v[16:17]
	v_cvt_pk_bf16_f32 v16, v28, v29
	v_cvt_pk_bf16_f32 v17, v30, v31
	v_cvt_pk_bf16_f32 v18, v18, v19
	v_cvt_pk_bf16_f32 v19, v92, v93
	v_lshl_add_u64 v[28:29], v[34:35], 1, s[6:7]
	global_store_dwordx4 v[28:29], v[16:19], off sc1
	s_nop 1
	s_mov_b64 s[2:3], 0
.LBB0_1106:
	s_andn2_b64 vcc, exec, s[2:3]
	s_cbranch_vccnz .LBB0_1108
	v_mov_b32_e32 v16, v40
	v_mov_b32_e32 v17, v40
	v_pk_mul_f32 v[16:17], v[102:103], v[16:17]
	v_lshl_add_u64 v[28:29], v[34:35], 2, s[12:13]
	v_pk_mul_f32 v[18:19], v[26:27], v[16:17]
	v_pk_mul_f32 v[16:17], v[24:25], v[42:43]
	global_store_dwordx4 v[28:29], v[20:23], off
	global_store_dwordx4 v[28:29], v[16:19], off offset:16
.LBB0_1108:
	s_nop 0
	v_add_u32_e32 v20, 0x80, v54
	v_mov_b32_e32 v26, v62
	v_mov_b32_e32 v27, v62
	v_ashrrev_i32_e32 v21, 31, v20
	v_pk_mul_f32 v[16:17], v[152:153], v[26:27]
	v_pk_mul_f32 v[24:25], v[150:151], v[62:63]
	v_lshl_add_u64 v[22:23], v[126:127], 0, v[20:21]
	v_pk_mul_f32 v[18:19], v[14:15], v[16:17]
	v_pk_mul_f32 v[16:17], v[12:13], v[24:25]
	s_mov_b64 s[2:3], -1
	s_and_b64 vcc, exec, s[4:5]
	v_pk_mul_f32 v[24:25], v[138:139], v[62:63]
	s_cbranch_vccnz .LBB0_1110
	v_pk_mul_f32 v[26:27], v[140:141], v[26:27]
	v_pk_add_f32 v[28:29], v[10:11], v[18:19]
	v_pk_add_f32 v[30:31], v[8:9], v[16:17]
	v_pk_fma_f32 v[34:35], v[6:7], v[26:27], v[2:3]
	v_pk_fma_f32 v[42:43], v[4:5], v[24:25], v[0:1]
	v_cvt_pk_bf16_f32 v26, v30, v31
	v_cvt_pk_bf16_f32 v27, v28, v29
	v_cvt_pk_bf16_f32 v28, v42, v43
	v_cvt_pk_bf16_f32 v29, v34, v35
	v_lshl_add_u64 v[30:31], v[22:23], 1, s[6:7]
	global_store_dwordx4 v[30:31], v[26:29], off sc1
	s_nop 1
	s_mov_b64 s[2:3], 0
.LBB0_1110:
	s_andn2_b64 vcc, exec, s[2:3]
	s_cbranch_vccnz .LBB0_1112
	v_lshl_add_u64 v[22:23], v[22:23], 2, s[12:13]
	v_mov_b32_e32 v63, v62
	global_store_dwordx4 v[22:23], v[16:19], off
	s_nop 1
	v_pk_mul_f32 v[16:17], v[140:141], v[62:63]
	v_pk_mul_f32 v[18:19], v[6:7], v[16:17]
	v_pk_mul_f32 v[16:17], v[4:5], v[24:25]
	global_store_dwordx4 v[22:23], v[16:19], off offset:16
.LBB0_1112:
	v_mov_b32_e32 v26, v60
	v_mov_b32_e32 v27, v60
	v_pk_mul_f32 v[16:17], v[148:149], v[26:27]
	v_pk_mul_f32 v[24:25], v[146:147], v[60:61]
	v_lshl_add_u64 v[22:23], v[128:129], 0, v[20:21]
	v_pk_mul_f32 v[18:19], v[14:15], v[16:17]
	v_pk_mul_f32 v[16:17], v[12:13], v[24:25]
	s_mov_b64 s[2:3], -1
	s_and_b64 vcc, exec, s[4:5]
	v_pk_mul_f32 v[24:25], v[134:135], v[60:61]
	s_cbranch_vccnz .LBB0_1114
	v_pk_mul_f32 v[26:27], v[136:137], v[26:27]
	v_pk_add_f32 v[28:29], v[10:11], v[18:19]
	v_pk_add_f32 v[30:31], v[8:9], v[16:17]
	v_pk_fma_f32 v[34:35], v[6:7], v[26:27], v[2:3]
	v_pk_fma_f32 v[42:43], v[4:5], v[24:25], v[0:1]
	v_cvt_pk_bf16_f32 v26, v30, v31
	v_cvt_pk_bf16_f32 v27, v28, v29
	v_cvt_pk_bf16_f32 v28, v42, v43
	v_cvt_pk_bf16_f32 v29, v34, v35
	v_lshl_add_u64 v[30:31], v[22:23], 1, s[6:7]
	global_store_dwordx4 v[30:31], v[26:29], off sc1
	s_nop 1
	s_mov_b64 s[2:3], 0
.LBB0_1114:
	s_andn2_b64 vcc, exec, s[2:3]
	s_cbranch_vccnz .LBB0_1116
	v_lshl_add_u64 v[22:23], v[22:23], 2, s[12:13]
	v_mov_b32_e32 v61, v60
	global_store_dwordx4 v[22:23], v[16:19], off
	s_nop 1
	v_pk_mul_f32 v[16:17], v[136:137], v[60:61]
	v_pk_mul_f32 v[18:19], v[6:7], v[16:17]
	v_pk_mul_f32 v[16:17], v[4:5], v[24:25]
	global_store_dwordx4 v[22:23], v[16:19], off offset:16
.LBB0_1116:
	v_mov_b32_e32 v26, v58
	v_mov_b32_e32 v27, v58
	v_pk_mul_f32 v[16:17], v[144:145], v[26:27]
	v_pk_mul_f32 v[24:25], v[142:143], v[58:59]
	v_lshl_add_u64 v[22:23], v[166:167], 0, v[20:21]
	v_pk_mul_f32 v[18:19], v[14:15], v[16:17]
	v_pk_mul_f32 v[16:17], v[12:13], v[24:25]
	s_mov_b64 s[2:3], -1
	s_and_b64 vcc, exec, s[4:5]
	v_pk_mul_f32 v[24:25], v[130:131], v[58:59]
	s_cbranch_vccnz .LBB0_1118
	v_pk_mul_f32 v[26:27], v[132:133], v[26:27]
	v_pk_add_f32 v[28:29], v[10:11], v[18:19]
	v_pk_add_f32 v[30:31], v[8:9], v[16:17]
	v_pk_fma_f32 v[34:35], v[6:7], v[26:27], v[2:3]
	v_pk_fma_f32 v[42:43], v[4:5], v[24:25], v[0:1]
	v_cvt_pk_bf16_f32 v26, v30, v31
	v_cvt_pk_bf16_f32 v27, v28, v29
	v_cvt_pk_bf16_f32 v28, v42, v43
	v_cvt_pk_bf16_f32 v29, v34, v35
	v_lshl_add_u64 v[30:31], v[22:23], 1, s[6:7]
	global_store_dwordx4 v[30:31], v[26:29], off sc1
	s_nop 1
	s_mov_b64 s[2:3], 0
.LBB0_1118:
	s_andn2_b64 vcc, exec, s[2:3]
	s_cbranch_vccnz .LBB0_1120
	v_lshl_add_u64 v[22:23], v[22:23], 2, s[12:13]
	v_mov_b32_e32 v59, v58
	global_store_dwordx4 v[22:23], v[16:19], off
	s_nop 1
	v_pk_mul_f32 v[16:17], v[132:133], v[58:59]
	v_pk_mul_f32 v[18:19], v[6:7], v[16:17]
	v_pk_mul_f32 v[16:17], v[4:5], v[24:25]
	global_store_dwordx4 v[22:23], v[16:19], off offset:16
.LBB0_1120:
	v_mov_b32_e32 v26, v56
	v_mov_b32_e32 v27, v56
	v_pk_mul_f32 v[16:17], v[156:157], v[26:27]
	v_pk_mul_f32 v[24:25], v[154:155], v[56:57]
	v_lshl_add_u64 v[22:23], v[158:159], 0, v[20:21]
	v_pk_mul_f32 v[18:19], v[14:15], v[16:17]
	v_pk_mul_f32 v[16:17], v[12:13], v[24:25]
	s_mov_b64 s[2:3], -1
	s_and_b64 vcc, exec, s[4:5]
	v_pk_mul_f32 v[24:25], v[212:213], v[56:57]
	s_cbranch_vccnz .LBB0_1122
	v_pk_mul_f32 v[26:27], v[210:211], v[26:27]
	v_pk_add_f32 v[28:29], v[10:11], v[18:19]
	v_pk_add_f32 v[30:31], v[8:9], v[16:17]
	v_pk_fma_f32 v[34:35], v[6:7], v[26:27], v[2:3]
	v_pk_fma_f32 v[42:43], v[4:5], v[24:25], v[0:1]
	v_cvt_pk_bf16_f32 v26, v30, v31
	v_cvt_pk_bf16_f32 v27, v28, v29
	v_cvt_pk_bf16_f32 v28, v42, v43
	v_cvt_pk_bf16_f32 v29, v34, v35
	v_lshl_add_u64 v[30:31], v[22:23], 1, s[6:7]
	global_store_dwordx4 v[30:31], v[26:29], off sc1
	s_nop 1
	s_mov_b64 s[2:3], 0
.LBB0_1122:
	s_andn2_b64 vcc, exec, s[2:3]
	s_cbranch_vccnz .LBB0_1124
	v_lshl_add_u64 v[22:23], v[22:23], 2, s[12:13]
	v_mov_b32_e32 v57, v56
	global_store_dwordx4 v[22:23], v[16:19], off
	s_nop 1
	v_pk_mul_f32 v[16:17], v[210:211], v[56:57]
	v_pk_mul_f32 v[18:19], v[6:7], v[16:17]
	v_pk_mul_f32 v[16:17], v[4:5], v[24:25]
	global_store_dwordx4 v[22:23], v[16:19], off offset:16
.LBB0_1124:
	v_mov_b32_e32 v26, v52
	v_mov_b32_e32 v27, v52
	v_pk_mul_f32 v[16:17], v[86:87], v[26:27]
	v_pk_mul_f32 v[24:25], v[84:85], v[52:53]
	v_lshl_add_u64 v[22:23], v[160:161], 0, v[20:21]
	v_pk_mul_f32 v[18:19], v[14:15], v[16:17]
	v_pk_mul_f32 v[16:17], v[12:13], v[24:25]
	s_mov_b64 s[2:3], -1
	s_and_b64 vcc, exec, s[4:5]
	v_pk_mul_f32 v[24:25], v[72:73], v[52:53]
	s_cbranch_vccnz .LBB0_1126
	v_pk_mul_f32 v[26:27], v[74:75], v[26:27]
	v_pk_add_f32 v[28:29], v[10:11], v[18:19]
	v_pk_add_f32 v[30:31], v[8:9], v[16:17]
	v_pk_fma_f32 v[34:35], v[6:7], v[26:27], v[2:3]
	v_pk_fma_f32 v[42:43], v[4:5], v[24:25], v[0:1]
	v_cvt_pk_bf16_f32 v26, v30, v31
	v_cvt_pk_bf16_f32 v27, v28, v29
	v_cvt_pk_bf16_f32 v28, v42, v43
	v_cvt_pk_bf16_f32 v29, v34, v35
	v_lshl_add_u64 v[30:31], v[22:23], 1, s[6:7]
	global_store_dwordx4 v[30:31], v[26:29], off sc1
	s_nop 1
	s_mov_b64 s[2:3], 0
.LBB0_1126:
	s_andn2_b64 vcc, exec, s[2:3]
	s_cbranch_vccnz .LBB0_1128
	v_lshl_add_u64 v[22:23], v[22:23], 2, s[12:13]
	v_mov_b32_e32 v53, v52
	global_store_dwordx4 v[22:23], v[16:19], off
	s_nop 1
	v_pk_mul_f32 v[16:17], v[74:75], v[52:53]
	v_pk_mul_f32 v[18:19], v[6:7], v[16:17]
	v_pk_mul_f32 v[16:17], v[4:5], v[24:25]
	global_store_dwordx4 v[22:23], v[16:19], off offset:16
.LBB0_1128:
	v_mov_b32_e32 v26, v48
	v_mov_b32_e32 v27, v48
	v_pk_mul_f32 v[16:17], v[82:83], v[26:27]
	v_pk_mul_f32 v[24:25], v[80:81], v[48:49]
	v_lshl_add_u64 v[22:23], v[50:51], 0, v[20:21]
	v_pk_mul_f32 v[18:19], v[14:15], v[16:17]
	v_pk_mul_f32 v[16:17], v[12:13], v[24:25]
	s_mov_b64 s[2:3], -1
	s_and_b64 vcc, exec, s[4:5]
	v_pk_mul_f32 v[24:25], v[64:65], v[48:49]
	s_cbranch_vccnz .LBB0_1130
	v_pk_mul_f32 v[26:27], v[66:67], v[26:27]
	v_pk_add_f32 v[28:29], v[10:11], v[18:19]
	v_pk_add_f32 v[30:31], v[8:9], v[16:17]
	v_pk_fma_f32 v[34:35], v[6:7], v[26:27], v[2:3]
	v_pk_fma_f32 v[42:43], v[4:5], v[24:25], v[0:1]
	v_cvt_pk_bf16_f32 v26, v30, v31
	v_cvt_pk_bf16_f32 v27, v28, v29
	v_cvt_pk_bf16_f32 v28, v42, v43
	v_cvt_pk_bf16_f32 v29, v34, v35
	v_lshl_add_u64 v[30:31], v[22:23], 1, s[6:7]
	global_store_dwordx4 v[30:31], v[26:29], off sc1
	s_nop 1
	s_mov_b64 s[2:3], 0
.LBB0_1130:
	s_andn2_b64 vcc, exec, s[2:3]
	s_cbranch_vccnz .LBB0_1132
	v_lshl_add_u64 v[22:23], v[22:23], 2, s[12:13]
	v_mov_b32_e32 v49, v48
	global_store_dwordx4 v[22:23], v[16:19], off
	s_nop 1
	v_pk_mul_f32 v[16:17], v[66:67], v[48:49]
	v_pk_mul_f32 v[18:19], v[6:7], v[16:17]
	v_pk_mul_f32 v[16:17], v[4:5], v[24:25]
	global_store_dwordx4 v[22:23], v[16:19], off offset:16
.LBB0_1132:
	v_mov_b32_e32 v26, v44
	v_mov_b32_e32 v27, v44
	v_pk_mul_f32 v[16:17], v[78:79], v[26:27]
	v_pk_mul_f32 v[24:25], v[76:77], v[44:45]
	v_lshl_add_u64 v[22:23], v[46:47], 0, v[20:21]
	v_pk_mul_f32 v[18:19], v[14:15], v[16:17]
	v_pk_mul_f32 v[16:17], v[12:13], v[24:25]
	s_mov_b64 s[2:3], -1
	s_and_b64 vcc, exec, s[4:5]
	v_pk_mul_f32 v[24:25], v[68:69], v[44:45]
	s_cbranch_vccnz .LBB0_1134
	v_pk_mul_f32 v[26:27], v[70:71], v[26:27]
	v_pk_add_f32 v[28:29], v[10:11], v[18:19]
	v_pk_add_f32 v[30:31], v[8:9], v[16:17]
	v_pk_fma_f32 v[34:35], v[6:7], v[26:27], v[2:3]
	v_pk_fma_f32 v[42:43], v[4:5], v[24:25], v[0:1]
	v_cvt_pk_bf16_f32 v26, v30, v31
	v_cvt_pk_bf16_f32 v27, v28, v29
	v_cvt_pk_bf16_f32 v28, v42, v43
	v_cvt_pk_bf16_f32 v29, v34, v35
	v_lshl_add_u64 v[30:31], v[22:23], 1, s[6:7]
	global_store_dwordx4 v[30:31], v[26:29], off sc1
	s_nop 1
	s_mov_b64 s[2:3], 0
.LBB0_1134:
	s_andn2_b64 vcc, exec, s[2:3]
	s_cbranch_vccnz .LBB0_1136
	v_lshl_add_u64 v[22:23], v[22:23], 2, s[12:13]
	v_mov_b32_e32 v45, v44
	global_store_dwordx4 v[22:23], v[16:19], off
	s_nop 1
	v_pk_mul_f32 v[16:17], v[70:71], v[44:45]
	v_pk_mul_f32 v[18:19], v[6:7], v[16:17]
	v_pk_mul_f32 v[16:17], v[4:5], v[24:25]
	global_store_dwordx4 v[22:23], v[16:19], off offset:16
.LBB0_1136:
	s_nop 1
	v_lshl_add_u64 v[16:17], v[32:33], 0, v[20:21]
	v_mov_b32_e32 v20, v40
	v_mov_b32_e32 v21, v40
	v_pk_mul_f32 v[18:19], v[90:91], v[20:21]
	v_pk_mul_f32 v[22:23], v[88:89], v[40:41]
	v_pk_mul_f32 v[14:15], v[14:15], v[18:19]
	v_pk_mul_f32 v[12:13], v[12:13], v[22:23]
	s_mov_b64 s[2:3], -1
	s_and_b64 vcc, exec, s[4:5]
	v_pk_mul_f32 v[18:19], v[38:39], v[40:41]
	s_cbranch_vccnz .LBB0_1139
	v_pk_mul_f32 v[20:21], v[36:37], v[20:21]
	v_pk_add_f32 v[10:11], v[10:11], v[14:15]
	v_pk_add_f32 v[8:9], v[8:9], v[12:13]
	v_pk_fma_f32 v[20:21], v[6:7], v[20:21], v[2:3]
	v_pk_fma_f32 v[2:3], v[4:5], v[18:19], v[0:1]
	v_cvt_pk_bf16_f32 v0, v8, v9
	v_cvt_pk_bf16_f32 v1, v10, v11
	v_cvt_pk_bf16_f32 v2, v2, v3
	v_cvt_pk_bf16_f32 v3, v20, v21
	v_lshl_add_u64 v[8:9], v[16:17], 1, s[6:7]
	global_store_dwordx4 v[8:9], v[0:3], off sc1
	s_nop 1
	s_cbranch_execz .LBB0_1140

.LBB0_1140:
	v_mov_b32_e32 v41, v40
	v_pk_mul_f32 v[0:1], v[36:37], v[40:41]
	v_lshl_add_u64 v[8:9], v[16:17], 2, s[12:13]
	v_pk_mul_f32 v[2:3], v[6:7], v[0:1]
	v_pk_mul_f32 v[0:1], v[4:5], v[18:19]
	global_store_dwordx4 v[8:9], v[12:15], off
	global_store_dwordx4 v[8:9], v[0:3], off offset:16
	s_and_b64 vcc, exec, s[4:5]
	s_cbranch_vccnz .LBB0_1145

.LBB0_1520:
	s_and_saveexec_b64 s[12:13], s[10:11]
	s_cbranch_execz .LBB0_1527
	s_load_dwordx2 s[2:3], s[0:1], 0x48
	s_load_dwordx2 s[16:17], s[0:1], 0x40
	v_lshlrev_b32_e32 v0, 2, v75
	v_add_u32_e32 v1, 0x1000, v0
	v_add_u32_e32 v2, 0x2000, v0
	v_add_u32_e32 v3, 0x3000, v0
	s_waitcnt lgkmcnt(0)
	global_load_dword v4, v0, s[2:3]
	global_load_dword v5, v0, s[2:3] offset:2048
	global_load_dword v6, v0, s[16:17]
	global_load_dword v7, v0, s[16:17] offset:2048
	global_load_dword v8, v1, s[16:17]
	global_load_dword v9, v1, s[16:17] offset:2048
	global_load_dword v10, v2, s[16:17]
	global_load_dword v11, v2, s[16:17] offset:2048
	global_load_dword v12, v3, s[16:17]
	global_load_dword v13, v3, s[16:17] offset:2048
	s_waitcnt vmcnt(9)
	v_mul_f32_e32 v14, 0xbfb8aa3b, v4
	v_exp_f32_e32 v14, v14
	s_nop 0
	v_add_f32_e32 v14, 1.0, v14
	v_rcp_f32_e32 v14, v14
	s_nop 0
	v_mul_f32_e32 v4, v4, v14
	ds_write_b32 v115, v4
	s_waitcnt vmcnt(8)
	v_mul_f32_e32 v14, 0xbfb8aa3b, v5
	v_exp_f32_e32 v14, v14
	s_nop 0
	v_add_f32_e32 v14, 1.0, v14
	v_rcp_f32_e32 v14, v14
	s_nop 0
	v_mul_f32_e32 v5, v5, v14
	ds_write_b32 v115, v5 offset:2048
	s_waitcnt vmcnt(7)
	v_mul_f32_e32 v14, 0xbfb8aa3b, v6
	v_exp_f32_e32 v14, v14
	s_nop 0
	v_add_f32_e32 v14, 1.0, v14
	v_rcp_f32_e32 v14, v14
	s_nop 0
	v_mul_f32_e32 v6, v6, v14
	ds_write_b32 v115, v6 offset:4096
	s_waitcnt vmcnt(6)
	v_mul_f32_e32 v14, 0xbfb8aa3b, v7
	v_exp_f32_e32 v14, v14
	s_nop 0
	v_add_f32_e32 v14, 1.0, v14
	v_rcp_f32_e32 v14, v14
	s_nop 0
	v_mul_f32_e32 v7, v7, v14
	ds_write_b32 v115, v7 offset:6144
	s_waitcnt vmcnt(5)
	v_mul_f32_e32 v14, 0xbfb8aa3b, v8
	v_exp_f32_e32 v14, v14
	s_nop 0
	v_add_f32_e32 v14, 1.0, v14
	v_rcp_f32_e32 v14, v14
	s_nop 0
	v_mul_f32_e32 v8, v8, v14
	ds_write_b32 v115, v8 offset:8192
	s_waitcnt vmcnt(4)
	v_mul_f32_e32 v14, 0xbfb8aa3b, v9
	v_exp_f32_e32 v14, v14
	s_nop 0
	v_add_f32_e32 v14, 1.0, v14
	v_rcp_f32_e32 v14, v14
	s_nop 0
	v_mul_f32_e32 v9, v9, v14
	ds_write_b32 v115, v9 offset:10240
	s_waitcnt vmcnt(3)
	v_mul_f32_e32 v14, 0xbfb8aa3b, v10
	v_exp_f32_e32 v14, v14
	s_nop 0
	v_add_f32_e32 v14, 1.0, v14
	v_rcp_f32_e32 v14, v14
	s_nop 0
	v_mul_f32_e32 v10, v10, v14
	ds_write_b32 v115, v10 offset:12288
	s_waitcnt vmcnt(2)
	v_mul_f32_e32 v14, 0xbfb8aa3b, v11
	v_exp_f32_e32 v14, v14
	s_nop 0
	v_add_f32_e32 v14, 1.0, v14
	v_rcp_f32_e32 v14, v14
	s_nop 0
	v_mul_f32_e32 v11, v11, v14
	ds_write_b32 v115, v11 offset:14336
	s_waitcnt vmcnt(1)
	v_mul_f32_e32 v14, 0xbfb8aa3b, v12
	v_exp_f32_e32 v14, v14
	s_nop 0
	v_add_f32_e32 v14, 1.0, v14
	v_rcp_f32_e32 v14, v14
	s_nop 0
	v_mul_f32_e32 v12, v12, v14
	ds_write_b32 v115, v12 offset:16384
	s_waitcnt vmcnt(0)
	v_mul_f32_e32 v14, 0xbfb8aa3b, v13
	v_exp_f32_e32 v14, v14
	s_nop 0
	v_add_f32_e32 v14, 1.0, v14
	v_rcp_f32_e32 v14, v14
	s_nop 0
	v_mul_f32_e32 v13, v13, v14
	ds_write_b32 v115, v13 offset:18432
